# v28 stack + closing s_barrier of each GEMM compute segment moved before its last MFMA
# baseline (speedup 1.0000x reference)
.LBB0_179:
	s_ashr_i32 s47, s46, 31
	s_lshl_b64 s[48:49], s[46:47], 19
	s_add_u32 s48, s26, s48
	s_addc_u32 s49, s27, s49
	s_and_b64 s[50:51], s[44:45], exec
	s_cselect_b32 s47, s49, s63
	s_cselect_b32 s82, s48, s62
	s_ashr_i32 s21, s20, 31
	s_lshl_b64 s[50:51], s[20:21], 19
	s_add_u32 s50, s59, s50
	s_addc_u32 s51, s66, s51
	s_and_b64 s[84:85], s[44:45], exec
	s_cselect_b32 s21, s51, s61
	s_cselect_b32 s83, s50, s60
	s_add_u32 s89, s60, 0x100
	s_addc_u32 s84, s61, 0
	s_add_u32 s60, s62, 0x40080
	s_addc_u32 s61, s63, 0
	s_mov_b32 s85, -2
	s_add_u32 s62, s60, 0xfffc0080
	s_addc_u32 s63, s61, -1
	s_add_i32 s86, 0, 0x10000
	s_cmp_eq_u32 s85, 12
	s_cselect_b32 vcc_hi, s47, s63
	s_cselect_b32 vcc_lo, s82, s62
	v_add_u32_e32 v142, s86, v145
	s_cselect_b32 s63, s21, s84
	s_cselect_b32 s62, s83, s89
	s_add_i32 s92, 0, 0x14000
	ds_read_b128 v[138:141], v142
	ds_read_b128 v[172:175], v142 offset:1024
	ds_read_b128 v[176:179], v142 offset:2048
	ds_read_b128 v[180:183], v142 offset:3072
	v_add_u32_e32 v142, s92, v145
	ds_read_b128 v[184:187], v142
	ds_read_b128 v[188:191], v142 offset:1024
	ds_read_b128 v[192:195], v142 offset:2048
	ds_read_b128 v[196:199], v142 offset:3072
	v_lshl_add_u64 v[142:143], s[60:61], 0, v[136:137]
	s_add_i32 m0, s68, 0xc000
	ds_read_b128 v[210:213], v148
	ds_read_b128 v[214:217], v148 offset:1024
	ds_read_b128 v[218:221], v148 offset:2048
	ds_read_b128 v[224:227], v148 offset:3072
	ds_read_b128 v[228:231], v148 offset:4096
	ds_read_b128 v[232:235], v148 offset:5120
	ds_read_b128 v[236:239], v148 offset:6144
	ds_read_b128 v[240:243], v148 offset:7168
	global_load_lds_dwordx4 v[142:143], off
	v_lshl_add_u64 v[142:143], s[60:61], 0, v[134:135]
	s_add_i32 m0, s68, 0xe000
	s_nop 0
	global_load_lds_dwordx4 v[142:143], off
	s_waitcnt vmcnt(8)
	s_waitcnt lgkmcnt(0)
	s_barrier
	s_setprio 1
	s_waitcnt lgkmcnt(0)
	v_mfma_f32_16x16x32_bf16 v[124:127], v[138:141], v[210:213], 0
	v_mfma_f32_16x16x32_bf16 v[116:119], v[176:179], v[210:213], 0
	v_mfma_f32_16x16x32_bf16 v[108:111], v[138:141], v[218:221], 0
	v_mfma_f32_16x16x32_bf16 v[100:103], v[176:179], v[218:221], 0
	v_mfma_f32_16x16x32_bf16 v[92:95], v[138:141], v[228:231], 0
	v_mfma_f32_16x16x32_bf16 v[84:87], v[176:179], v[228:231], 0
	v_mfma_f32_16x16x32_bf16 v[76:79], v[138:141], v[236:239], 0
	v_mfma_f32_16x16x32_bf16 v[68:71], v[176:179], v[236:239], 0
	v_mfma_f32_16x16x32_bf16 v[124:127], v[172:175], v[214:217], v[124:127]
	v_mfma_f32_16x16x32_bf16 v[116:119], v[180:183], v[214:217], v[116:119]
	v_mfma_f32_16x16x32_bf16 v[108:111], v[172:175], v[224:227], v[108:111]
	v_mfma_f32_16x16x32_bf16 v[100:103], v[180:183], v[224:227], v[100:103]
	v_mfma_f32_16x16x32_bf16 v[92:95], v[172:175], v[232:235], v[92:95]
	v_mfma_f32_16x16x32_bf16 v[84:87], v[180:183], v[232:235], v[84:87]
	v_mfma_f32_16x16x32_bf16 v[76:79], v[172:175], v[240:243], v[76:79]
	v_mfma_f32_16x16x32_bf16 v[68:71], v[180:183], v[240:243], v[68:71]
	s_setprio 0
	s_setprio 1
	v_mfma_f32_16x16x32_bf16 v[120:123], v[184:187], v[210:213], 0
	v_mfma_f32_16x16x32_bf16 v[112:115], v[192:195], v[210:213], 0
	v_mfma_f32_16x16x32_bf16 v[104:107], v[184:187], v[218:221], 0
	v_mfma_f32_16x16x32_bf16 v[96:99], v[192:195], v[218:221], 0
	v_mfma_f32_16x16x32_bf16 v[88:91], v[184:187], v[228:231], 0
	v_mfma_f32_16x16x32_bf16 v[80:83], v[192:195], v[228:231], 0
	v_mfma_f32_16x16x32_bf16 v[72:75], v[184:187], v[236:239], 0
	v_mfma_f32_16x16x32_bf16 v[64:67], v[192:195], v[236:239], 0
	v_mfma_f32_16x16x32_bf16 v[120:123], v[188:191], v[214:217], v[120:123]
	v_mfma_f32_16x16x32_bf16 v[112:115], v[196:199], v[214:217], v[112:115]
	v_mfma_f32_16x16x32_bf16 v[104:107], v[188:191], v[224:227], v[104:107]
	v_mfma_f32_16x16x32_bf16 v[96:99], v[196:199], v[224:227], v[96:99]
	v_mfma_f32_16x16x32_bf16 v[88:91], v[188:191], v[232:235], v[88:91]
	v_mfma_f32_16x16x32_bf16 v[80:83], v[196:199], v[232:235], v[80:83]
	v_mfma_f32_16x16x32_bf16 v[72:75], v[188:191], v[240:243], v[72:75]
	s_barrier
	v_mfma_f32_16x16x32_bf16 v[64:67], v[196:199], v[240:243], v[64:67]
	s_setprio 0
	s_add_i32 s86, s86, s67
	v_lshl_add_u64 v[142:143], s[62:63], 0, v[152:153]
	s_mov_b32 m0, s86
	ds_read_b128 v[210:213], v148 offset:16384
	ds_read_b128 v[214:217], v148 offset:17408
	ds_read_b128 v[218:221], v148 offset:18432
	ds_read_b128 v[224:227], v148 offset:19456
	ds_read_b128 v[228:231], v148 offset:20480
	ds_read_b128 v[232:235], v148 offset:21504
	ds_read_b128 v[236:239], v148 offset:22528
	ds_read_b128 v[240:243], v148 offset:23552
	global_load_lds_dwordx4 v[142:143], off
	s_add_i32 m0, s86, 0x2000
	s_add_u32 s86, s62, 0x40000
	v_lshl_add_u64 v[150:151], s[62:63], 0, v[128:129]
	s_addc_u32 s87, s63, 0
	s_add_i32 s92, s92, s67
	global_load_lds_dwordx4 v[150:151], off
	v_lshl_add_u64 v[244:245], s[86:87], 0, v[152:153]
	s_mov_b32 m0, s92
	v_lshl_add_u64 v[246:247], vcc, 0, v[130:131]
	global_load_lds_dwordx4 v[244:245], off
	v_lshl_add_u64 v[244:245], s[86:87], 0, v[128:129]
	s_add_i32 m0, s92, 0x2000
	s_nop 0
	global_load_lds_dwordx4 v[244:245], off
	v_lshl_add_u64 v[244:245], vcc, 0, v[132:133]
	s_mov_b32 m0, s68
	s_nop 0
	global_load_lds_dwordx4 v[244:245], off
	s_mov_b32 m0, s69
	s_nop 0
	global_load_lds_dwordx4 v[246:247], off
	s_waitcnt vmcnt(8)
	s_waitcnt lgkmcnt(0)
	s_barrier
	s_setprio 1
	s_waitcnt lgkmcnt(0)
	v_mfma_f32_16x16x32_bf16 v[60:63], v[138:141], v[210:213], 0
	v_mfma_f32_16x16x32_bf16 v[52:55], v[176:179], v[210:213], 0
	v_mfma_f32_16x16x32_bf16 v[44:47], v[138:141], v[218:221], 0
	v_mfma_f32_16x16x32_bf16 v[36:39], v[176:179], v[218:221], 0
	v_mfma_f32_16x16x32_bf16 v[28:31], v[138:141], v[228:231], 0
	v_mfma_f32_16x16x32_bf16 v[20:23], v[176:179], v[228:231], 0
	v_mfma_f32_16x16x32_bf16 v[12:15], v[138:141], v[236:239], 0
	v_mfma_f32_16x16x32_bf16 v[4:7], v[176:179], v[236:239], 0
	v_mfma_f32_16x16x32_bf16 v[60:63], v[172:175], v[214:217], v[60:63]
	v_mfma_f32_16x16x32_bf16 v[52:55], v[180:183], v[214:217], v[52:55]
	v_mfma_f32_16x16x32_bf16 v[44:47], v[172:175], v[224:227], v[44:47]
	v_mfma_f32_16x16x32_bf16 v[36:39], v[180:183], v[224:227], v[36:39]
	v_mfma_f32_16x16x32_bf16 v[28:31], v[172:175], v[232:235], v[28:31]
	v_mfma_f32_16x16x32_bf16 v[20:23], v[180:183], v[232:235], v[20:23]
	v_mfma_f32_16x16x32_bf16 v[12:15], v[172:175], v[240:243], v[12:15]
	v_mfma_f32_16x16x32_bf16 v[4:7], v[180:183], v[240:243], v[4:7]
	s_setprio 0
	s_setprio 1
	v_mfma_f32_16x16x32_bf16 v[56:59], v[184:187], v[210:213], 0
	v_mfma_f32_16x16x32_bf16 v[48:51], v[192:195], v[210:213], 0
	v_mfma_f32_16x16x32_bf16 v[40:43], v[184:187], v[218:221], 0
	v_mfma_f32_16x16x32_bf16 v[32:35], v[192:195], v[218:221], 0
	v_mfma_f32_16x16x32_bf16 v[24:27], v[184:187], v[228:231], 0
	v_mfma_f32_16x16x32_bf16 v[16:19], v[192:195], v[228:231], 0
	v_mfma_f32_16x16x32_bf16 v[8:11], v[184:187], v[236:239], 0
	v_mfma_f32_16x16x32_bf16 v[0:3], v[192:195], v[236:239], 0
	v_mfma_f32_16x16x32_bf16 v[56:59], v[188:191], v[214:217], v[56:59]
	v_mfma_f32_16x16x32_bf16 v[48:51], v[196:199], v[214:217], v[48:51]
	v_mfma_f32_16x16x32_bf16 v[40:43], v[188:191], v[224:227], v[40:43]
	v_mfma_f32_16x16x32_bf16 v[32:35], v[196:199], v[224:227], v[32:35]
	v_mfma_f32_16x16x32_bf16 v[24:27], v[188:191], v[232:235], v[24:27]
	v_mfma_f32_16x16x32_bf16 v[16:19], v[196:199], v[232:235], v[16:19]
	v_mfma_f32_16x16x32_bf16 v[8:11], v[188:191], v[240:243], v[8:11]
	s_barrier
	v_mfma_f32_16x16x32_bf16 v[0:3], v[196:199], v[240:243], v[0:3]
	s_setprio 0
	s_add_i32 s92, 0, 0x18000
	v_add_u32_e32 v149, s92, v145
	s_add_i32 s93, 0, 0x1c000
	ds_read_b128 v[138:141], v149
	ds_read_b128 v[172:175], v149 offset:1024
	ds_read_b128 v[176:179], v149 offset:2048
	ds_read_b128 v[180:183], v149 offset:3072
	v_add_u32_e32 v149, s93, v145
	ds_read_b128 v[184:187], v149
	ds_read_b128 v[188:191], v149 offset:1024
	ds_read_b128 v[192:195], v149 offset:2048
	ds_read_b128 v[196:199], v149 offset:3072
	s_add_u32 s86, vcc_lo, 0x40000
	s_addc_u32 s87, vcc_hi, 0
	s_mov_b32 m0, s74
	v_lshl_add_u64 v[248:249], s[86:87], 0, v[132:133]
	ds_read_b128 v[210:213], v148 offset:32768
	ds_read_b128 v[214:217], v148 offset:33792
	ds_read_b128 v[218:221], v148 offset:34816
	ds_read_b128 v[224:227], v148 offset:35840
	ds_read_b128 v[228:231], v148 offset:36864
	ds_read_b128 v[232:235], v148 offset:37888
	ds_read_b128 v[236:239], v148 offset:38912
	ds_read_b128 v[240:243], v148 offset:39936
	global_load_lds_dwordx4 v[248:249], off
	v_lshl_add_u64 v[248:249], s[86:87], 0, v[130:131]
	s_mov_b32 m0, s75
	s_nop 0
	global_load_lds_dwordx4 v[248:249], off
	s_waitcnt vmcnt(8)
	s_waitcnt lgkmcnt(0)
	s_barrier
	s_setprio 1
	s_waitcnt lgkmcnt(0)
	v_mfma_f32_16x16x32_bf16 v[124:127], v[138:141], v[210:213], v[124:127]
	v_mfma_f32_16x16x32_bf16 v[116:119], v[176:179], v[210:213], v[116:119]
	v_mfma_f32_16x16x32_bf16 v[108:111], v[138:141], v[218:221], v[108:111]
	v_mfma_f32_16x16x32_bf16 v[100:103], v[176:179], v[218:221], v[100:103]
	v_mfma_f32_16x16x32_bf16 v[92:95], v[138:141], v[228:231], v[92:95]
	v_mfma_f32_16x16x32_bf16 v[84:87], v[176:179], v[228:231], v[84:87]
	v_mfma_f32_16x16x32_bf16 v[76:79], v[138:141], v[236:239], v[76:79]
	v_mfma_f32_16x16x32_bf16 v[68:71], v[176:179], v[236:239], v[68:71]
	v_mfma_f32_16x16x32_bf16 v[124:127], v[172:175], v[214:217], v[124:127]
	v_mfma_f32_16x16x32_bf16 v[116:119], v[180:183], v[214:217], v[116:119]
	v_mfma_f32_16x16x32_bf16 v[108:111], v[172:175], v[224:227], v[108:111]
	v_mfma_f32_16x16x32_bf16 v[100:103], v[180:183], v[224:227], v[100:103]
	v_mfma_f32_16x16x32_bf16 v[92:95], v[172:175], v[232:235], v[92:95]
	v_mfma_f32_16x16x32_bf16 v[84:87], v[180:183], v[232:235], v[84:87]
	v_mfma_f32_16x16x32_bf16 v[76:79], v[172:175], v[240:243], v[76:79]
	v_mfma_f32_16x16x32_bf16 v[68:71], v[180:183], v[240:243], v[68:71]
	s_setprio 0
	s_setprio 1
	v_mfma_f32_16x16x32_bf16 v[120:123], v[184:187], v[210:213], v[120:123]
	v_mfma_f32_16x16x32_bf16 v[112:115], v[192:195], v[210:213], v[112:115]
	v_mfma_f32_16x16x32_bf16 v[104:107], v[184:187], v[218:221], v[104:107]
	v_mfma_f32_16x16x32_bf16 v[96:99], v[192:195], v[218:221], v[96:99]
	v_mfma_f32_16x16x32_bf16 v[88:91], v[184:187], v[228:231], v[88:91]
	v_mfma_f32_16x16x32_bf16 v[80:83], v[192:195], v[228:231], v[80:83]
	v_mfma_f32_16x16x32_bf16 v[72:75], v[184:187], v[236:239], v[72:75]
	v_mfma_f32_16x16x32_bf16 v[64:67], v[192:195], v[236:239], v[64:67]
	v_mfma_f32_16x16x32_bf16 v[120:123], v[188:191], v[214:217], v[120:123]
	v_mfma_f32_16x16x32_bf16 v[112:115], v[196:199], v[214:217], v[112:115]
	v_mfma_f32_16x16x32_bf16 v[104:107], v[188:191], v[224:227], v[104:107]
	v_mfma_f32_16x16x32_bf16 v[96:99], v[196:199], v[224:227], v[96:99]
	v_mfma_f32_16x16x32_bf16 v[88:91], v[188:191], v[232:235], v[88:91]
	v_mfma_f32_16x16x32_bf16 v[80:83], v[196:199], v[232:235], v[80:83]
	v_mfma_f32_16x16x32_bf16 v[72:75], v[188:191], v[240:243], v[72:75]
	s_barrier
	v_mfma_f32_16x16x32_bf16 v[64:67], v[196:199], v[240:243], v[64:67]
	s_setprio 0
	s_add_i32 s86, s92, s67
	v_lshl_add_u64 v[142:143], v[142:143], 0, s[22:23]
	s_mov_b32 m0, s86
	ds_read_b128 v[210:213], v148 offset:49152
	ds_read_b128 v[214:217], v148 offset:50176
	ds_read_b128 v[218:221], v148 offset:51200
	ds_read_b128 v[224:227], v148 offset:52224
	ds_read_b128 v[228:231], v148 offset:53248
	ds_read_b128 v[232:235], v148 offset:54272
	ds_read_b128 v[236:239], v148 offset:55296
	ds_read_b128 v[240:243], v148 offset:56320
	global_load_lds_dwordx4 v[142:143], off
	s_add_i32 m0, s86, 0x2000
	s_add_u32 s62, s62, 0x40080
	v_lshl_add_u64 v[142:143], v[150:151], 0, s[22:23]
	s_addc_u32 s63, s63, 0
	s_add_i32 s86, s93, s67
	global_load_lds_dwordx4 v[142:143], off
	v_lshl_add_u64 v[142:143], s[62:63], 0, v[152:153]
	s_mov_b32 m0, s86
	s_nop 0
	global_load_lds_dwordx4 v[142:143], off
	v_lshl_add_u64 v[142:143], s[62:63], 0, v[128:129]
	s_add_i32 m0, s86, 0x2000
	s_nop 0
	global_load_lds_dwordx4 v[142:143], off
	v_lshl_add_u64 v[142:143], v[244:245], 0, s[22:23]
	s_mov_b32 m0, s77
	s_nop 0
	global_load_lds_dwordx4 v[142:143], off
	v_lshl_add_u64 v[142:143], v[246:247], 0, s[22:23]
	s_mov_b32 m0, s78
	s_nop 0
	global_load_lds_dwordx4 v[142:143], off
	s_waitcnt vmcnt(8)
	s_waitcnt lgkmcnt(0)
	s_barrier
	s_setprio 1
	s_waitcnt lgkmcnt(0)
	v_mfma_f32_16x16x32_bf16 v[60:63], v[138:141], v[210:213], v[60:63]
	v_mfma_f32_16x16x32_bf16 v[52:55], v[176:179], v[210:213], v[52:55]
	v_mfma_f32_16x16x32_bf16 v[44:47], v[138:141], v[218:221], v[44:47]
	v_mfma_f32_16x16x32_bf16 v[36:39], v[176:179], v[218:221], v[36:39]
	v_mfma_f32_16x16x32_bf16 v[28:31], v[138:141], v[228:231], v[28:31]
	v_mfma_f32_16x16x32_bf16 v[20:23], v[176:179], v[228:231], v[20:23]
	v_mfma_f32_16x16x32_bf16 v[12:15], v[138:141], v[236:239], v[12:15]
	v_mfma_f32_16x16x32_bf16 v[4:7], v[176:179], v[236:239], v[4:7]
	v_mfma_f32_16x16x32_bf16 v[60:63], v[172:175], v[214:217], v[60:63]
	v_mfma_f32_16x16x32_bf16 v[52:55], v[180:183], v[214:217], v[52:55]
	v_mfma_f32_16x16x32_bf16 v[44:47], v[172:175], v[224:227], v[44:47]
	v_mfma_f32_16x16x32_bf16 v[36:39], v[180:183], v[224:227], v[36:39]
	v_mfma_f32_16x16x32_bf16 v[28:31], v[172:175], v[232:235], v[28:31]
	v_mfma_f32_16x16x32_bf16 v[20:23], v[180:183], v[232:235], v[20:23]
	v_mfma_f32_16x16x32_bf16 v[12:15], v[172:175], v[240:243], v[12:15]
	v_mfma_f32_16x16x32_bf16 v[4:7], v[180:183], v[240:243], v[4:7]
	s_setprio 0
	s_setprio 1
	v_mfma_f32_16x16x32_bf16 v[56:59], v[184:187], v[210:213], v[56:59]
	v_mfma_f32_16x16x32_bf16 v[48:51], v[192:195], v[210:213], v[48:51]
	v_mfma_f32_16x16x32_bf16 v[40:43], v[184:187], v[218:221], v[40:43]
	v_mfma_f32_16x16x32_bf16 v[32:35], v[192:195], v[218:221], v[32:35]
	v_mfma_f32_16x16x32_bf16 v[24:27], v[184:187], v[228:231], v[24:27]
	v_mfma_f32_16x16x32_bf16 v[16:19], v[192:195], v[228:231], v[16:19]
	v_mfma_f32_16x16x32_bf16 v[8:11], v[184:187], v[236:239], v[8:11]
	v_mfma_f32_16x16x32_bf16 v[0:3], v[192:195], v[236:239], v[0:3]
	v_mfma_f32_16x16x32_bf16 v[56:59], v[188:191], v[214:217], v[56:59]
	v_mfma_f32_16x16x32_bf16 v[48:51], v[196:199], v[214:217], v[48:51]
	v_mfma_f32_16x16x32_bf16 v[40:43], v[188:191], v[224:227], v[40:43]
	v_mfma_f32_16x16x32_bf16 v[32:35], v[196:199], v[224:227], v[32:35]
	v_mfma_f32_16x16x32_bf16 v[24:27], v[188:191], v[232:235], v[24:27]
	v_mfma_f32_16x16x32_bf16 v[16:19], v[196:199], v[232:235], v[16:19]
	v_mfma_f32_16x16x32_bf16 v[8:11], v[188:191], v[240:243], v[8:11]
	s_barrier
	v_mfma_f32_16x16x32_bf16 v[0:3], v[196:199], v[240:243], v[0:3]
	s_setprio 0
	s_add_i32 s85, s85, 2
	s_add_u32 s89, s89, 0x100
	s_addc_u32 s84, s84, 0
	s_add_u32 s60, s60, 0x100
	s_addc_u32 s61, s61, 0
	s_cmp_gt_u32 s85, 13
.LBB0_180:
	s_add_u32 s62, s60, 0xfffc0080
	s_addc_u32 s63, s61, -1
	s_add_i32 s86, 0, 0x10000
	s_cmp_eq_u32 s85, 12
	s_cselect_b32 vcc_hi, s47, s63
	s_cselect_b32 vcc_lo, s82, s62
	v_add_u32_e32 v142, s86, v145
	s_cselect_b32 s63, s21, s84
	s_cselect_b32 s62, s83, s89
	s_add_i32 s92, 0, 0x14000
	ds_read_b128 v[138:141], v142
	ds_read_b128 v[172:175], v142 offset:1024
	ds_read_b128 v[176:179], v142 offset:2048
	ds_read_b128 v[180:183], v142 offset:3072
	v_add_u32_e32 v142, s92, v145
	ds_read_b128 v[184:187], v142
	ds_read_b128 v[188:191], v142 offset:1024
	ds_read_b128 v[192:195], v142 offset:2048
	ds_read_b128 v[196:199], v142 offset:3072
	v_lshl_add_u64 v[142:143], s[60:61], 0, v[136:137]
	s_add_i32 m0, s68, 0xc000
	ds_read_b128 v[210:213], v148
	ds_read_b128 v[214:217], v148 offset:1024
	ds_read_b128 v[218:221], v148 offset:2048
	ds_read_b128 v[224:227], v148 offset:3072
	ds_read_b128 v[228:231], v148 offset:4096
	ds_read_b128 v[232:235], v148 offset:5120
	ds_read_b128 v[236:239], v148 offset:6144
	ds_read_b128 v[240:243], v148 offset:7168
	global_load_lds_dwordx4 v[142:143], off
	v_lshl_add_u64 v[142:143], s[60:61], 0, v[134:135]
	s_add_i32 m0, s68, 0xe000
	s_nop 0
	global_load_lds_dwordx4 v[142:143], off
	s_waitcnt vmcnt(8)
	s_waitcnt lgkmcnt(0)
	s_barrier
	s_setprio 1
	s_waitcnt lgkmcnt(0)
	v_mfma_f32_16x16x32_bf16 v[124:127], v[138:141], v[210:213], v[124:127]
	v_mfma_f32_16x16x32_bf16 v[116:119], v[176:179], v[210:213], v[116:119]
	v_mfma_f32_16x16x32_bf16 v[108:111], v[138:141], v[218:221], v[108:111]
	v_mfma_f32_16x16x32_bf16 v[100:103], v[176:179], v[218:221], v[100:103]
	v_mfma_f32_16x16x32_bf16 v[92:95], v[138:141], v[228:231], v[92:95]
	v_mfma_f32_16x16x32_bf16 v[84:87], v[176:179], v[228:231], v[84:87]
	v_mfma_f32_16x16x32_bf16 v[76:79], v[138:141], v[236:239], v[76:79]
	v_mfma_f32_16x16x32_bf16 v[68:71], v[176:179], v[236:239], v[68:71]
	v_mfma_f32_16x16x32_bf16 v[124:127], v[172:175], v[214:217], v[124:127]
	v_mfma_f32_16x16x32_bf16 v[116:119], v[180:183], v[214:217], v[116:119]
	v_mfma_f32_16x16x32_bf16 v[108:111], v[172:175], v[224:227], v[108:111]
	v_mfma_f32_16x16x32_bf16 v[100:103], v[180:183], v[224:227], v[100:103]
	v_mfma_f32_16x16x32_bf16 v[92:95], v[172:175], v[232:235], v[92:95]
	v_mfma_f32_16x16x32_bf16 v[84:87], v[180:183], v[232:235], v[84:87]
	v_mfma_f32_16x16x32_bf16 v[76:79], v[172:175], v[240:243], v[76:79]
	v_mfma_f32_16x16x32_bf16 v[68:71], v[180:183], v[240:243], v[68:71]
	s_setprio 0
	s_setprio 1
	v_mfma_f32_16x16x32_bf16 v[120:123], v[184:187], v[210:213], v[120:123]
	v_mfma_f32_16x16x32_bf16 v[112:115], v[192:195], v[210:213], v[112:115]
	v_mfma_f32_16x16x32_bf16 v[104:107], v[184:187], v[218:221], v[104:107]
	v_mfma_f32_16x16x32_bf16 v[96:99], v[192:195], v[218:221], v[96:99]
	v_mfma_f32_16x16x32_bf16 v[88:91], v[184:187], v[228:231], v[88:91]
	v_mfma_f32_16x16x32_bf16 v[80:83], v[192:195], v[228:231], v[80:83]
	v_mfma_f32_16x16x32_bf16 v[72:75], v[184:187], v[236:239], v[72:75]
	v_mfma_f32_16x16x32_bf16 v[64:67], v[192:195], v[236:239], v[64:67]
	v_mfma_f32_16x16x32_bf16 v[120:123], v[188:191], v[214:217], v[120:123]
	v_mfma_f32_16x16x32_bf16 v[112:115], v[196:199], v[214:217], v[112:115]
	v_mfma_f32_16x16x32_bf16 v[104:107], v[188:191], v[224:227], v[104:107]
	v_mfma_f32_16x16x32_bf16 v[96:99], v[196:199], v[224:227], v[96:99]
	v_mfma_f32_16x16x32_bf16 v[88:91], v[188:191], v[232:235], v[88:91]
	v_mfma_f32_16x16x32_bf16 v[80:83], v[196:199], v[232:235], v[80:83]
	v_mfma_f32_16x16x32_bf16 v[72:75], v[188:191], v[240:243], v[72:75]
	s_barrier
	v_mfma_f32_16x16x32_bf16 v[64:67], v[196:199], v[240:243], v[64:67]
	s_setprio 0
	s_add_i32 s86, s86, s67
	v_lshl_add_u64 v[142:143], s[62:63], 0, v[152:153]
	s_mov_b32 m0, s86
	ds_read_b128 v[210:213], v148 offset:16384
	ds_read_b128 v[214:217], v148 offset:17408
	ds_read_b128 v[218:221], v148 offset:18432
	ds_read_b128 v[224:227], v148 offset:19456
	ds_read_b128 v[228:231], v148 offset:20480
	ds_read_b128 v[232:235], v148 offset:21504
	ds_read_b128 v[236:239], v148 offset:22528
	ds_read_b128 v[240:243], v148 offset:23552
	global_load_lds_dwordx4 v[142:143], off
	s_add_i32 m0, s86, 0x2000
	s_add_u32 s86, s62, 0x40000
	v_lshl_add_u64 v[150:151], s[62:63], 0, v[128:129]
	s_addc_u32 s87, s63, 0
	s_add_i32 s92, s92, s67
	global_load_lds_dwordx4 v[150:151], off
	v_lshl_add_u64 v[244:245], s[86:87], 0, v[152:153]
	s_mov_b32 m0, s92
	v_lshl_add_u64 v[246:247], vcc, 0, v[130:131]
	global_load_lds_dwordx4 v[244:245], off
	v_lshl_add_u64 v[244:245], s[86:87], 0, v[128:129]
	s_add_i32 m0, s92, 0x2000
	s_nop 0
	global_load_lds_dwordx4 v[244:245], off
	v_lshl_add_u64 v[244:245], vcc, 0, v[132:133]
	s_mov_b32 m0, s68
	s_nop 0
	global_load_lds_dwordx4 v[244:245], off
	s_mov_b32 m0, s69
	s_nop 0
	global_load_lds_dwordx4 v[246:247], off
	s_waitcnt vmcnt(8)
	s_waitcnt lgkmcnt(0)
	s_barrier
	s_setprio 1
	s_waitcnt lgkmcnt(0)
	v_mfma_f32_16x16x32_bf16 v[60:63], v[138:141], v[210:213], v[60:63]
	v_mfma_f32_16x16x32_bf16 v[52:55], v[176:179], v[210:213], v[52:55]
	v_mfma_f32_16x16x32_bf16 v[44:47], v[138:141], v[218:221], v[44:47]
	v_mfma_f32_16x16x32_bf16 v[36:39], v[176:179], v[218:221], v[36:39]
	v_mfma_f32_16x16x32_bf16 v[28:31], v[138:141], v[228:231], v[28:31]
	v_mfma_f32_16x16x32_bf16 v[20:23], v[176:179], v[228:231], v[20:23]
	v_mfma_f32_16x16x32_bf16 v[12:15], v[138:141], v[236:239], v[12:15]
	v_mfma_f32_16x16x32_bf16 v[4:7], v[176:179], v[236:239], v[4:7]
	v_mfma_f32_16x16x32_bf16 v[60:63], v[172:175], v[214:217], v[60:63]
	v_mfma_f32_16x16x32_bf16 v[52:55], v[180:183], v[214:217], v[52:55]
	v_mfma_f32_16x16x32_bf16 v[44:47], v[172:175], v[224:227], v[44:47]
	v_mfma_f32_16x16x32_bf16 v[36:39], v[180:183], v[224:227], v[36:39]
	v_mfma_f32_16x16x32_bf16 v[28:31], v[172:175], v[232:235], v[28:31]
	v_mfma_f32_16x16x32_bf16 v[20:23], v[180:183], v[232:235], v[20:23]
	v_mfma_f32_16x16x32_bf16 v[12:15], v[172:175], v[240:243], v[12:15]
	v_mfma_f32_16x16x32_bf16 v[4:7], v[180:183], v[240:243], v[4:7]
	s_setprio 0
	s_setprio 1
	v_mfma_f32_16x16x32_bf16 v[56:59], v[184:187], v[210:213], v[56:59]
	v_mfma_f32_16x16x32_bf16 v[48:51], v[192:195], v[210:213], v[48:51]
	v_mfma_f32_16x16x32_bf16 v[40:43], v[184:187], v[218:221], v[40:43]
	v_mfma_f32_16x16x32_bf16 v[32:35], v[192:195], v[218:221], v[32:35]
	v_mfma_f32_16x16x32_bf16 v[24:27], v[184:187], v[228:231], v[24:27]
	v_mfma_f32_16x16x32_bf16 v[16:19], v[192:195], v[228:231], v[16:19]
	v_mfma_f32_16x16x32_bf16 v[8:11], v[184:187], v[236:239], v[8:11]
	v_mfma_f32_16x16x32_bf16 v[0:3], v[192:195], v[236:239], v[0:3]
	v_mfma_f32_16x16x32_bf16 v[56:59], v[188:191], v[214:217], v[56:59]
	v_mfma_f32_16x16x32_bf16 v[48:51], v[196:199], v[214:217], v[48:51]
	v_mfma_f32_16x16x32_bf16 v[40:43], v[188:191], v[224:227], v[40:43]
	v_mfma_f32_16x16x32_bf16 v[32:35], v[196:199], v[224:227], v[32:35]
	v_mfma_f32_16x16x32_bf16 v[24:27], v[188:191], v[232:235], v[24:27]
	v_mfma_f32_16x16x32_bf16 v[16:19], v[196:199], v[232:235], v[16:19]
	v_mfma_f32_16x16x32_bf16 v[8:11], v[188:191], v[240:243], v[8:11]
	s_barrier
	v_mfma_f32_16x16x32_bf16 v[0:3], v[196:199], v[240:243], v[0:3]
	s_setprio 0
	s_add_i32 s92, 0, 0x18000
	v_add_u32_e32 v149, s92, v145
	s_add_i32 s93, 0, 0x1c000
	ds_read_b128 v[138:141], v149
	ds_read_b128 v[172:175], v149 offset:1024
	ds_read_b128 v[176:179], v149 offset:2048
	ds_read_b128 v[180:183], v149 offset:3072
	v_add_u32_e32 v149, s93, v145
	ds_read_b128 v[184:187], v149
	ds_read_b128 v[188:191], v149 offset:1024
	ds_read_b128 v[192:195], v149 offset:2048
	ds_read_b128 v[196:199], v149 offset:3072
	s_add_u32 s86, vcc_lo, 0x40000
	s_addc_u32 s87, vcc_hi, 0
	s_mov_b32 m0, s74
	v_lshl_add_u64 v[248:249], s[86:87], 0, v[132:133]
	ds_read_b128 v[210:213], v148 offset:32768
	ds_read_b128 v[214:217], v148 offset:33792
	ds_read_b128 v[218:221], v148 offset:34816
	ds_read_b128 v[224:227], v148 offset:35840
	ds_read_b128 v[228:231], v148 offset:36864
	ds_read_b128 v[232:235], v148 offset:37888
	ds_read_b128 v[236:239], v148 offset:38912
	ds_read_b128 v[240:243], v148 offset:39936
	global_load_lds_dwordx4 v[248:249], off
	v_lshl_add_u64 v[248:249], s[86:87], 0, v[130:131]
	s_mov_b32 m0, s75
	s_nop 0
	global_load_lds_dwordx4 v[248:249], off
	s_waitcnt vmcnt(8)
	s_waitcnt lgkmcnt(0)
	s_barrier
	s_setprio 1
	s_waitcnt lgkmcnt(0)
	v_mfma_f32_16x16x32_bf16 v[124:127], v[138:141], v[210:213], v[124:127]
	v_mfma_f32_16x16x32_bf16 v[116:119], v[176:179], v[210:213], v[116:119]
	v_mfma_f32_16x16x32_bf16 v[108:111], v[138:141], v[218:221], v[108:111]
	v_mfma_f32_16x16x32_bf16 v[100:103], v[176:179], v[218:221], v[100:103]
	v_mfma_f32_16x16x32_bf16 v[92:95], v[138:141], v[228:231], v[92:95]
	v_mfma_f32_16x16x32_bf16 v[84:87], v[176:179], v[228:231], v[84:87]
	v_mfma_f32_16x16x32_bf16 v[76:79], v[138:141], v[236:239], v[76:79]
	v_mfma_f32_16x16x32_bf16 v[68:71], v[176:179], v[236:239], v[68:71]
	v_mfma_f32_16x16x32_bf16 v[124:127], v[172:175], v[214:217], v[124:127]
	v_mfma_f32_16x16x32_bf16 v[116:119], v[180:183], v[214:217], v[116:119]
	v_mfma_f32_16x16x32_bf16 v[108:111], v[172:175], v[224:227], v[108:111]
	v_mfma_f32_16x16x32_bf16 v[100:103], v[180:183], v[224:227], v[100:103]
	v_mfma_f32_16x16x32_bf16 v[92:95], v[172:175], v[232:235], v[92:95]
	v_mfma_f32_16x16x32_bf16 v[84:87], v[180:183], v[232:235], v[84:87]
	v_mfma_f32_16x16x32_bf16 v[76:79], v[172:175], v[240:243], v[76:79]
	v_mfma_f32_16x16x32_bf16 v[68:71], v[180:183], v[240:243], v[68:71]
	s_setprio 0
	s_setprio 1
	v_mfma_f32_16x16x32_bf16 v[120:123], v[184:187], v[210:213], v[120:123]
	v_mfma_f32_16x16x32_bf16 v[112:115], v[192:195], v[210:213], v[112:115]
	v_mfma_f32_16x16x32_bf16 v[104:107], v[184:187], v[218:221], v[104:107]
	v_mfma_f32_16x16x32_bf16 v[96:99], v[192:195], v[218:221], v[96:99]
	v_mfma_f32_16x16x32_bf16 v[88:91], v[184:187], v[228:231], v[88:91]
	v_mfma_f32_16x16x32_bf16 v[80:83], v[192:195], v[228:231], v[80:83]
	v_mfma_f32_16x16x32_bf16 v[72:75], v[184:187], v[236:239], v[72:75]
	v_mfma_f32_16x16x32_bf16 v[64:67], v[192:195], v[236:239], v[64:67]
	v_mfma_f32_16x16x32_bf16 v[120:123], v[188:191], v[214:217], v[120:123]
	v_mfma_f32_16x16x32_bf16 v[112:115], v[196:199], v[214:217], v[112:115]
	v_mfma_f32_16x16x32_bf16 v[104:107], v[188:191], v[224:227], v[104:107]
	v_mfma_f32_16x16x32_bf16 v[96:99], v[196:199], v[224:227], v[96:99]
	v_mfma_f32_16x16x32_bf16 v[88:91], v[188:191], v[232:235], v[88:91]
	v_mfma_f32_16x16x32_bf16 v[80:83], v[196:199], v[232:235], v[80:83]
	v_mfma_f32_16x16x32_bf16 v[72:75], v[188:191], v[240:243], v[72:75]
	s_barrier
	v_mfma_f32_16x16x32_bf16 v[64:67], v[196:199], v[240:243], v[64:67]
	s_setprio 0
	s_add_i32 s86, s92, s67
	v_lshl_add_u64 v[142:143], v[142:143], 0, s[22:23]
	s_mov_b32 m0, s86
	ds_read_b128 v[210:213], v148 offset:49152
	ds_read_b128 v[214:217], v148 offset:50176
	ds_read_b128 v[218:221], v148 offset:51200
	ds_read_b128 v[224:227], v148 offset:52224
	ds_read_b128 v[228:231], v148 offset:53248
	ds_read_b128 v[232:235], v148 offset:54272
	ds_read_b128 v[236:239], v148 offset:55296
	ds_read_b128 v[240:243], v148 offset:56320
	global_load_lds_dwordx4 v[142:143], off
	s_add_i32 m0, s86, 0x2000
	s_add_u32 s62, s62, 0x40080
	v_lshl_add_u64 v[142:143], v[150:151], 0, s[22:23]
	s_addc_u32 s63, s63, 0
	s_add_i32 s86, s93, s67
	global_load_lds_dwordx4 v[142:143], off
	v_lshl_add_u64 v[142:143], s[62:63], 0, v[152:153]
	s_mov_b32 m0, s86
	s_nop 0
	global_load_lds_dwordx4 v[142:143], off
	v_lshl_add_u64 v[142:143], s[62:63], 0, v[128:129]
	s_add_i32 m0, s86, 0x2000
	s_nop 0
	global_load_lds_dwordx4 v[142:143], off
	v_lshl_add_u64 v[142:143], v[244:245], 0, s[22:23]
	s_mov_b32 m0, s77
	s_nop 0
	global_load_lds_dwordx4 v[142:143], off
	v_lshl_add_u64 v[142:143], v[246:247], 0, s[22:23]
	s_mov_b32 m0, s78
	s_nop 0
	global_load_lds_dwordx4 v[142:143], off
	s_waitcnt vmcnt(8)
	s_waitcnt lgkmcnt(0)
	s_barrier
	s_setprio 1
	s_waitcnt lgkmcnt(0)
	v_mfma_f32_16x16x32_bf16 v[60:63], v[138:141], v[210:213], v[60:63]
	v_mfma_f32_16x16x32_bf16 v[52:55], v[176:179], v[210:213], v[52:55]
	v_mfma_f32_16x16x32_bf16 v[44:47], v[138:141], v[218:221], v[44:47]
	v_mfma_f32_16x16x32_bf16 v[36:39], v[176:179], v[218:221], v[36:39]
	v_mfma_f32_16x16x32_bf16 v[28:31], v[138:141], v[228:231], v[28:31]
	v_mfma_f32_16x16x32_bf16 v[20:23], v[176:179], v[228:231], v[20:23]
	v_mfma_f32_16x16x32_bf16 v[12:15], v[138:141], v[236:239], v[12:15]
	v_mfma_f32_16x16x32_bf16 v[4:7], v[176:179], v[236:239], v[4:7]
	v_mfma_f32_16x16x32_bf16 v[60:63], v[172:175], v[214:217], v[60:63]
	v_mfma_f32_16x16x32_bf16 v[52:55], v[180:183], v[214:217], v[52:55]
	v_mfma_f32_16x16x32_bf16 v[44:47], v[172:175], v[224:227], v[44:47]
	v_mfma_f32_16x16x32_bf16 v[36:39], v[180:183], v[224:227], v[36:39]
	v_mfma_f32_16x16x32_bf16 v[28:31], v[172:175], v[232:235], v[28:31]
	v_mfma_f32_16x16x32_bf16 v[20:23], v[180:183], v[232:235], v[20:23]
	v_mfma_f32_16x16x32_bf16 v[12:15], v[172:175], v[240:243], v[12:15]
	v_mfma_f32_16x16x32_bf16 v[4:7], v[180:183], v[240:243], v[4:7]
	s_setprio 0
	s_setprio 1
	v_mfma_f32_16x16x32_bf16 v[56:59], v[184:187], v[210:213], v[56:59]
	v_mfma_f32_16x16x32_bf16 v[48:51], v[192:195], v[210:213], v[48:51]
	v_mfma_f32_16x16x32_bf16 v[40:43], v[184:187], v[218:221], v[40:43]
	v_mfma_f32_16x16x32_bf16 v[32:35], v[192:195], v[218:221], v[32:35]
	v_mfma_f32_16x16x32_bf16 v[24:27], v[184:187], v[228:231], v[24:27]
	v_mfma_f32_16x16x32_bf16 v[16:19], v[192:195], v[228:231], v[16:19]
	v_mfma_f32_16x16x32_bf16 v[8:11], v[184:187], v[236:239], v[8:11]
	v_mfma_f32_16x16x32_bf16 v[0:3], v[192:195], v[236:239], v[0:3]
	v_mfma_f32_16x16x32_bf16 v[56:59], v[188:191], v[214:217], v[56:59]
	v_mfma_f32_16x16x32_bf16 v[48:51], v[196:199], v[214:217], v[48:51]
	v_mfma_f32_16x16x32_bf16 v[40:43], v[188:191], v[224:227], v[40:43]
	v_mfma_f32_16x16x32_bf16 v[32:35], v[196:199], v[224:227], v[32:35]
	v_mfma_f32_16x16x32_bf16 v[24:27], v[188:191], v[232:235], v[24:27]
	v_mfma_f32_16x16x32_bf16 v[16:19], v[196:199], v[232:235], v[16:19]
	v_mfma_f32_16x16x32_bf16 v[8:11], v[188:191], v[240:243], v[8:11]
	s_barrier
	v_mfma_f32_16x16x32_bf16 v[0:3], v[196:199], v[240:243], v[0:3]
	s_setprio 0
	s_add_i32 s85, s85, 2
	s_add_u32 s89, s89, 0x100
	s_addc_u32 s84, s84, 0
	s_add_u32 s60, s60, 0x100
	s_addc_u32 s61, s61, 0
	s_cmp_gt_u32 s85, 13
	s_cbranch_scc0 .LBB0_180
	s_and_b64 vcc, exec, s[18:19]
	s_cbranch_vccz .LBB0_183
	s_barrier

.LBB0_280:
	s_add_u32 s84, s18, 0x100
	s_addc_u32 s85, s19, 0
	s_mov_b32 s86, -2
	s_waitcnt lgkmcnt(0)
	s_add_u32 vcc_lo, s60, 0x100
	s_addc_u32 vcc_hi, s61, 0
	s_add_i32 s87, 0, 0x10000
	s_cmp_eq_u32 s86, 40
	s_cselect_b32 s67, s51, vcc_hi
	s_cselect_b32 s66, s50, vcc_lo
	s_cselect_b32 s19, s45, s85
	s_cselect_b32 s18, s44, s84
	s_add_i32 s92, 0, 0x14000
	v_add_u32_e32 v140, s87, v210
	v_add_u32_e32 v186, s92, v210
	ds_read_b128 v[128:131], v140
	ds_read_b128 v[132:135], v140 offset:1024
	ds_read_b128 v[136:139], v140 offset:2048
	ds_read_b128 v[140:143], v140 offset:3072
	ds_read_b128 v[144:147], v186
	ds_read_b128 v[148:151], v186 offset:1024
	ds_read_b128 v[182:185], v186 offset:2048
	ds_read_b128 v[186:189], v186 offset:3072
	v_lshl_add_u64 v[198:199], s[60:61], 0, v[180:181]
	s_add_i32 m0, s69, 0xc000
	ds_read_b128 v[190:193], v212
	ds_read_b128 v[194:197], v212 offset:1024
	ds_read_b128 v[214:217], v212 offset:2048
	ds_read_b128 v[218:221], v212 offset:3072
	ds_read_b128 v[224:227], v212 offset:4096
	ds_read_b128 v[228:231], v212 offset:5120
	ds_read_b128 v[232:235], v212 offset:6144
	ds_read_b128 v[236:239], v212 offset:7168
	global_load_lds_dwordx4 v[198:199], off
	v_lshl_add_u64 v[198:199], s[60:61], 0, v[178:179]
	s_add_i32 m0, s69, 0xe000
	s_nop 0
	global_load_lds_dwordx4 v[198:199], off
	s_waitcnt vmcnt(8)
	s_waitcnt lgkmcnt(0)
	s_barrier
	s_setprio 1
	s_waitcnt lgkmcnt(0)
	v_mfma_f32_16x16x32_bf16 v[124:127], v[128:131], v[190:193], 0
	v_mfma_f32_16x16x32_bf16 v[120:123], v[136:139], v[190:193], 0
	v_mfma_f32_16x16x32_bf16 v[108:111], v[128:131], v[214:217], 0
	v_mfma_f32_16x16x32_bf16 v[104:107], v[136:139], v[214:217], 0
	v_mfma_f32_16x16x32_bf16 v[92:95], v[128:131], v[224:227], 0
	v_mfma_f32_16x16x32_bf16 v[88:91], v[136:139], v[224:227], 0
	v_mfma_f32_16x16x32_bf16 v[76:79], v[128:131], v[232:235], 0
	v_mfma_f32_16x16x32_bf16 v[72:75], v[136:139], v[232:235], 0
	v_mfma_f32_16x16x32_bf16 v[124:127], v[132:135], v[194:197], v[124:127]
	v_mfma_f32_16x16x32_bf16 v[120:123], v[140:143], v[194:197], v[120:123]
	v_mfma_f32_16x16x32_bf16 v[108:111], v[132:135], v[218:221], v[108:111]
	v_mfma_f32_16x16x32_bf16 v[104:107], v[140:143], v[218:221], v[104:107]
	v_mfma_f32_16x16x32_bf16 v[92:95], v[132:135], v[228:231], v[92:95]
	v_mfma_f32_16x16x32_bf16 v[88:91], v[140:143], v[228:231], v[88:91]
	v_mfma_f32_16x16x32_bf16 v[76:79], v[132:135], v[236:239], v[76:79]
	v_mfma_f32_16x16x32_bf16 v[72:75], v[140:143], v[236:239], v[72:75]
	s_setprio 0
	s_setprio 1
	v_mfma_f32_16x16x32_bf16 v[116:119], v[144:147], v[190:193], 0
	v_mfma_f32_16x16x32_bf16 v[112:115], v[182:185], v[190:193], 0
	v_mfma_f32_16x16x32_bf16 v[100:103], v[144:147], v[214:217], 0
	v_mfma_f32_16x16x32_bf16 v[96:99], v[182:185], v[214:217], 0
	v_mfma_f32_16x16x32_bf16 v[84:87], v[144:147], v[224:227], 0
	v_mfma_f32_16x16x32_bf16 v[80:83], v[182:185], v[224:227], 0
	v_mfma_f32_16x16x32_bf16 v[68:71], v[144:147], v[232:235], 0
	v_mfma_f32_16x16x32_bf16 v[64:67], v[182:185], v[232:235], 0
	v_mfma_f32_16x16x32_bf16 v[116:119], v[148:151], v[194:197], v[116:119]
	v_mfma_f32_16x16x32_bf16 v[112:115], v[186:189], v[194:197], v[112:115]
	v_mfma_f32_16x16x32_bf16 v[100:103], v[148:151], v[218:221], v[100:103]
	v_mfma_f32_16x16x32_bf16 v[96:99], v[186:189], v[218:221], v[96:99]
	v_mfma_f32_16x16x32_bf16 v[84:87], v[148:151], v[228:231], v[84:87]
	v_mfma_f32_16x16x32_bf16 v[80:83], v[186:189], v[228:231], v[80:83]
	v_mfma_f32_16x16x32_bf16 v[68:71], v[148:151], v[236:239], v[68:71]
	s_barrier
	v_mfma_f32_16x16x32_bf16 v[64:67], v[186:189], v[236:239], v[64:67]
	s_setprio 0
	s_add_i32 s60, s87, s68
	v_lshl_add_u64 v[198:199], s[18:19], 0, v[152:153]
	s_mov_b32 m0, s60
	ds_read_b128 v[190:193], v212 offset:16384
	ds_read_b128 v[194:197], v212 offset:17408
	ds_read_b128 v[214:217], v212 offset:18432
	ds_read_b128 v[218:221], v212 offset:19456
	ds_read_b128 v[224:227], v212 offset:20480
	ds_read_b128 v[228:231], v212 offset:21504
	ds_read_b128 v[232:235], v212 offset:22528
	ds_read_b128 v[236:239], v212 offset:23552
	global_load_lds_dwordx4 v[198:199], off
	s_add_i32 m0, s60, 0x2000
	s_add_u32 s60, s18, 0xb0000
	v_lshl_add_u64 v[240:241], s[18:19], 0, v[172:173]
	s_addc_u32 s61, s19, 0
	s_add_i32 s87, s92, s68
	global_load_lds_dwordx4 v[240:241], off
	v_lshl_add_u64 v[242:243], s[60:61], 0, v[152:153]
	s_mov_b32 m0, s87
	v_lshl_add_u64 v[244:245], s[66:67], 0, v[174:175]
	global_load_lds_dwordx4 v[242:243], off
	v_lshl_add_u64 v[242:243], s[60:61], 0, v[172:173]
	s_add_i32 m0, s87, 0x2000
	s_nop 0
	global_load_lds_dwordx4 v[242:243], off
	v_lshl_add_u64 v[242:243], s[66:67], 0, v[176:177]
	s_mov_b32 m0, s69
	s_nop 0
	global_load_lds_dwordx4 v[242:243], off
	s_mov_b32 m0, s74
	s_nop 0
	global_load_lds_dwordx4 v[244:245], off
	s_waitcnt vmcnt(8)
	s_waitcnt lgkmcnt(0)
	s_barrier
	s_setprio 1
	s_waitcnt lgkmcnt(0)
	v_mfma_f32_16x16x32_bf16 v[60:63], v[128:131], v[190:193], 0
	v_mfma_f32_16x16x32_bf16 v[56:59], v[136:139], v[190:193], 0
	v_mfma_f32_16x16x32_bf16 v[44:47], v[128:131], v[214:217], 0
	v_mfma_f32_16x16x32_bf16 v[40:43], v[136:139], v[214:217], 0
	v_mfma_f32_16x16x32_bf16 v[28:31], v[128:131], v[224:227], 0
	v_mfma_f32_16x16x32_bf16 v[24:27], v[136:139], v[224:227], 0
	v_mfma_f32_16x16x32_bf16 v[12:15], v[128:131], v[232:235], 0
	v_mfma_f32_16x16x32_bf16 v[8:11], v[136:139], v[232:235], 0
	v_mfma_f32_16x16x32_bf16 v[60:63], v[132:135], v[194:197], v[60:63]
	v_mfma_f32_16x16x32_bf16 v[56:59], v[140:143], v[194:197], v[56:59]
	v_mfma_f32_16x16x32_bf16 v[44:47], v[132:135], v[218:221], v[44:47]
	v_mfma_f32_16x16x32_bf16 v[40:43], v[140:143], v[218:221], v[40:43]
	v_mfma_f32_16x16x32_bf16 v[28:31], v[132:135], v[228:231], v[28:31]
	v_mfma_f32_16x16x32_bf16 v[24:27], v[140:143], v[228:231], v[24:27]
	v_mfma_f32_16x16x32_bf16 v[12:15], v[132:135], v[236:239], v[12:15]
	v_mfma_f32_16x16x32_bf16 v[8:11], v[140:143], v[236:239], v[8:11]
	s_setprio 0
	s_setprio 1
	v_mfma_f32_16x16x32_bf16 v[52:55], v[144:147], v[190:193], 0
	v_mfma_f32_16x16x32_bf16 v[48:51], v[182:185], v[190:193], 0
	v_mfma_f32_16x16x32_bf16 v[36:39], v[144:147], v[214:217], 0
	v_mfma_f32_16x16x32_bf16 v[32:35], v[182:185], v[214:217], 0
	v_mfma_f32_16x16x32_bf16 v[20:23], v[144:147], v[224:227], 0
	v_mfma_f32_16x16x32_bf16 v[16:19], v[182:185], v[224:227], 0
	v_mfma_f32_16x16x32_bf16 v[4:7], v[144:147], v[232:235], 0
	v_mfma_f32_16x16x32_bf16 v[0:3], v[182:185], v[232:235], 0
	v_mfma_f32_16x16x32_bf16 v[52:55], v[148:151], v[194:197], v[52:55]
	v_mfma_f32_16x16x32_bf16 v[48:51], v[186:189], v[194:197], v[48:51]
	v_mfma_f32_16x16x32_bf16 v[36:39], v[148:151], v[218:221], v[36:39]
	v_mfma_f32_16x16x32_bf16 v[32:35], v[186:189], v[218:221], v[32:35]
	v_mfma_f32_16x16x32_bf16 v[20:23], v[148:151], v[228:231], v[20:23]
	v_mfma_f32_16x16x32_bf16 v[16:19], v[186:189], v[228:231], v[16:19]
	v_mfma_f32_16x16x32_bf16 v[4:7], v[148:151], v[236:239], v[4:7]
	s_barrier
	v_mfma_f32_16x16x32_bf16 v[0:3], v[186:189], v[236:239], v[0:3]
	s_setprio 0
	s_add_i32 s87, 0, 0x18000
	s_add_i32 s92, 0, 0x1c000
	v_add_u32_e32 v140, s87, v210
	v_add_u32_e32 v186, s92, v210
	ds_read_b128 v[128:131], v140
	ds_read_b128 v[132:135], v140 offset:1024
	ds_read_b128 v[136:139], v140 offset:2048
	ds_read_b128 v[140:143], v140 offset:3072
	ds_read_b128 v[144:147], v186
	ds_read_b128 v[148:151], v186 offset:1024
	ds_read_b128 v[182:185], v186 offset:2048
	ds_read_b128 v[186:189], v186 offset:3072
	s_add_u32 s60, s66, 0xb0000
	s_addc_u32 s61, s67, 0
	s_mov_b32 m0, s75
	v_lshl_add_u64 v[246:247], s[60:61], 0, v[176:177]
	ds_read_b128 v[190:193], v212 offset:32768
	ds_read_b128 v[194:197], v212 offset:33792
	ds_read_b128 v[214:217], v212 offset:34816
	ds_read_b128 v[218:221], v212 offset:35840
	ds_read_b128 v[224:227], v212 offset:36864
	ds_read_b128 v[228:231], v212 offset:37888
	ds_read_b128 v[232:235], v212 offset:38912
	ds_read_b128 v[236:239], v212 offset:39936
	global_load_lds_dwordx4 v[246:247], off
	v_lshl_add_u64 v[246:247], s[60:61], 0, v[174:175]
	s_mov_b32 m0, s76
	s_nop 0
	global_load_lds_dwordx4 v[246:247], off
	s_waitcnt vmcnt(8)
	s_waitcnt lgkmcnt(0)
	s_barrier
	s_setprio 1
	s_waitcnt lgkmcnt(0)
	v_mfma_f32_16x16x32_bf16 v[124:127], v[128:131], v[190:193], v[124:127]
	v_mfma_f32_16x16x32_bf16 v[120:123], v[136:139], v[190:193], v[120:123]
	v_mfma_f32_16x16x32_bf16 v[108:111], v[128:131], v[214:217], v[108:111]
	v_mfma_f32_16x16x32_bf16 v[104:107], v[136:139], v[214:217], v[104:107]
	v_mfma_f32_16x16x32_bf16 v[92:95], v[128:131], v[224:227], v[92:95]
	v_mfma_f32_16x16x32_bf16 v[88:91], v[136:139], v[224:227], v[88:91]
	v_mfma_f32_16x16x32_bf16 v[76:79], v[128:131], v[232:235], v[76:79]
	v_mfma_f32_16x16x32_bf16 v[72:75], v[136:139], v[232:235], v[72:75]
	v_mfma_f32_16x16x32_bf16 v[124:127], v[132:135], v[194:197], v[124:127]
	v_mfma_f32_16x16x32_bf16 v[120:123], v[140:143], v[194:197], v[120:123]
	v_mfma_f32_16x16x32_bf16 v[108:111], v[132:135], v[218:221], v[108:111]
	v_mfma_f32_16x16x32_bf16 v[104:107], v[140:143], v[218:221], v[104:107]
	v_mfma_f32_16x16x32_bf16 v[92:95], v[132:135], v[228:231], v[92:95]
	v_mfma_f32_16x16x32_bf16 v[88:91], v[140:143], v[228:231], v[88:91]
	v_mfma_f32_16x16x32_bf16 v[76:79], v[132:135], v[236:239], v[76:79]
	v_mfma_f32_16x16x32_bf16 v[72:75], v[140:143], v[236:239], v[72:75]
	s_setprio 0
	s_setprio 1
	v_mfma_f32_16x16x32_bf16 v[116:119], v[144:147], v[190:193], v[116:119]
	v_mfma_f32_16x16x32_bf16 v[112:115], v[182:185], v[190:193], v[112:115]
	v_mfma_f32_16x16x32_bf16 v[100:103], v[144:147], v[214:217], v[100:103]
	v_mfma_f32_16x16x32_bf16 v[96:99], v[182:185], v[214:217], v[96:99]
	v_mfma_f32_16x16x32_bf16 v[84:87], v[144:147], v[224:227], v[84:87]
	v_mfma_f32_16x16x32_bf16 v[80:83], v[182:185], v[224:227], v[80:83]
	v_mfma_f32_16x16x32_bf16 v[68:71], v[144:147], v[232:235], v[68:71]
	v_mfma_f32_16x16x32_bf16 v[64:67], v[182:185], v[232:235], v[64:67]
	v_mfma_f32_16x16x32_bf16 v[116:119], v[148:151], v[194:197], v[116:119]
	v_mfma_f32_16x16x32_bf16 v[112:115], v[186:189], v[194:197], v[112:115]
	v_mfma_f32_16x16x32_bf16 v[100:103], v[148:151], v[218:221], v[100:103]
	v_mfma_f32_16x16x32_bf16 v[96:99], v[186:189], v[218:221], v[96:99]
	v_mfma_f32_16x16x32_bf16 v[84:87], v[148:151], v[228:231], v[84:87]
	v_mfma_f32_16x16x32_bf16 v[80:83], v[186:189], v[228:231], v[80:83]
	v_mfma_f32_16x16x32_bf16 v[68:71], v[148:151], v[236:239], v[68:71]
	s_barrier
	v_mfma_f32_16x16x32_bf16 v[64:67], v[186:189], v[236:239], v[64:67]
	s_setprio 0
	s_add_i32 s60, s87, s68
	v_lshl_add_u64 v[198:199], v[198:199], 0, s[22:23]
	s_mov_b32 m0, s60
	ds_read_b128 v[190:193], v212 offset:49152
	ds_read_b128 v[194:197], v212 offset:50176
	ds_read_b128 v[214:217], v212 offset:51200
	ds_read_b128 v[218:221], v212 offset:52224
	ds_read_b128 v[224:227], v212 offset:53248
	ds_read_b128 v[228:231], v212 offset:54272
	ds_read_b128 v[232:235], v212 offset:55296
	ds_read_b128 v[236:239], v212 offset:56320
	global_load_lds_dwordx4 v[198:199], off
	s_add_i32 m0, s60, 0x2000
	s_add_u32 s18, s18, 0xb0080
	v_lshl_add_u64 v[198:199], v[240:241], 0, s[22:23]
	s_addc_u32 s19, s19, 0
	s_add_i32 s60, s92, s68
	global_load_lds_dwordx4 v[198:199], off
	v_lshl_add_u64 v[198:199], s[18:19], 0, v[152:153]
	s_mov_b32 m0, s60
	s_nop 0
	global_load_lds_dwordx4 v[198:199], off
	v_lshl_add_u64 v[198:199], s[18:19], 0, v[172:173]
	s_add_i32 m0, s60, 0x2000
	s_nop 0
	global_load_lds_dwordx4 v[198:199], off
	v_lshl_add_u64 v[198:199], v[242:243], 0, s[22:23]
	s_mov_b32 m0, s79
	s_nop 0
	global_load_lds_dwordx4 v[198:199], off
	v_lshl_add_u64 v[198:199], v[244:245], 0, s[22:23]
	s_mov_b32 m0, s80
	s_nop 0
	global_load_lds_dwordx4 v[198:199], off
	s_waitcnt vmcnt(8)
	s_waitcnt lgkmcnt(0)
	s_barrier
	s_setprio 1
	s_waitcnt lgkmcnt(0)
	v_mfma_f32_16x16x32_bf16 v[60:63], v[128:131], v[190:193], v[60:63]
	v_mfma_f32_16x16x32_bf16 v[56:59], v[136:139], v[190:193], v[56:59]
	v_mfma_f32_16x16x32_bf16 v[44:47], v[128:131], v[214:217], v[44:47]
	v_mfma_f32_16x16x32_bf16 v[40:43], v[136:139], v[214:217], v[40:43]
	v_mfma_f32_16x16x32_bf16 v[28:31], v[128:131], v[224:227], v[28:31]
	v_mfma_f32_16x16x32_bf16 v[24:27], v[136:139], v[224:227], v[24:27]
	v_mfma_f32_16x16x32_bf16 v[12:15], v[128:131], v[232:235], v[12:15]
	v_mfma_f32_16x16x32_bf16 v[8:11], v[136:139], v[232:235], v[8:11]
	v_mfma_f32_16x16x32_bf16 v[60:63], v[132:135], v[194:197], v[60:63]
	v_mfma_f32_16x16x32_bf16 v[56:59], v[140:143], v[194:197], v[56:59]
	v_mfma_f32_16x16x32_bf16 v[44:47], v[132:135], v[218:221], v[44:47]
	v_mfma_f32_16x16x32_bf16 v[40:43], v[140:143], v[218:221], v[40:43]
	v_mfma_f32_16x16x32_bf16 v[28:31], v[132:135], v[228:231], v[28:31]
	v_mfma_f32_16x16x32_bf16 v[24:27], v[140:143], v[228:231], v[24:27]
	v_mfma_f32_16x16x32_bf16 v[12:15], v[132:135], v[236:239], v[12:15]
	v_mfma_f32_16x16x32_bf16 v[8:11], v[140:143], v[236:239], v[8:11]
	s_setprio 0
	s_setprio 1
	v_mfma_f32_16x16x32_bf16 v[52:55], v[144:147], v[190:193], v[52:55]
	v_mfma_f32_16x16x32_bf16 v[48:51], v[182:185], v[190:193], v[48:51]
	v_mfma_f32_16x16x32_bf16 v[36:39], v[144:147], v[214:217], v[36:39]
	v_mfma_f32_16x16x32_bf16 v[32:35], v[182:185], v[214:217], v[32:35]
	v_mfma_f32_16x16x32_bf16 v[20:23], v[144:147], v[224:227], v[20:23]
	v_mfma_f32_16x16x32_bf16 v[16:19], v[182:185], v[224:227], v[16:19]
	v_mfma_f32_16x16x32_bf16 v[4:7], v[144:147], v[232:235], v[4:7]
	v_mfma_f32_16x16x32_bf16 v[0:3], v[182:185], v[232:235], v[0:3]
	v_mfma_f32_16x16x32_bf16 v[52:55], v[148:151], v[194:197], v[52:55]
	v_mfma_f32_16x16x32_bf16 v[48:51], v[186:189], v[194:197], v[48:51]
	v_mfma_f32_16x16x32_bf16 v[36:39], v[148:151], v[218:221], v[36:39]
	v_mfma_f32_16x16x32_bf16 v[32:35], v[186:189], v[218:221], v[32:35]
	v_mfma_f32_16x16x32_bf16 v[20:23], v[148:151], v[228:231], v[20:23]
	v_mfma_f32_16x16x32_bf16 v[16:19], v[186:189], v[228:231], v[16:19]
	v_mfma_f32_16x16x32_bf16 v[4:7], v[148:151], v[236:239], v[4:7]
	s_barrier
	v_mfma_f32_16x16x32_bf16 v[0:3], v[186:189], v[236:239], v[0:3]
	s_setprio 0
	s_add_i32 s86, s86, 2
	s_add_u32 s84, s84, 0x100
	s_addc_u32 s85, s85, 0
	s_cmp_gt_u32 s86, 41
	s_mov_b64 s[60:61], vcc
.LBB0_281:
	s_add_u32 vcc_lo, s60, 0x100
	s_addc_u32 vcc_hi, s61, 0
	s_add_i32 s87, 0, 0x10000
	s_cmp_eq_u32 s86, 40
	s_cselect_b32 s67, s51, vcc_hi
	s_cselect_b32 s66, s50, vcc_lo
	s_cselect_b32 s19, s45, s85
	s_cselect_b32 s18, s44, s84
	s_add_i32 s92, 0, 0x14000
	v_add_u32_e32 v140, s87, v210
	v_add_u32_e32 v186, s92, v210
	ds_read_b128 v[128:131], v140
	ds_read_b128 v[132:135], v140 offset:1024
	ds_read_b128 v[136:139], v140 offset:2048
	ds_read_b128 v[140:143], v140 offset:3072
	ds_read_b128 v[144:147], v186
	ds_read_b128 v[148:151], v186 offset:1024
	ds_read_b128 v[182:185], v186 offset:2048
	ds_read_b128 v[186:189], v186 offset:3072
	v_lshl_add_u64 v[198:199], s[60:61], 0, v[180:181]
	s_add_i32 m0, s69, 0xc000
	ds_read_b128 v[190:193], v212
	ds_read_b128 v[194:197], v212 offset:1024
	ds_read_b128 v[214:217], v212 offset:2048
	ds_read_b128 v[218:221], v212 offset:3072
	ds_read_b128 v[224:227], v212 offset:4096
	ds_read_b128 v[228:231], v212 offset:5120
	ds_read_b128 v[232:235], v212 offset:6144
	ds_read_b128 v[236:239], v212 offset:7168
	global_load_lds_dwordx4 v[198:199], off
	v_lshl_add_u64 v[198:199], s[60:61], 0, v[178:179]
	s_add_i32 m0, s69, 0xe000
	s_nop 0
	global_load_lds_dwordx4 v[198:199], off
	s_waitcnt vmcnt(8)
	s_waitcnt lgkmcnt(0)
	s_barrier
	s_setprio 1
	s_waitcnt lgkmcnt(0)
	v_mfma_f32_16x16x32_bf16 v[124:127], v[128:131], v[190:193], v[124:127]
	v_mfma_f32_16x16x32_bf16 v[120:123], v[136:139], v[190:193], v[120:123]
	v_mfma_f32_16x16x32_bf16 v[108:111], v[128:131], v[214:217], v[108:111]
	v_mfma_f32_16x16x32_bf16 v[104:107], v[136:139], v[214:217], v[104:107]
	v_mfma_f32_16x16x32_bf16 v[92:95], v[128:131], v[224:227], v[92:95]
	v_mfma_f32_16x16x32_bf16 v[88:91], v[136:139], v[224:227], v[88:91]
	v_mfma_f32_16x16x32_bf16 v[76:79], v[128:131], v[232:235], v[76:79]
	v_mfma_f32_16x16x32_bf16 v[72:75], v[136:139], v[232:235], v[72:75]
	v_mfma_f32_16x16x32_bf16 v[124:127], v[132:135], v[194:197], v[124:127]
	v_mfma_f32_16x16x32_bf16 v[120:123], v[140:143], v[194:197], v[120:123]
	v_mfma_f32_16x16x32_bf16 v[108:111], v[132:135], v[218:221], v[108:111]
	v_mfma_f32_16x16x32_bf16 v[104:107], v[140:143], v[218:221], v[104:107]
	v_mfma_f32_16x16x32_bf16 v[92:95], v[132:135], v[228:231], v[92:95]
	v_mfma_f32_16x16x32_bf16 v[88:91], v[140:143], v[228:231], v[88:91]
	v_mfma_f32_16x16x32_bf16 v[76:79], v[132:135], v[236:239], v[76:79]
	v_mfma_f32_16x16x32_bf16 v[72:75], v[140:143], v[236:239], v[72:75]
	s_setprio 0
	s_setprio 1
	v_mfma_f32_16x16x32_bf16 v[116:119], v[144:147], v[190:193], v[116:119]
	v_mfma_f32_16x16x32_bf16 v[112:115], v[182:185], v[190:193], v[112:115]
	v_mfma_f32_16x16x32_bf16 v[100:103], v[144:147], v[214:217], v[100:103]
	v_mfma_f32_16x16x32_bf16 v[96:99], v[182:185], v[214:217], v[96:99]
	v_mfma_f32_16x16x32_bf16 v[84:87], v[144:147], v[224:227], v[84:87]
	v_mfma_f32_16x16x32_bf16 v[80:83], v[182:185], v[224:227], v[80:83]
	v_mfma_f32_16x16x32_bf16 v[68:71], v[144:147], v[232:235], v[68:71]
	v_mfma_f32_16x16x32_bf16 v[64:67], v[182:185], v[232:235], v[64:67]
	v_mfma_f32_16x16x32_bf16 v[116:119], v[148:151], v[194:197], v[116:119]
	v_mfma_f32_16x16x32_bf16 v[112:115], v[186:189], v[194:197], v[112:115]
	v_mfma_f32_16x16x32_bf16 v[100:103], v[148:151], v[218:221], v[100:103]
	v_mfma_f32_16x16x32_bf16 v[96:99], v[186:189], v[218:221], v[96:99]
	v_mfma_f32_16x16x32_bf16 v[84:87], v[148:151], v[228:231], v[84:87]
	v_mfma_f32_16x16x32_bf16 v[80:83], v[186:189], v[228:231], v[80:83]
	v_mfma_f32_16x16x32_bf16 v[68:71], v[148:151], v[236:239], v[68:71]
	s_barrier
	v_mfma_f32_16x16x32_bf16 v[64:67], v[186:189], v[236:239], v[64:67]
	s_setprio 0
	s_add_i32 s60, s87, s68
	v_lshl_add_u64 v[198:199], s[18:19], 0, v[152:153]
	s_mov_b32 m0, s60
	ds_read_b128 v[190:193], v212 offset:16384
	ds_read_b128 v[194:197], v212 offset:17408
	ds_read_b128 v[214:217], v212 offset:18432
	ds_read_b128 v[218:221], v212 offset:19456
	ds_read_b128 v[224:227], v212 offset:20480
	ds_read_b128 v[228:231], v212 offset:21504
	ds_read_b128 v[232:235], v212 offset:22528
	ds_read_b128 v[236:239], v212 offset:23552
	global_load_lds_dwordx4 v[198:199], off
	s_add_i32 m0, s60, 0x2000
	s_add_u32 s60, s18, 0xb0000
	v_lshl_add_u64 v[240:241], s[18:19], 0, v[172:173]
	s_addc_u32 s61, s19, 0
	s_add_i32 s87, s92, s68
	global_load_lds_dwordx4 v[240:241], off
	v_lshl_add_u64 v[242:243], s[60:61], 0, v[152:153]
	s_mov_b32 m0, s87
	v_lshl_add_u64 v[244:245], s[66:67], 0, v[174:175]
	global_load_lds_dwordx4 v[242:243], off
	v_lshl_add_u64 v[242:243], s[60:61], 0, v[172:173]
	s_add_i32 m0, s87, 0x2000
	s_nop 0
	global_load_lds_dwordx4 v[242:243], off
	v_lshl_add_u64 v[242:243], s[66:67], 0, v[176:177]
	s_mov_b32 m0, s69
	s_nop 0
	global_load_lds_dwordx4 v[242:243], off
	s_mov_b32 m0, s74
	s_nop 0
	global_load_lds_dwordx4 v[244:245], off
	s_waitcnt vmcnt(8)
	s_waitcnt lgkmcnt(0)
	s_barrier
	s_setprio 1
	s_waitcnt lgkmcnt(0)
	v_mfma_f32_16x16x32_bf16 v[60:63], v[128:131], v[190:193], v[60:63]
	v_mfma_f32_16x16x32_bf16 v[56:59], v[136:139], v[190:193], v[56:59]
	v_mfma_f32_16x16x32_bf16 v[44:47], v[128:131], v[214:217], v[44:47]
	v_mfma_f32_16x16x32_bf16 v[40:43], v[136:139], v[214:217], v[40:43]
	v_mfma_f32_16x16x32_bf16 v[28:31], v[128:131], v[224:227], v[28:31]
	v_mfma_f32_16x16x32_bf16 v[24:27], v[136:139], v[224:227], v[24:27]
	v_mfma_f32_16x16x32_bf16 v[12:15], v[128:131], v[232:235], v[12:15]
	v_mfma_f32_16x16x32_bf16 v[8:11], v[136:139], v[232:235], v[8:11]
	v_mfma_f32_16x16x32_bf16 v[60:63], v[132:135], v[194:197], v[60:63]
	v_mfma_f32_16x16x32_bf16 v[56:59], v[140:143], v[194:197], v[56:59]
	v_mfma_f32_16x16x32_bf16 v[44:47], v[132:135], v[218:221], v[44:47]
	v_mfma_f32_16x16x32_bf16 v[40:43], v[140:143], v[218:221], v[40:43]
	v_mfma_f32_16x16x32_bf16 v[28:31], v[132:135], v[228:231], v[28:31]
	v_mfma_f32_16x16x32_bf16 v[24:27], v[140:143], v[228:231], v[24:27]
	v_mfma_f32_16x16x32_bf16 v[12:15], v[132:135], v[236:239], v[12:15]
	v_mfma_f32_16x16x32_bf16 v[8:11], v[140:143], v[236:239], v[8:11]
	s_setprio 0
	s_setprio 1
	v_mfma_f32_16x16x32_bf16 v[52:55], v[144:147], v[190:193], v[52:55]
	v_mfma_f32_16x16x32_bf16 v[48:51], v[182:185], v[190:193], v[48:51]
	v_mfma_f32_16x16x32_bf16 v[36:39], v[144:147], v[214:217], v[36:39]
	v_mfma_f32_16x16x32_bf16 v[32:35], v[182:185], v[214:217], v[32:35]
	v_mfma_f32_16x16x32_bf16 v[20:23], v[144:147], v[224:227], v[20:23]
	v_mfma_f32_16x16x32_bf16 v[16:19], v[182:185], v[224:227], v[16:19]
	v_mfma_f32_16x16x32_bf16 v[4:7], v[144:147], v[232:235], v[4:7]
	v_mfma_f32_16x16x32_bf16 v[0:3], v[182:185], v[232:235], v[0:3]
	v_mfma_f32_16x16x32_bf16 v[52:55], v[148:151], v[194:197], v[52:55]
	v_mfma_f32_16x16x32_bf16 v[48:51], v[186:189], v[194:197], v[48:51]
	v_mfma_f32_16x16x32_bf16 v[36:39], v[148:151], v[218:221], v[36:39]
	v_mfma_f32_16x16x32_bf16 v[32:35], v[186:189], v[218:221], v[32:35]
	v_mfma_f32_16x16x32_bf16 v[20:23], v[148:151], v[228:231], v[20:23]
	v_mfma_f32_16x16x32_bf16 v[16:19], v[186:189], v[228:231], v[16:19]
	v_mfma_f32_16x16x32_bf16 v[4:7], v[148:151], v[236:239], v[4:7]
	s_barrier
	v_mfma_f32_16x16x32_bf16 v[0:3], v[186:189], v[236:239], v[0:3]
	s_setprio 0
	s_add_i32 s87, 0, 0x18000
	s_add_i32 s92, 0, 0x1c000
	v_add_u32_e32 v140, s87, v210
	v_add_u32_e32 v186, s92, v210
	ds_read_b128 v[128:131], v140
	ds_read_b128 v[132:135], v140 offset:1024
	ds_read_b128 v[136:139], v140 offset:2048
	ds_read_b128 v[140:143], v140 offset:3072
	ds_read_b128 v[144:147], v186
	ds_read_b128 v[148:151], v186 offset:1024
	ds_read_b128 v[182:185], v186 offset:2048
	ds_read_b128 v[186:189], v186 offset:3072
	s_add_u32 s60, s66, 0xb0000
	s_addc_u32 s61, s67, 0
	s_mov_b32 m0, s75
	v_lshl_add_u64 v[246:247], s[60:61], 0, v[176:177]
	ds_read_b128 v[190:193], v212 offset:32768
	ds_read_b128 v[194:197], v212 offset:33792
	ds_read_b128 v[214:217], v212 offset:34816
	ds_read_b128 v[218:221], v212 offset:35840
	ds_read_b128 v[224:227], v212 offset:36864
	ds_read_b128 v[228:231], v212 offset:37888
	ds_read_b128 v[232:235], v212 offset:38912
	ds_read_b128 v[236:239], v212 offset:39936
	global_load_lds_dwordx4 v[246:247], off
	v_lshl_add_u64 v[246:247], s[60:61], 0, v[174:175]
	s_mov_b32 m0, s76
	s_nop 0
	global_load_lds_dwordx4 v[246:247], off
	s_waitcnt vmcnt(8)
	s_waitcnt lgkmcnt(0)
	s_barrier
	s_setprio 1
	s_waitcnt lgkmcnt(0)
	v_mfma_f32_16x16x32_bf16 v[124:127], v[128:131], v[190:193], v[124:127]
	v_mfma_f32_16x16x32_bf16 v[120:123], v[136:139], v[190:193], v[120:123]
	v_mfma_f32_16x16x32_bf16 v[108:111], v[128:131], v[214:217], v[108:111]
	v_mfma_f32_16x16x32_bf16 v[104:107], v[136:139], v[214:217], v[104:107]
	v_mfma_f32_16x16x32_bf16 v[92:95], v[128:131], v[224:227], v[92:95]
	v_mfma_f32_16x16x32_bf16 v[88:91], v[136:139], v[224:227], v[88:91]
	v_mfma_f32_16x16x32_bf16 v[76:79], v[128:131], v[232:235], v[76:79]
	v_mfma_f32_16x16x32_bf16 v[72:75], v[136:139], v[232:235], v[72:75]
	v_mfma_f32_16x16x32_bf16 v[124:127], v[132:135], v[194:197], v[124:127]
	v_mfma_f32_16x16x32_bf16 v[120:123], v[140:143], v[194:197], v[120:123]
	v_mfma_f32_16x16x32_bf16 v[108:111], v[132:135], v[218:221], v[108:111]
	v_mfma_f32_16x16x32_bf16 v[104:107], v[140:143], v[218:221], v[104:107]
	v_mfma_f32_16x16x32_bf16 v[92:95], v[132:135], v[228:231], v[92:95]
	v_mfma_f32_16x16x32_bf16 v[88:91], v[140:143], v[228:231], v[88:91]
	v_mfma_f32_16x16x32_bf16 v[76:79], v[132:135], v[236:239], v[76:79]
	v_mfma_f32_16x16x32_bf16 v[72:75], v[140:143], v[236:239], v[72:75]
	s_setprio 0
	s_setprio 1
	v_mfma_f32_16x16x32_bf16 v[116:119], v[144:147], v[190:193], v[116:119]
	v_mfma_f32_16x16x32_bf16 v[112:115], v[182:185], v[190:193], v[112:115]
	v_mfma_f32_16x16x32_bf16 v[100:103], v[144:147], v[214:217], v[100:103]
	v_mfma_f32_16x16x32_bf16 v[96:99], v[182:185], v[214:217], v[96:99]
	v_mfma_f32_16x16x32_bf16 v[84:87], v[144:147], v[224:227], v[84:87]
	v_mfma_f32_16x16x32_bf16 v[80:83], v[182:185], v[224:227], v[80:83]
	v_mfma_f32_16x16x32_bf16 v[68:71], v[144:147], v[232:235], v[68:71]
	v_mfma_f32_16x16x32_bf16 v[64:67], v[182:185], v[232:235], v[64:67]
	v_mfma_f32_16x16x32_bf16 v[116:119], v[148:151], v[194:197], v[116:119]
	v_mfma_f32_16x16x32_bf16 v[112:115], v[186:189], v[194:197], v[112:115]
	v_mfma_f32_16x16x32_bf16 v[100:103], v[148:151], v[218:221], v[100:103]
	v_mfma_f32_16x16x32_bf16 v[96:99], v[186:189], v[218:221], v[96:99]
	v_mfma_f32_16x16x32_bf16 v[84:87], v[148:151], v[228:231], v[84:87]
	v_mfma_f32_16x16x32_bf16 v[80:83], v[186:189], v[228:231], v[80:83]
	v_mfma_f32_16x16x32_bf16 v[68:71], v[148:151], v[236:239], v[68:71]
	s_barrier
	v_mfma_f32_16x16x32_bf16 v[64:67], v[186:189], v[236:239], v[64:67]
	s_setprio 0
	s_add_i32 s60, s87, s68
	v_lshl_add_u64 v[198:199], v[198:199], 0, s[22:23]
	s_mov_b32 m0, s60
	ds_read_b128 v[190:193], v212 offset:49152
	ds_read_b128 v[194:197], v212 offset:50176
	ds_read_b128 v[214:217], v212 offset:51200
	ds_read_b128 v[218:221], v212 offset:52224
	ds_read_b128 v[224:227], v212 offset:53248
	ds_read_b128 v[228:231], v212 offset:54272
	ds_read_b128 v[232:235], v212 offset:55296
	ds_read_b128 v[236:239], v212 offset:56320
	global_load_lds_dwordx4 v[198:199], off
	s_add_i32 m0, s60, 0x2000
	s_add_u32 s18, s18, 0xb0080
	v_lshl_add_u64 v[198:199], v[240:241], 0, s[22:23]
	s_addc_u32 s19, s19, 0
	s_add_i32 s60, s92, s68
	global_load_lds_dwordx4 v[198:199], off
	v_lshl_add_u64 v[198:199], s[18:19], 0, v[152:153]
	s_mov_b32 m0, s60
	s_nop 0
	global_load_lds_dwordx4 v[198:199], off
	v_lshl_add_u64 v[198:199], s[18:19], 0, v[172:173]
	s_add_i32 m0, s60, 0x2000
	s_nop 0
	global_load_lds_dwordx4 v[198:199], off
	v_lshl_add_u64 v[198:199], v[242:243], 0, s[22:23]
	s_mov_b32 m0, s79
	s_nop 0
	global_load_lds_dwordx4 v[198:199], off
	v_lshl_add_u64 v[198:199], v[244:245], 0, s[22:23]
	s_mov_b32 m0, s80
	s_nop 0
	global_load_lds_dwordx4 v[198:199], off
	s_waitcnt vmcnt(8)
	s_waitcnt lgkmcnt(0)
	s_barrier
	s_setprio 1
	s_waitcnt lgkmcnt(0)
	v_mfma_f32_16x16x32_bf16 v[60:63], v[128:131], v[190:193], v[60:63]
	v_mfma_f32_16x16x32_bf16 v[56:59], v[136:139], v[190:193], v[56:59]
	v_mfma_f32_16x16x32_bf16 v[44:47], v[128:131], v[214:217], v[44:47]
	v_mfma_f32_16x16x32_bf16 v[40:43], v[136:139], v[214:217], v[40:43]
	v_mfma_f32_16x16x32_bf16 v[28:31], v[128:131], v[224:227], v[28:31]
	v_mfma_f32_16x16x32_bf16 v[24:27], v[136:139], v[224:227], v[24:27]
	v_mfma_f32_16x16x32_bf16 v[12:15], v[128:131], v[232:235], v[12:15]
	v_mfma_f32_16x16x32_bf16 v[8:11], v[136:139], v[232:235], v[8:11]
	v_mfma_f32_16x16x32_bf16 v[60:63], v[132:135], v[194:197], v[60:63]
	v_mfma_f32_16x16x32_bf16 v[56:59], v[140:143], v[194:197], v[56:59]
	v_mfma_f32_16x16x32_bf16 v[44:47], v[132:135], v[218:221], v[44:47]
	v_mfma_f32_16x16x32_bf16 v[40:43], v[140:143], v[218:221], v[40:43]
	v_mfma_f32_16x16x32_bf16 v[28:31], v[132:135], v[228:231], v[28:31]
	v_mfma_f32_16x16x32_bf16 v[24:27], v[140:143], v[228:231], v[24:27]
	v_mfma_f32_16x16x32_bf16 v[12:15], v[132:135], v[236:239], v[12:15]
	v_mfma_f32_16x16x32_bf16 v[8:11], v[140:143], v[236:239], v[8:11]
	s_setprio 0
	s_setprio 1
	v_mfma_f32_16x16x32_bf16 v[52:55], v[144:147], v[190:193], v[52:55]
	v_mfma_f32_16x16x32_bf16 v[48:51], v[182:185], v[190:193], v[48:51]
	v_mfma_f32_16x16x32_bf16 v[36:39], v[144:147], v[214:217], v[36:39]
	v_mfma_f32_16x16x32_bf16 v[32:35], v[182:185], v[214:217], v[32:35]
	v_mfma_f32_16x16x32_bf16 v[20:23], v[144:147], v[224:227], v[20:23]
	v_mfma_f32_16x16x32_bf16 v[16:19], v[182:185], v[224:227], v[16:19]
	v_mfma_f32_16x16x32_bf16 v[4:7], v[144:147], v[232:235], v[4:7]
	v_mfma_f32_16x16x32_bf16 v[0:3], v[182:185], v[232:235], v[0:3]
	v_mfma_f32_16x16x32_bf16 v[52:55], v[148:151], v[194:197], v[52:55]
	v_mfma_f32_16x16x32_bf16 v[48:51], v[186:189], v[194:197], v[48:51]
	v_mfma_f32_16x16x32_bf16 v[36:39], v[148:151], v[218:221], v[36:39]
	v_mfma_f32_16x16x32_bf16 v[32:35], v[186:189], v[218:221], v[32:35]
	v_mfma_f32_16x16x32_bf16 v[20:23], v[148:151], v[228:231], v[20:23]
	v_mfma_f32_16x16x32_bf16 v[16:19], v[186:189], v[228:231], v[16:19]
	v_mfma_f32_16x16x32_bf16 v[4:7], v[148:151], v[236:239], v[4:7]
	s_barrier
	v_mfma_f32_16x16x32_bf16 v[0:3], v[186:189], v[236:239], v[0:3]
	s_setprio 0
	s_add_i32 s86, s86, 2
	s_add_u32 s84, s84, 0x100
	s_addc_u32 s85, s85, 0
	s_cmp_gt_u32 s86, 41
	s_mov_b64 s[60:61], vcc
	s_cbranch_scc0 .LBB0_281
	s_and_b64 vcc, exec, s[10:11]
	s_cbranch_vccz .LBB0_284
	s_barrier

.LBB0_418:
	s_ashr_i32 s21, s20, 31
	s_lshl_b64 s[50:51], s[20:21], 19
	s_add_u32 s50, s26, s50
	s_addc_u32 s51, s27, s51
	s_and_b64 s[60:61], s[46:47], exec
	s_cselect_b32 s21, s51, s45
	s_cselect_b32 s78, s50, s44
	s_ashr_i32 s19, s18, 31
	s_lshl_b64 s[60:61], s[18:19], 19
	v_readlane_b32 s19, v254, 42
	s_add_u32 s60, s19, s60
	v_readlane_b32 s19, v254, 43
	s_addc_u32 s61, s19, s61
	s_and_b64 s[62:63], s[46:47], exec
	s_cselect_b32 s19, s61, s49
	s_cselect_b32 s79, s60, s48
	s_add_u32 s80, s48, 0x100
	s_addc_u32 s81, s49, 0
	s_add_u32 s48, s44, 0x40080
	s_addc_u32 s49, s45, 0
	s_mov_b32 s82, -2
	s_add_u32 s44, s48, 0xfffc0080
	s_addc_u32 s45, s49, -1
	s_add_i32 s83, 0, 0x10000
	s_cmp_eq_u32 s82, 12
	s_cselect_b32 s63, s21, s45
	s_cselect_b32 s62, s78, s44
	s_cselect_b32 s45, s19, s81
	s_cselect_b32 s44, s79, s80
	s_add_i32 s86, 0, 0x14000
	v_add_u32_e32 v88, s83, v185
	v_add_u32_e32 v182, s86, v185
	ds_read_b128 v[72:75], v88
	ds_read_b128 v[76:79], v88 offset:1024
	ds_read_b128 v[80:83], v88 offset:2048
	ds_read_b128 v[88:91], v88 offset:3072
	ds_read_b128 v[174:177], v182
	ds_read_b128 v[178:181], v182 offset:1024
	ds_read_b128 v[190:193], v182 offset:2048
	ds_read_b128 v[194:197], v182 offset:3072
	v_lshl_add_u64 v[182:183], s[48:49], 0, v[172:173]
	s_add_i32 m0, s59, 0xc000
	ds_read_b128 v[210:213], v188
	ds_read_b128 v[214:217], v188 offset:1024
	ds_read_b128 v[218:221], v188 offset:2048
	ds_read_b128 v[224:227], v188 offset:3072
	ds_read_b128 v[228:231], v188 offset:4096
	ds_read_b128 v[232:235], v188 offset:5120
	ds_read_b128 v[236:239], v188 offset:6144
	ds_read_b128 v[240:243], v188 offset:7168
	global_load_lds_dwordx4 v[182:183], off
	v_lshl_add_u64 v[182:183], s[48:49], 0, v[150:151]
	s_add_i32 m0, s59, 0xe000
	s_nop 0
	global_load_lds_dwordx4 v[182:183], off
	s_waitcnt vmcnt(8)
	s_waitcnt lgkmcnt(0)
	s_barrier
	s_setprio 1
	s_waitcnt lgkmcnt(0)
	v_mfma_f32_16x16x32_bf16 v[140:143], v[72:75], v[210:213], 0
	v_mfma_f32_16x16x32_bf16 v[136:139], v[80:83], v[210:213], 0
	v_mfma_f32_16x16x32_bf16 v[124:127], v[72:75], v[218:221], 0
	v_mfma_f32_16x16x32_bf16 v[120:123], v[80:83], v[218:221], 0
	v_mfma_f32_16x16x32_bf16 v[108:111], v[72:75], v[228:231], 0
	v_mfma_f32_16x16x32_bf16 v[104:107], v[80:83], v[228:231], 0
	v_mfma_f32_16x16x32_bf16 v[92:95], v[72:75], v[236:239], 0
	v_mfma_f32_16x16x32_bf16 v[84:87], v[80:83], v[236:239], 0
	v_mfma_f32_16x16x32_bf16 v[140:143], v[76:79], v[214:217], v[140:143]
	v_mfma_f32_16x16x32_bf16 v[136:139], v[88:91], v[214:217], v[136:139]
	v_mfma_f32_16x16x32_bf16 v[124:127], v[76:79], v[224:227], v[124:127]
	v_mfma_f32_16x16x32_bf16 v[120:123], v[88:91], v[224:227], v[120:123]
	v_mfma_f32_16x16x32_bf16 v[108:111], v[76:79], v[232:235], v[108:111]
	v_mfma_f32_16x16x32_bf16 v[104:107], v[88:91], v[232:235], v[104:107]
	v_mfma_f32_16x16x32_bf16 v[92:95], v[76:79], v[240:243], v[92:95]
	v_mfma_f32_16x16x32_bf16 v[84:87], v[88:91], v[240:243], v[84:87]
	s_setprio 0
	s_setprio 1
	v_mfma_f32_16x16x32_bf16 v[132:135], v[174:177], v[210:213], 0
	v_mfma_f32_16x16x32_bf16 v[128:131], v[190:193], v[210:213], 0
	v_mfma_f32_16x16x32_bf16 v[116:119], v[174:177], v[218:221], 0
	v_mfma_f32_16x16x32_bf16 v[112:115], v[190:193], v[218:221], 0
	v_mfma_f32_16x16x32_bf16 v[100:103], v[174:177], v[228:231], 0
	v_mfma_f32_16x16x32_bf16 v[96:99], v[190:193], v[228:231], 0
	v_mfma_f32_16x16x32_bf16 v[68:71], v[174:177], v[236:239], 0
	v_mfma_f32_16x16x32_bf16 v[64:67], v[190:193], v[236:239], 0
	v_mfma_f32_16x16x32_bf16 v[132:135], v[178:181], v[214:217], v[132:135]
	v_mfma_f32_16x16x32_bf16 v[128:131], v[194:197], v[214:217], v[128:131]
	v_mfma_f32_16x16x32_bf16 v[116:119], v[178:181], v[224:227], v[116:119]
	v_mfma_f32_16x16x32_bf16 v[112:115], v[194:197], v[224:227], v[112:115]
	v_mfma_f32_16x16x32_bf16 v[100:103], v[178:181], v[232:235], v[100:103]
	v_mfma_f32_16x16x32_bf16 v[96:99], v[194:197], v[232:235], v[96:99]
	v_mfma_f32_16x16x32_bf16 v[68:71], v[178:181], v[240:243], v[68:71]
	s_barrier
	v_mfma_f32_16x16x32_bf16 v[64:67], v[194:197], v[240:243], v[64:67]
	s_setprio 0
	s_add_i32 s83, s83, s8
	v_lshl_add_u64 v[182:183], s[44:45], 0, v[152:153]
	s_mov_b32 m0, s83
	ds_read_b128 v[210:213], v188 offset:16384
	ds_read_b128 v[214:217], v188 offset:17408
	ds_read_b128 v[218:221], v188 offset:18432
	ds_read_b128 v[224:227], v188 offset:19456
	ds_read_b128 v[228:231], v188 offset:20480
	ds_read_b128 v[232:235], v188 offset:21504
	ds_read_b128 v[236:239], v188 offset:22528
	ds_read_b128 v[240:243], v188 offset:23552
	global_load_lds_dwordx4 v[182:183], off
	s_add_i32 m0, s83, 0x2000
	s_add_u32 s84, s44, 0x40000
	v_lshl_add_u64 v[198:199], s[44:45], 0, v[144:145]
	s_addc_u32 s85, s45, 0
	s_add_i32 s83, s86, s8
	global_load_lds_dwordx4 v[198:199], off
	v_lshl_add_u64 v[244:245], s[84:85], 0, v[152:153]
	s_mov_b32 m0, s83
	v_lshl_add_u64 v[246:247], s[62:63], 0, v[146:147]
	global_load_lds_dwordx4 v[244:245], off
	v_lshl_add_u64 v[244:245], s[84:85], 0, v[144:145]
	s_add_i32 m0, s83, 0x2000
	s_nop 0
	global_load_lds_dwordx4 v[244:245], off
	v_lshl_add_u64 v[244:245], s[62:63], 0, v[148:149]
	s_mov_b32 m0, s59
	s_nop 0
	global_load_lds_dwordx4 v[244:245], off
	s_mov_b32 m0, s66
	s_nop 0
	global_load_lds_dwordx4 v[246:247], off
	s_waitcnt vmcnt(8)
	s_waitcnt lgkmcnt(0)
	s_barrier
	s_setprio 1
	s_waitcnt lgkmcnt(0)
	v_mfma_f32_16x16x32_bf16 v[60:63], v[72:75], v[210:213], 0
	v_mfma_f32_16x16x32_bf16 v[56:59], v[80:83], v[210:213], 0
	v_mfma_f32_16x16x32_bf16 v[44:47], v[72:75], v[218:221], 0
	v_mfma_f32_16x16x32_bf16 v[40:43], v[80:83], v[218:221], 0
	v_mfma_f32_16x16x32_bf16 v[28:31], v[72:75], v[228:231], 0
	v_mfma_f32_16x16x32_bf16 v[24:27], v[80:83], v[228:231], 0
	v_mfma_f32_16x16x32_bf16 v[12:15], v[72:75], v[236:239], 0
	v_mfma_f32_16x16x32_bf16 v[8:11], v[80:83], v[236:239], 0
	v_mfma_f32_16x16x32_bf16 v[60:63], v[76:79], v[214:217], v[60:63]
	v_mfma_f32_16x16x32_bf16 v[56:59], v[88:91], v[214:217], v[56:59]
	v_mfma_f32_16x16x32_bf16 v[44:47], v[76:79], v[224:227], v[44:47]
	v_mfma_f32_16x16x32_bf16 v[40:43], v[88:91], v[224:227], v[40:43]
	v_mfma_f32_16x16x32_bf16 v[28:31], v[76:79], v[232:235], v[28:31]
	v_mfma_f32_16x16x32_bf16 v[24:27], v[88:91], v[232:235], v[24:27]
	v_mfma_f32_16x16x32_bf16 v[12:15], v[76:79], v[240:243], v[12:15]
	v_mfma_f32_16x16x32_bf16 v[8:11], v[88:91], v[240:243], v[8:11]
	s_setprio 0
	s_setprio 1
	v_mfma_f32_16x16x32_bf16 v[52:55], v[174:177], v[210:213], 0
	v_mfma_f32_16x16x32_bf16 v[48:51], v[190:193], v[210:213], 0
	v_mfma_f32_16x16x32_bf16 v[36:39], v[174:177], v[218:221], 0
	v_mfma_f32_16x16x32_bf16 v[32:35], v[190:193], v[218:221], 0
	v_mfma_f32_16x16x32_bf16 v[20:23], v[174:177], v[228:231], 0
	v_mfma_f32_16x16x32_bf16 v[16:19], v[190:193], v[228:231], 0
	v_mfma_f32_16x16x32_bf16 v[4:7], v[174:177], v[236:239], 0
	v_mfma_f32_16x16x32_bf16 v[0:3], v[190:193], v[236:239], 0
	v_mfma_f32_16x16x32_bf16 v[52:55], v[178:181], v[214:217], v[52:55]
	v_mfma_f32_16x16x32_bf16 v[48:51], v[194:197], v[214:217], v[48:51]
	v_mfma_f32_16x16x32_bf16 v[36:39], v[178:181], v[224:227], v[36:39]
	v_mfma_f32_16x16x32_bf16 v[32:35], v[194:197], v[224:227], v[32:35]
	v_mfma_f32_16x16x32_bf16 v[20:23], v[178:181], v[232:235], v[20:23]
	v_mfma_f32_16x16x32_bf16 v[16:19], v[194:197], v[232:235], v[16:19]
	v_mfma_f32_16x16x32_bf16 v[4:7], v[178:181], v[240:243], v[4:7]
	s_barrier
	v_mfma_f32_16x16x32_bf16 v[0:3], v[194:197], v[240:243], v[0:3]
	s_setprio 0
	s_add_i32 s83, 0, 0x18000
	s_add_i32 s84, 0, 0x1c000
	v_add_u32_e32 v88, s83, v185
	v_add_u32_e32 v189, s84, v185
	ds_read_b128 v[72:75], v88
	ds_read_b128 v[76:79], v88 offset:1024
	ds_read_b128 v[80:83], v88 offset:2048
	ds_read_b128 v[88:91], v88 offset:3072
	ds_read_b128 v[174:177], v189
	ds_read_b128 v[178:181], v189 offset:1024
	ds_read_b128 v[190:193], v189 offset:2048
	ds_read_b128 v[194:197], v189 offset:3072
	s_add_u32 s62, s62, 0x40000
	s_addc_u32 s63, s63, 0
	s_mov_b32 m0, s67
	v_lshl_add_u64 v[248:249], s[62:63], 0, v[148:149]
	ds_read_b128 v[210:213], v188 offset:32768
	ds_read_b128 v[214:217], v188 offset:33792
	ds_read_b128 v[218:221], v188 offset:34816
	ds_read_b128 v[224:227], v188 offset:35840
	ds_read_b128 v[228:231], v188 offset:36864
	ds_read_b128 v[232:235], v188 offset:37888
	ds_read_b128 v[236:239], v188 offset:38912
	ds_read_b128 v[240:243], v188 offset:39936
	global_load_lds_dwordx4 v[248:249], off
	v_lshl_add_u64 v[248:249], s[62:63], 0, v[146:147]
	s_mov_b32 m0, s68
	s_nop 0
	global_load_lds_dwordx4 v[248:249], off
	s_waitcnt vmcnt(8)
	s_waitcnt lgkmcnt(0)
	s_barrier
	s_setprio 1
	s_waitcnt lgkmcnt(0)
	v_mfma_f32_16x16x32_bf16 v[140:143], v[72:75], v[210:213], v[140:143]
	v_mfma_f32_16x16x32_bf16 v[136:139], v[80:83], v[210:213], v[136:139]
	v_mfma_f32_16x16x32_bf16 v[124:127], v[72:75], v[218:221], v[124:127]
	v_mfma_f32_16x16x32_bf16 v[120:123], v[80:83], v[218:221], v[120:123]
	v_mfma_f32_16x16x32_bf16 v[108:111], v[72:75], v[228:231], v[108:111]
	v_mfma_f32_16x16x32_bf16 v[104:107], v[80:83], v[228:231], v[104:107]
	v_mfma_f32_16x16x32_bf16 v[92:95], v[72:75], v[236:239], v[92:95]
	v_mfma_f32_16x16x32_bf16 v[84:87], v[80:83], v[236:239], v[84:87]
	v_mfma_f32_16x16x32_bf16 v[140:143], v[76:79], v[214:217], v[140:143]
	v_mfma_f32_16x16x32_bf16 v[136:139], v[88:91], v[214:217], v[136:139]
	v_mfma_f32_16x16x32_bf16 v[124:127], v[76:79], v[224:227], v[124:127]
	v_mfma_f32_16x16x32_bf16 v[120:123], v[88:91], v[224:227], v[120:123]
	v_mfma_f32_16x16x32_bf16 v[108:111], v[76:79], v[232:235], v[108:111]
	v_mfma_f32_16x16x32_bf16 v[104:107], v[88:91], v[232:235], v[104:107]
	v_mfma_f32_16x16x32_bf16 v[92:95], v[76:79], v[240:243], v[92:95]
	v_mfma_f32_16x16x32_bf16 v[84:87], v[88:91], v[240:243], v[84:87]
	s_setprio 0
	s_setprio 1
	v_mfma_f32_16x16x32_bf16 v[132:135], v[174:177], v[210:213], v[132:135]
	v_mfma_f32_16x16x32_bf16 v[128:131], v[190:193], v[210:213], v[128:131]
	v_mfma_f32_16x16x32_bf16 v[116:119], v[174:177], v[218:221], v[116:119]
	v_mfma_f32_16x16x32_bf16 v[112:115], v[190:193], v[218:221], v[112:115]
	v_mfma_f32_16x16x32_bf16 v[100:103], v[174:177], v[228:231], v[100:103]
	v_mfma_f32_16x16x32_bf16 v[96:99], v[190:193], v[228:231], v[96:99]
	v_mfma_f32_16x16x32_bf16 v[68:71], v[174:177], v[236:239], v[68:71]
	v_mfma_f32_16x16x32_bf16 v[64:67], v[190:193], v[236:239], v[64:67]
	v_mfma_f32_16x16x32_bf16 v[132:135], v[178:181], v[214:217], v[132:135]
	v_mfma_f32_16x16x32_bf16 v[128:131], v[194:197], v[214:217], v[128:131]
	v_mfma_f32_16x16x32_bf16 v[116:119], v[178:181], v[224:227], v[116:119]
	v_mfma_f32_16x16x32_bf16 v[112:115], v[194:197], v[224:227], v[112:115]
	v_mfma_f32_16x16x32_bf16 v[100:103], v[178:181], v[232:235], v[100:103]
	v_mfma_f32_16x16x32_bf16 v[96:99], v[194:197], v[232:235], v[96:99]
	v_mfma_f32_16x16x32_bf16 v[68:71], v[178:181], v[240:243], v[68:71]
	s_barrier
	v_mfma_f32_16x16x32_bf16 v[64:67], v[194:197], v[240:243], v[64:67]
	s_setprio 0
	s_add_i32 s62, s83, s8
	v_lshl_add_u64 v[182:183], v[182:183], 0, s[22:23]
	s_mov_b32 m0, s62
	ds_read_b128 v[210:213], v188 offset:49152
	ds_read_b128 v[214:217], v188 offset:50176
	ds_read_b128 v[218:221], v188 offset:51200
	ds_read_b128 v[224:227], v188 offset:52224
	ds_read_b128 v[228:231], v188 offset:53248
	ds_read_b128 v[232:235], v188 offset:54272
	ds_read_b128 v[236:239], v188 offset:55296
	ds_read_b128 v[240:243], v188 offset:56320
	global_load_lds_dwordx4 v[182:183], off
	s_add_i32 m0, s62, 0x2000
	s_add_u32 s44, s44, 0x40080
	v_lshl_add_u64 v[182:183], v[198:199], 0, s[22:23]
	s_addc_u32 s45, s45, 0
	s_add_i32 s62, s84, s8
	global_load_lds_dwordx4 v[182:183], off
	v_lshl_add_u64 v[182:183], s[44:45], 0, v[152:153]
	s_mov_b32 m0, s62
	s_nop 0
	global_load_lds_dwordx4 v[182:183], off
	v_lshl_add_u64 v[182:183], s[44:45], 0, v[144:145]
	s_add_i32 m0, s62, 0x2000
	s_nop 0
	global_load_lds_dwordx4 v[182:183], off
	v_lshl_add_u64 v[182:183], v[244:245], 0, s[22:23]
	s_mov_b32 m0, s69
	s_nop 0
	global_load_lds_dwordx4 v[182:183], off
	v_lshl_add_u64 v[182:183], v[246:247], 0, s[22:23]
	s_mov_b32 m0, s74
	s_nop 0
	global_load_lds_dwordx4 v[182:183], off
	s_waitcnt vmcnt(8)
	s_waitcnt lgkmcnt(0)
	s_barrier
	s_setprio 1
	s_waitcnt lgkmcnt(0)
	v_mfma_f32_16x16x32_bf16 v[60:63], v[72:75], v[210:213], v[60:63]
	v_mfma_f32_16x16x32_bf16 v[56:59], v[80:83], v[210:213], v[56:59]
	v_mfma_f32_16x16x32_bf16 v[44:47], v[72:75], v[218:221], v[44:47]
	v_mfma_f32_16x16x32_bf16 v[40:43], v[80:83], v[218:221], v[40:43]
	v_mfma_f32_16x16x32_bf16 v[28:31], v[72:75], v[228:231], v[28:31]
	v_mfma_f32_16x16x32_bf16 v[24:27], v[80:83], v[228:231], v[24:27]
	v_mfma_f32_16x16x32_bf16 v[12:15], v[72:75], v[236:239], v[12:15]
	v_mfma_f32_16x16x32_bf16 v[8:11], v[80:83], v[236:239], v[8:11]
	v_mfma_f32_16x16x32_bf16 v[60:63], v[76:79], v[214:217], v[60:63]
	v_mfma_f32_16x16x32_bf16 v[56:59], v[88:91], v[214:217], v[56:59]
	v_mfma_f32_16x16x32_bf16 v[44:47], v[76:79], v[224:227], v[44:47]
	v_mfma_f32_16x16x32_bf16 v[40:43], v[88:91], v[224:227], v[40:43]
	v_mfma_f32_16x16x32_bf16 v[28:31], v[76:79], v[232:235], v[28:31]
	v_mfma_f32_16x16x32_bf16 v[24:27], v[88:91], v[232:235], v[24:27]
	v_mfma_f32_16x16x32_bf16 v[12:15], v[76:79], v[240:243], v[12:15]
	v_mfma_f32_16x16x32_bf16 v[8:11], v[88:91], v[240:243], v[8:11]
	s_setprio 0
	s_setprio 1
	v_mfma_f32_16x16x32_bf16 v[52:55], v[174:177], v[210:213], v[52:55]
	v_mfma_f32_16x16x32_bf16 v[48:51], v[190:193], v[210:213], v[48:51]
	v_mfma_f32_16x16x32_bf16 v[36:39], v[174:177], v[218:221], v[36:39]
	v_mfma_f32_16x16x32_bf16 v[32:35], v[190:193], v[218:221], v[32:35]
	v_mfma_f32_16x16x32_bf16 v[20:23], v[174:177], v[228:231], v[20:23]
	v_mfma_f32_16x16x32_bf16 v[16:19], v[190:193], v[228:231], v[16:19]
	v_mfma_f32_16x16x32_bf16 v[4:7], v[174:177], v[236:239], v[4:7]
	v_mfma_f32_16x16x32_bf16 v[0:3], v[190:193], v[236:239], v[0:3]
	v_mfma_f32_16x16x32_bf16 v[52:55], v[178:181], v[214:217], v[52:55]
	v_mfma_f32_16x16x32_bf16 v[48:51], v[194:197], v[214:217], v[48:51]
	v_mfma_f32_16x16x32_bf16 v[36:39], v[178:181], v[224:227], v[36:39]
	v_mfma_f32_16x16x32_bf16 v[32:35], v[194:197], v[224:227], v[32:35]
	v_mfma_f32_16x16x32_bf16 v[20:23], v[178:181], v[232:235], v[20:23]
	v_mfma_f32_16x16x32_bf16 v[16:19], v[194:197], v[232:235], v[16:19]
	v_mfma_f32_16x16x32_bf16 v[4:7], v[178:181], v[240:243], v[4:7]
	s_barrier
	v_mfma_f32_16x16x32_bf16 v[0:3], v[194:197], v[240:243], v[0:3]
	s_setprio 0
	s_add_i32 s82, s82, 2
	s_add_u32 s80, s80, 0x100
	s_addc_u32 s81, s81, 0
	s_add_u32 s48, s48, 0x100
	s_addc_u32 s49, s49, 0
	s_cmp_gt_u32 s82, 13
.LBB0_419:
	s_add_u32 s44, s48, 0xfffc0080
	s_addc_u32 s45, s49, -1
	s_add_i32 s83, 0, 0x10000
	s_cmp_eq_u32 s82, 12
	s_cselect_b32 s63, s21, s45
	s_cselect_b32 s62, s78, s44
	s_cselect_b32 s45, s19, s81
	s_cselect_b32 s44, s79, s80
	s_add_i32 s86, 0, 0x14000
	v_add_u32_e32 v88, s83, v185
	v_add_u32_e32 v182, s86, v185
	ds_read_b128 v[72:75], v88
	ds_read_b128 v[76:79], v88 offset:1024
	ds_read_b128 v[80:83], v88 offset:2048
	ds_read_b128 v[88:91], v88 offset:3072
	ds_read_b128 v[174:177], v182
	ds_read_b128 v[178:181], v182 offset:1024
	ds_read_b128 v[190:193], v182 offset:2048
	ds_read_b128 v[194:197], v182 offset:3072
	v_lshl_add_u64 v[182:183], s[48:49], 0, v[172:173]
	s_add_i32 m0, s59, 0xc000
	ds_read_b128 v[210:213], v188
	ds_read_b128 v[214:217], v188 offset:1024
	ds_read_b128 v[218:221], v188 offset:2048
	ds_read_b128 v[224:227], v188 offset:3072
	ds_read_b128 v[228:231], v188 offset:4096
	ds_read_b128 v[232:235], v188 offset:5120
	ds_read_b128 v[236:239], v188 offset:6144
	ds_read_b128 v[240:243], v188 offset:7168
	global_load_lds_dwordx4 v[182:183], off
	v_lshl_add_u64 v[182:183], s[48:49], 0, v[150:151]
	s_add_i32 m0, s59, 0xe000
	s_nop 0
	global_load_lds_dwordx4 v[182:183], off
	s_waitcnt vmcnt(8)
	s_waitcnt lgkmcnt(0)
	s_barrier
	s_setprio 1
	s_waitcnt lgkmcnt(0)
	v_mfma_f32_16x16x32_bf16 v[140:143], v[72:75], v[210:213], v[140:143]
	v_mfma_f32_16x16x32_bf16 v[136:139], v[80:83], v[210:213], v[136:139]
	v_mfma_f32_16x16x32_bf16 v[124:127], v[72:75], v[218:221], v[124:127]
	v_mfma_f32_16x16x32_bf16 v[120:123], v[80:83], v[218:221], v[120:123]
	v_mfma_f32_16x16x32_bf16 v[108:111], v[72:75], v[228:231], v[108:111]
	v_mfma_f32_16x16x32_bf16 v[104:107], v[80:83], v[228:231], v[104:107]
	v_mfma_f32_16x16x32_bf16 v[92:95], v[72:75], v[236:239], v[92:95]
	v_mfma_f32_16x16x32_bf16 v[84:87], v[80:83], v[236:239], v[84:87]
	v_mfma_f32_16x16x32_bf16 v[140:143], v[76:79], v[214:217], v[140:143]
	v_mfma_f32_16x16x32_bf16 v[136:139], v[88:91], v[214:217], v[136:139]
	v_mfma_f32_16x16x32_bf16 v[124:127], v[76:79], v[224:227], v[124:127]
	v_mfma_f32_16x16x32_bf16 v[120:123], v[88:91], v[224:227], v[120:123]
	v_mfma_f32_16x16x32_bf16 v[108:111], v[76:79], v[232:235], v[108:111]
	v_mfma_f32_16x16x32_bf16 v[104:107], v[88:91], v[232:235], v[104:107]
	v_mfma_f32_16x16x32_bf16 v[92:95], v[76:79], v[240:243], v[92:95]
	v_mfma_f32_16x16x32_bf16 v[84:87], v[88:91], v[240:243], v[84:87]
	s_setprio 0
	s_setprio 1
	v_mfma_f32_16x16x32_bf16 v[132:135], v[174:177], v[210:213], v[132:135]
	v_mfma_f32_16x16x32_bf16 v[128:131], v[190:193], v[210:213], v[128:131]
	v_mfma_f32_16x16x32_bf16 v[116:119], v[174:177], v[218:221], v[116:119]
	v_mfma_f32_16x16x32_bf16 v[112:115], v[190:193], v[218:221], v[112:115]
	v_mfma_f32_16x16x32_bf16 v[100:103], v[174:177], v[228:231], v[100:103]
	v_mfma_f32_16x16x32_bf16 v[96:99], v[190:193], v[228:231], v[96:99]
	v_mfma_f32_16x16x32_bf16 v[68:71], v[174:177], v[236:239], v[68:71]
	v_mfma_f32_16x16x32_bf16 v[64:67], v[190:193], v[236:239], v[64:67]
	v_mfma_f32_16x16x32_bf16 v[132:135], v[178:181], v[214:217], v[132:135]
	v_mfma_f32_16x16x32_bf16 v[128:131], v[194:197], v[214:217], v[128:131]
	v_mfma_f32_16x16x32_bf16 v[116:119], v[178:181], v[224:227], v[116:119]
	v_mfma_f32_16x16x32_bf16 v[112:115], v[194:197], v[224:227], v[112:115]
	v_mfma_f32_16x16x32_bf16 v[100:103], v[178:181], v[232:235], v[100:103]
	v_mfma_f32_16x16x32_bf16 v[96:99], v[194:197], v[232:235], v[96:99]
	v_mfma_f32_16x16x32_bf16 v[68:71], v[178:181], v[240:243], v[68:71]
	s_barrier
	v_mfma_f32_16x16x32_bf16 v[64:67], v[194:197], v[240:243], v[64:67]
	s_setprio 0
	s_add_i32 s83, s83, s8
	v_lshl_add_u64 v[182:183], s[44:45], 0, v[152:153]
	s_mov_b32 m0, s83
	ds_read_b128 v[210:213], v188 offset:16384
	ds_read_b128 v[214:217], v188 offset:17408
	ds_read_b128 v[218:221], v188 offset:18432
	ds_read_b128 v[224:227], v188 offset:19456
	ds_read_b128 v[228:231], v188 offset:20480
	ds_read_b128 v[232:235], v188 offset:21504
	ds_read_b128 v[236:239], v188 offset:22528
	ds_read_b128 v[240:243], v188 offset:23552
	global_load_lds_dwordx4 v[182:183], off
	s_add_i32 m0, s83, 0x2000
	s_add_u32 s84, s44, 0x40000
	v_lshl_add_u64 v[198:199], s[44:45], 0, v[144:145]
	s_addc_u32 s85, s45, 0
	s_add_i32 s83, s86, s8
	global_load_lds_dwordx4 v[198:199], off
	v_lshl_add_u64 v[244:245], s[84:85], 0, v[152:153]
	s_mov_b32 m0, s83
	v_lshl_add_u64 v[246:247], s[62:63], 0, v[146:147]
	global_load_lds_dwordx4 v[244:245], off
	v_lshl_add_u64 v[244:245], s[84:85], 0, v[144:145]
	s_add_i32 m0, s83, 0x2000
	s_nop 0
	global_load_lds_dwordx4 v[244:245], off
	v_lshl_add_u64 v[244:245], s[62:63], 0, v[148:149]
	s_mov_b32 m0, s59
	s_nop 0
	global_load_lds_dwordx4 v[244:245], off
	s_mov_b32 m0, s66
	s_nop 0
	global_load_lds_dwordx4 v[246:247], off
	s_waitcnt vmcnt(8)
	s_waitcnt lgkmcnt(0)
	s_barrier
	s_setprio 1
	s_waitcnt lgkmcnt(0)
	v_mfma_f32_16x16x32_bf16 v[60:63], v[72:75], v[210:213], v[60:63]
	v_mfma_f32_16x16x32_bf16 v[56:59], v[80:83], v[210:213], v[56:59]
	v_mfma_f32_16x16x32_bf16 v[44:47], v[72:75], v[218:221], v[44:47]
	v_mfma_f32_16x16x32_bf16 v[40:43], v[80:83], v[218:221], v[40:43]
	v_mfma_f32_16x16x32_bf16 v[28:31], v[72:75], v[228:231], v[28:31]
	v_mfma_f32_16x16x32_bf16 v[24:27], v[80:83], v[228:231], v[24:27]
	v_mfma_f32_16x16x32_bf16 v[12:15], v[72:75], v[236:239], v[12:15]
	v_mfma_f32_16x16x32_bf16 v[8:11], v[80:83], v[236:239], v[8:11]
	v_mfma_f32_16x16x32_bf16 v[60:63], v[76:79], v[214:217], v[60:63]
	v_mfma_f32_16x16x32_bf16 v[56:59], v[88:91], v[214:217], v[56:59]
	v_mfma_f32_16x16x32_bf16 v[44:47], v[76:79], v[224:227], v[44:47]
	v_mfma_f32_16x16x32_bf16 v[40:43], v[88:91], v[224:227], v[40:43]
	v_mfma_f32_16x16x32_bf16 v[28:31], v[76:79], v[232:235], v[28:31]
	v_mfma_f32_16x16x32_bf16 v[24:27], v[88:91], v[232:235], v[24:27]
	v_mfma_f32_16x16x32_bf16 v[12:15], v[76:79], v[240:243], v[12:15]
	v_mfma_f32_16x16x32_bf16 v[8:11], v[88:91], v[240:243], v[8:11]
	s_setprio 0
	s_setprio 1
	v_mfma_f32_16x16x32_bf16 v[52:55], v[174:177], v[210:213], v[52:55]
	v_mfma_f32_16x16x32_bf16 v[48:51], v[190:193], v[210:213], v[48:51]
	v_mfma_f32_16x16x32_bf16 v[36:39], v[174:177], v[218:221], v[36:39]
	v_mfma_f32_16x16x32_bf16 v[32:35], v[190:193], v[218:221], v[32:35]
	v_mfma_f32_16x16x32_bf16 v[20:23], v[174:177], v[228:231], v[20:23]
	v_mfma_f32_16x16x32_bf16 v[16:19], v[190:193], v[228:231], v[16:19]
	v_mfma_f32_16x16x32_bf16 v[4:7], v[174:177], v[236:239], v[4:7]
	v_mfma_f32_16x16x32_bf16 v[0:3], v[190:193], v[236:239], v[0:3]
	v_mfma_f32_16x16x32_bf16 v[52:55], v[178:181], v[214:217], v[52:55]
	v_mfma_f32_16x16x32_bf16 v[48:51], v[194:197], v[214:217], v[48:51]
	v_mfma_f32_16x16x32_bf16 v[36:39], v[178:181], v[224:227], v[36:39]
	v_mfma_f32_16x16x32_bf16 v[32:35], v[194:197], v[224:227], v[32:35]
	v_mfma_f32_16x16x32_bf16 v[20:23], v[178:181], v[232:235], v[20:23]
	v_mfma_f32_16x16x32_bf16 v[16:19], v[194:197], v[232:235], v[16:19]
	v_mfma_f32_16x16x32_bf16 v[4:7], v[178:181], v[240:243], v[4:7]
	s_barrier
	v_mfma_f32_16x16x32_bf16 v[0:3], v[194:197], v[240:243], v[0:3]
	s_setprio 0
	s_add_i32 s83, 0, 0x18000
	s_add_i32 s84, 0, 0x1c000
	v_add_u32_e32 v88, s83, v185
	v_add_u32_e32 v189, s84, v185
	ds_read_b128 v[72:75], v88
	ds_read_b128 v[76:79], v88 offset:1024
	ds_read_b128 v[80:83], v88 offset:2048
	ds_read_b128 v[88:91], v88 offset:3072
	ds_read_b128 v[174:177], v189
	ds_read_b128 v[178:181], v189 offset:1024
	ds_read_b128 v[190:193], v189 offset:2048
	ds_read_b128 v[194:197], v189 offset:3072
	s_add_u32 s62, s62, 0x40000
	s_addc_u32 s63, s63, 0
	s_mov_b32 m0, s67
	v_lshl_add_u64 v[248:249], s[62:63], 0, v[148:149]
	ds_read_b128 v[210:213], v188 offset:32768
	ds_read_b128 v[214:217], v188 offset:33792
	ds_read_b128 v[218:221], v188 offset:34816
	ds_read_b128 v[224:227], v188 offset:35840
	ds_read_b128 v[228:231], v188 offset:36864
	ds_read_b128 v[232:235], v188 offset:37888
	ds_read_b128 v[236:239], v188 offset:38912
	ds_read_b128 v[240:243], v188 offset:39936
	global_load_lds_dwordx4 v[248:249], off
	v_lshl_add_u64 v[248:249], s[62:63], 0, v[146:147]
	s_mov_b32 m0, s68
	s_nop 0
	global_load_lds_dwordx4 v[248:249], off
	s_waitcnt vmcnt(8)
	s_waitcnt lgkmcnt(0)
	s_barrier
	s_setprio 1
	s_waitcnt lgkmcnt(0)
	v_mfma_f32_16x16x32_bf16 v[140:143], v[72:75], v[210:213], v[140:143]
	v_mfma_f32_16x16x32_bf16 v[136:139], v[80:83], v[210:213], v[136:139]
	v_mfma_f32_16x16x32_bf16 v[124:127], v[72:75], v[218:221], v[124:127]
	v_mfma_f32_16x16x32_bf16 v[120:123], v[80:83], v[218:221], v[120:123]
	v_mfma_f32_16x16x32_bf16 v[108:111], v[72:75], v[228:231], v[108:111]
	v_mfma_f32_16x16x32_bf16 v[104:107], v[80:83], v[228:231], v[104:107]
	v_mfma_f32_16x16x32_bf16 v[92:95], v[72:75], v[236:239], v[92:95]
	v_mfma_f32_16x16x32_bf16 v[84:87], v[80:83], v[236:239], v[84:87]
	v_mfma_f32_16x16x32_bf16 v[140:143], v[76:79], v[214:217], v[140:143]
	v_mfma_f32_16x16x32_bf16 v[136:139], v[88:91], v[214:217], v[136:139]
	v_mfma_f32_16x16x32_bf16 v[124:127], v[76:79], v[224:227], v[124:127]
	v_mfma_f32_16x16x32_bf16 v[120:123], v[88:91], v[224:227], v[120:123]
	v_mfma_f32_16x16x32_bf16 v[108:111], v[76:79], v[232:235], v[108:111]
	v_mfma_f32_16x16x32_bf16 v[104:107], v[88:91], v[232:235], v[104:107]
	v_mfma_f32_16x16x32_bf16 v[92:95], v[76:79], v[240:243], v[92:95]
	v_mfma_f32_16x16x32_bf16 v[84:87], v[88:91], v[240:243], v[84:87]
	s_setprio 0
	s_setprio 1
	v_mfma_f32_16x16x32_bf16 v[132:135], v[174:177], v[210:213], v[132:135]
	v_mfma_f32_16x16x32_bf16 v[128:131], v[190:193], v[210:213], v[128:131]
	v_mfma_f32_16x16x32_bf16 v[116:119], v[174:177], v[218:221], v[116:119]
	v_mfma_f32_16x16x32_bf16 v[112:115], v[190:193], v[218:221], v[112:115]
	v_mfma_f32_16x16x32_bf16 v[100:103], v[174:177], v[228:231], v[100:103]
	v_mfma_f32_16x16x32_bf16 v[96:99], v[190:193], v[228:231], v[96:99]
	v_mfma_f32_16x16x32_bf16 v[68:71], v[174:177], v[236:239], v[68:71]
	v_mfma_f32_16x16x32_bf16 v[64:67], v[190:193], v[236:239], v[64:67]
	v_mfma_f32_16x16x32_bf16 v[132:135], v[178:181], v[214:217], v[132:135]
	v_mfma_f32_16x16x32_bf16 v[128:131], v[194:197], v[214:217], v[128:131]
	v_mfma_f32_16x16x32_bf16 v[116:119], v[178:181], v[224:227], v[116:119]
	v_mfma_f32_16x16x32_bf16 v[112:115], v[194:197], v[224:227], v[112:115]
	v_mfma_f32_16x16x32_bf16 v[100:103], v[178:181], v[232:235], v[100:103]
	v_mfma_f32_16x16x32_bf16 v[96:99], v[194:197], v[232:235], v[96:99]
	v_mfma_f32_16x16x32_bf16 v[68:71], v[178:181], v[240:243], v[68:71]
	s_barrier
	v_mfma_f32_16x16x32_bf16 v[64:67], v[194:197], v[240:243], v[64:67]
	s_setprio 0
	s_add_i32 s62, s83, s8
	v_lshl_add_u64 v[182:183], v[182:183], 0, s[22:23]
	s_mov_b32 m0, s62
	ds_read_b128 v[210:213], v188 offset:49152
	ds_read_b128 v[214:217], v188 offset:50176
	ds_read_b128 v[218:221], v188 offset:51200
	ds_read_b128 v[224:227], v188 offset:52224
	ds_read_b128 v[228:231], v188 offset:53248
	ds_read_b128 v[232:235], v188 offset:54272
	ds_read_b128 v[236:239], v188 offset:55296
	ds_read_b128 v[240:243], v188 offset:56320
	global_load_lds_dwordx4 v[182:183], off
	s_add_i32 m0, s62, 0x2000
	s_add_u32 s44, s44, 0x40080
	v_lshl_add_u64 v[182:183], v[198:199], 0, s[22:23]
	s_addc_u32 s45, s45, 0
	s_add_i32 s62, s84, s8
	global_load_lds_dwordx4 v[182:183], off
	v_lshl_add_u64 v[182:183], s[44:45], 0, v[152:153]
	s_mov_b32 m0, s62
	s_nop 0
	global_load_lds_dwordx4 v[182:183], off
	v_lshl_add_u64 v[182:183], s[44:45], 0, v[144:145]
	s_add_i32 m0, s62, 0x2000
	s_nop 0
	global_load_lds_dwordx4 v[182:183], off
	v_lshl_add_u64 v[182:183], v[244:245], 0, s[22:23]
	s_mov_b32 m0, s69
	s_nop 0
	global_load_lds_dwordx4 v[182:183], off
	v_lshl_add_u64 v[182:183], v[246:247], 0, s[22:23]
	s_mov_b32 m0, s74
	s_nop 0
	global_load_lds_dwordx4 v[182:183], off
	s_waitcnt vmcnt(8)
	s_waitcnt lgkmcnt(0)
	s_barrier
	s_setprio 1
	s_waitcnt lgkmcnt(0)
	v_mfma_f32_16x16x32_bf16 v[60:63], v[72:75], v[210:213], v[60:63]
	v_mfma_f32_16x16x32_bf16 v[56:59], v[80:83], v[210:213], v[56:59]
	v_mfma_f32_16x16x32_bf16 v[44:47], v[72:75], v[218:221], v[44:47]
	v_mfma_f32_16x16x32_bf16 v[40:43], v[80:83], v[218:221], v[40:43]
	v_mfma_f32_16x16x32_bf16 v[28:31], v[72:75], v[228:231], v[28:31]
	v_mfma_f32_16x16x32_bf16 v[24:27], v[80:83], v[228:231], v[24:27]
	v_mfma_f32_16x16x32_bf16 v[12:15], v[72:75], v[236:239], v[12:15]
	v_mfma_f32_16x16x32_bf16 v[8:11], v[80:83], v[236:239], v[8:11]
	v_mfma_f32_16x16x32_bf16 v[60:63], v[76:79], v[214:217], v[60:63]
	v_mfma_f32_16x16x32_bf16 v[56:59], v[88:91], v[214:217], v[56:59]
	v_mfma_f32_16x16x32_bf16 v[44:47], v[76:79], v[224:227], v[44:47]
	v_mfma_f32_16x16x32_bf16 v[40:43], v[88:91], v[224:227], v[40:43]
	v_mfma_f32_16x16x32_bf16 v[28:31], v[76:79], v[232:235], v[28:31]
	v_mfma_f32_16x16x32_bf16 v[24:27], v[88:91], v[232:235], v[24:27]
	v_mfma_f32_16x16x32_bf16 v[12:15], v[76:79], v[240:243], v[12:15]
	v_mfma_f32_16x16x32_bf16 v[8:11], v[88:91], v[240:243], v[8:11]
	s_setprio 0
	s_setprio 1
	v_mfma_f32_16x16x32_bf16 v[52:55], v[174:177], v[210:213], v[52:55]
	v_mfma_f32_16x16x32_bf16 v[48:51], v[190:193], v[210:213], v[48:51]
	v_mfma_f32_16x16x32_bf16 v[36:39], v[174:177], v[218:221], v[36:39]
	v_mfma_f32_16x16x32_bf16 v[32:35], v[190:193], v[218:221], v[32:35]
	v_mfma_f32_16x16x32_bf16 v[20:23], v[174:177], v[228:231], v[20:23]
	v_mfma_f32_16x16x32_bf16 v[16:19], v[190:193], v[228:231], v[16:19]
	v_mfma_f32_16x16x32_bf16 v[4:7], v[174:177], v[236:239], v[4:7]
	v_mfma_f32_16x16x32_bf16 v[0:3], v[190:193], v[236:239], v[0:3]
	v_mfma_f32_16x16x32_bf16 v[52:55], v[178:181], v[214:217], v[52:55]
	v_mfma_f32_16x16x32_bf16 v[48:51], v[194:197], v[214:217], v[48:51]
	v_mfma_f32_16x16x32_bf16 v[36:39], v[178:181], v[224:227], v[36:39]
	v_mfma_f32_16x16x32_bf16 v[32:35], v[194:197], v[224:227], v[32:35]
	v_mfma_f32_16x16x32_bf16 v[20:23], v[178:181], v[232:235], v[20:23]
	v_mfma_f32_16x16x32_bf16 v[16:19], v[194:197], v[232:235], v[16:19]
	v_mfma_f32_16x16x32_bf16 v[4:7], v[178:181], v[240:243], v[4:7]
	s_barrier
	v_mfma_f32_16x16x32_bf16 v[0:3], v[194:197], v[240:243], v[0:3]
	s_setprio 0
	s_add_i32 s82, s82, 2
	s_add_u32 s80, s80, 0x100
	s_addc_u32 s81, s81, 0
	s_add_u32 s48, s48, 0x100
	s_addc_u32 s49, s49, 0
	s_cmp_gt_u32 s82, 13
	s_cbranch_scc0 .LBB0_419
	s_and_b64 vcc, exec, s[16:17]
	s_cbranch_vccz .LBB0_422
	s_barrier

.LBB0_704:
	s_ashr_i32 s21, s20, 31
	s_lshl_b64 s[48:49], s[20:21], 18
	v_readlane_b32 s19, v254, 14
	s_add_u32 s48, s19, s48
	v_readlane_b32 s19, v254, 15
	s_addc_u32 s49, s19, s49
	s_and_b64 s[50:51], s[46:47], exec
	s_cselect_b32 s21, s49, s45
	s_cselect_b32 s78, s48, s44
	s_ashr_i32 s19, s18, 31
	s_lshl_b64 s[50:51], s[18:19], 18
	v_readlane_b32 s19, v254, 10
	s_add_u32 s50, s19, s50
	v_readlane_b32 s19, v254, 11
	s_addc_u32 s51, s19, s51
	s_and_b64 s[62:63], s[46:47], exec
	s_cselect_b32 s19, s51, s61
	s_cselect_b32 s79, s50, s60
	s_add_u32 s80, s60, 0x100
	s_addc_u32 s81, s61, 0
	s_add_u32 s60, s44, 0x20080
	s_addc_u32 s61, s45, 0
	s_mov_b32 s82, -2
	s_add_u32 s44, s60, 0xfffe0080
	s_addc_u32 s45, s61, -1
	s_add_i32 s83, 0, 0x10000
	s_cmp_eq_u32 s82, 4
	s_cselect_b32 s63, s21, s45
	s_cselect_b32 s62, s78, s44
	s_cselect_b32 s45, s19, s81
	s_cselect_b32 s44, s79, s80
	s_add_i32 s86, 0, 0x14000
	v_add_u32_e32 v140, s83, v195
	v_add_u32_e32 v186, s86, v195
	ds_read_b128 v[124:127], v140
	ds_read_b128 v[132:135], v140 offset:1024
	ds_read_b128 v[136:139], v140 offset:2048
	ds_read_b128 v[140:143], v140 offset:3072
	ds_read_b128 v[144:147], v186
	ds_read_b128 v[148:151], v186 offset:1024
	ds_read_b128 v[182:185], v186 offset:2048
	ds_read_b128 v[186:189], v186 offset:3072
	v_lshl_add_u64 v[198:199], s[60:61], 0, v[180:181]
	s_add_i32 m0, s59, 0xc000
	ds_read_b128 v[190:193], v197
	ds_read_b128 v[210:213], v197 offset:1024
	ds_read_b128 v[214:217], v197 offset:2048
	ds_read_b128 v[218:221], v197 offset:3072
	ds_read_b128 v[224:227], v197 offset:4096
	ds_read_b128 v[228:231], v197 offset:5120
	ds_read_b128 v[232:235], v197 offset:6144
	ds_read_b128 v[236:239], v197 offset:7168
	global_load_lds_dwordx4 v[198:199], off
	v_lshl_add_u64 v[198:199], s[60:61], 0, v[178:179]
	s_add_i32 m0, s59, 0xe000
	s_nop 0
	global_load_lds_dwordx4 v[198:199], off
	s_waitcnt vmcnt(8)
	s_waitcnt lgkmcnt(0)
	s_barrier
	s_setprio 1
	s_waitcnt lgkmcnt(0)
	v_mfma_f32_16x16x32_bf16 v[128:131], v[124:127], v[190:193], 0
	v_mfma_f32_16x16x32_bf16 v[120:123], v[136:139], v[190:193], 0
	v_mfma_f32_16x16x32_bf16 v[108:111], v[124:127], v[214:217], 0
	v_mfma_f32_16x16x32_bf16 v[104:107], v[136:139], v[214:217], 0
	v_mfma_f32_16x16x32_bf16 v[92:95], v[124:127], v[224:227], 0
	v_mfma_f32_16x16x32_bf16 v[88:91], v[136:139], v[224:227], 0
	v_mfma_f32_16x16x32_bf16 v[76:79], v[124:127], v[232:235], 0
	v_mfma_f32_16x16x32_bf16 v[72:75], v[136:139], v[232:235], 0
	v_mfma_f32_16x16x32_bf16 v[128:131], v[132:135], v[210:213], v[128:131]
	v_mfma_f32_16x16x32_bf16 v[120:123], v[140:143], v[210:213], v[120:123]
	v_mfma_f32_16x16x32_bf16 v[108:111], v[132:135], v[218:221], v[108:111]
	v_mfma_f32_16x16x32_bf16 v[104:107], v[140:143], v[218:221], v[104:107]
	v_mfma_f32_16x16x32_bf16 v[92:95], v[132:135], v[228:231], v[92:95]
	v_mfma_f32_16x16x32_bf16 v[88:91], v[140:143], v[228:231], v[88:91]
	v_mfma_f32_16x16x32_bf16 v[76:79], v[132:135], v[236:239], v[76:79]
	v_mfma_f32_16x16x32_bf16 v[72:75], v[140:143], v[236:239], v[72:75]
	s_setprio 0
	s_setprio 1
	v_mfma_f32_16x16x32_bf16 v[116:119], v[144:147], v[190:193], 0
	v_mfma_f32_16x16x32_bf16 v[112:115], v[182:185], v[190:193], 0
	v_mfma_f32_16x16x32_bf16 v[100:103], v[144:147], v[214:217], 0
	v_mfma_f32_16x16x32_bf16 v[96:99], v[182:185], v[214:217], 0
	v_mfma_f32_16x16x32_bf16 v[84:87], v[144:147], v[224:227], 0
	v_mfma_f32_16x16x32_bf16 v[80:83], v[182:185], v[224:227], 0
	v_mfma_f32_16x16x32_bf16 v[68:71], v[144:147], v[232:235], 0
	v_mfma_f32_16x16x32_bf16 v[64:67], v[182:185], v[232:235], 0
	v_mfma_f32_16x16x32_bf16 v[116:119], v[148:151], v[210:213], v[116:119]
	v_mfma_f32_16x16x32_bf16 v[112:115], v[186:189], v[210:213], v[112:115]
	v_mfma_f32_16x16x32_bf16 v[100:103], v[148:151], v[218:221], v[100:103]
	v_mfma_f32_16x16x32_bf16 v[96:99], v[186:189], v[218:221], v[96:99]
	v_mfma_f32_16x16x32_bf16 v[84:87], v[148:151], v[228:231], v[84:87]
	v_mfma_f32_16x16x32_bf16 v[80:83], v[186:189], v[228:231], v[80:83]
	v_mfma_f32_16x16x32_bf16 v[68:71], v[148:151], v[236:239], v[68:71]
	s_barrier
	v_mfma_f32_16x16x32_bf16 v[64:67], v[186:189], v[236:239], v[64:67]
	s_setprio 0
	s_add_i32 s83, s83, s8
	v_lshl_add_u64 v[198:199], s[44:45], 0, v[152:153]
	s_mov_b32 m0, s83
	ds_read_b128 v[190:193], v197 offset:16384
	ds_read_b128 v[210:213], v197 offset:17408
	ds_read_b128 v[214:217], v197 offset:18432
	ds_read_b128 v[218:221], v197 offset:19456
	ds_read_b128 v[224:227], v197 offset:20480
	ds_read_b128 v[228:231], v197 offset:21504
	ds_read_b128 v[232:235], v197 offset:22528
	ds_read_b128 v[236:239], v197 offset:23552
	global_load_lds_dwordx4 v[198:199], off
	s_add_i32 m0, s83, 0x2000
	s_add_u32 s84, s44, 0x20000
	v_lshl_add_u64 v[240:241], s[44:45], 0, v[172:173]
	s_addc_u32 s85, s45, 0
	s_add_i32 s83, s86, s8
	global_load_lds_dwordx4 v[240:241], off
	v_lshl_add_u64 v[242:243], s[84:85], 0, v[152:153]
	s_mov_b32 m0, s83
	v_lshl_add_u64 v[244:245], s[62:63], 0, v[174:175]
	global_load_lds_dwordx4 v[242:243], off
	v_lshl_add_u64 v[242:243], s[84:85], 0, v[172:173]
	s_add_i32 m0, s83, 0x2000
	s_nop 0
	global_load_lds_dwordx4 v[242:243], off
	v_lshl_add_u64 v[242:243], s[62:63], 0, v[176:177]
	s_mov_b32 m0, s59
	s_nop 0
	global_load_lds_dwordx4 v[242:243], off
	s_mov_b32 m0, s66
	s_nop 0
	global_load_lds_dwordx4 v[244:245], off
	s_waitcnt vmcnt(8)
	s_waitcnt lgkmcnt(0)
	s_barrier
	s_setprio 1
	s_waitcnt lgkmcnt(0)
	v_mfma_f32_16x16x32_bf16 v[60:63], v[124:127], v[190:193], 0
	v_mfma_f32_16x16x32_bf16 v[56:59], v[136:139], v[190:193], 0
	v_mfma_f32_16x16x32_bf16 v[48:51], v[124:127], v[214:217], 0
	v_mfma_f32_16x16x32_bf16 v[40:43], v[136:139], v[214:217], 0
	v_mfma_f32_16x16x32_bf16 v[32:35], v[124:127], v[224:227], 0
	v_mfma_f32_16x16x32_bf16 v[24:27], v[136:139], v[224:227], 0
	v_mfma_f32_16x16x32_bf16 v[16:19], v[124:127], v[232:235], 0
	v_mfma_f32_16x16x32_bf16 v[8:11], v[136:139], v[232:235], 0
	v_mfma_f32_16x16x32_bf16 v[60:63], v[132:135], v[210:213], v[60:63]
	v_mfma_f32_16x16x32_bf16 v[56:59], v[140:143], v[210:213], v[56:59]
	v_mfma_f32_16x16x32_bf16 v[48:51], v[132:135], v[218:221], v[48:51]
	v_mfma_f32_16x16x32_bf16 v[40:43], v[140:143], v[218:221], v[40:43]
	v_mfma_f32_16x16x32_bf16 v[32:35], v[132:135], v[228:231], v[32:35]
	v_mfma_f32_16x16x32_bf16 v[24:27], v[140:143], v[228:231], v[24:27]
	v_mfma_f32_16x16x32_bf16 v[16:19], v[132:135], v[236:239], v[16:19]
	v_mfma_f32_16x16x32_bf16 v[8:11], v[140:143], v[236:239], v[8:11]
	s_setprio 0
	s_setprio 1
	v_mfma_f32_16x16x32_bf16 v[52:55], v[144:147], v[190:193], 0
	v_mfma_f32_16x16x32_bf16 v[44:47], v[182:185], v[190:193], 0
	v_mfma_f32_16x16x32_bf16 v[36:39], v[144:147], v[214:217], 0
	v_mfma_f32_16x16x32_bf16 v[28:31], v[182:185], v[214:217], 0
	v_mfma_f32_16x16x32_bf16 v[20:23], v[144:147], v[224:227], 0
	v_mfma_f32_16x16x32_bf16 v[12:15], v[182:185], v[224:227], 0
	v_mfma_f32_16x16x32_bf16 v[4:7], v[144:147], v[232:235], 0
	v_mfma_f32_16x16x32_bf16 v[0:3], v[182:185], v[232:235], 0
	v_mfma_f32_16x16x32_bf16 v[52:55], v[148:151], v[210:213], v[52:55]
	v_mfma_f32_16x16x32_bf16 v[44:47], v[186:189], v[210:213], v[44:47]
	v_mfma_f32_16x16x32_bf16 v[36:39], v[148:151], v[218:221], v[36:39]
	v_mfma_f32_16x16x32_bf16 v[28:31], v[186:189], v[218:221], v[28:31]
	v_mfma_f32_16x16x32_bf16 v[20:23], v[148:151], v[228:231], v[20:23]
	v_mfma_f32_16x16x32_bf16 v[12:15], v[186:189], v[228:231], v[12:15]
	v_mfma_f32_16x16x32_bf16 v[4:7], v[148:151], v[236:239], v[4:7]
	s_barrier
	v_mfma_f32_16x16x32_bf16 v[0:3], v[186:189], v[236:239], v[0:3]
	s_setprio 0
	s_add_i32 s83, 0, 0x18000
	s_add_i32 s84, 0, 0x1c000
	v_add_u32_e32 v140, s83, v195
	v_add_u32_e32 v186, s84, v195
	ds_read_b128 v[124:127], v140
	ds_read_b128 v[132:135], v140 offset:1024
	ds_read_b128 v[136:139], v140 offset:2048
	ds_read_b128 v[140:143], v140 offset:3072
	ds_read_b128 v[144:147], v186
	ds_read_b128 v[148:151], v186 offset:1024
	ds_read_b128 v[182:185], v186 offset:2048
	ds_read_b128 v[186:189], v186 offset:3072
	s_add_u32 s62, s62, 0x20000
	s_addc_u32 s63, s63, 0
	s_mov_b32 m0, s67
	v_lshl_add_u64 v[246:247], s[62:63], 0, v[176:177]
	ds_read_b128 v[190:193], v197 offset:32768
	ds_read_b128 v[210:213], v197 offset:33792
	ds_read_b128 v[214:217], v197 offset:34816
	ds_read_b128 v[218:221], v197 offset:35840
	ds_read_b128 v[224:227], v197 offset:36864
	ds_read_b128 v[228:231], v197 offset:37888
	ds_read_b128 v[232:235], v197 offset:38912
	ds_read_b128 v[236:239], v197 offset:39936
	global_load_lds_dwordx4 v[246:247], off
	v_lshl_add_u64 v[246:247], s[62:63], 0, v[174:175]
	s_mov_b32 m0, s68
	s_nop 0
	global_load_lds_dwordx4 v[246:247], off
	s_waitcnt vmcnt(8)
	s_waitcnt lgkmcnt(0)
	s_barrier
	s_setprio 1
	s_waitcnt lgkmcnt(0)
	v_mfma_f32_16x16x32_bf16 v[128:131], v[124:127], v[190:193], v[128:131]
	v_mfma_f32_16x16x32_bf16 v[120:123], v[136:139], v[190:193], v[120:123]
	v_mfma_f32_16x16x32_bf16 v[108:111], v[124:127], v[214:217], v[108:111]
	v_mfma_f32_16x16x32_bf16 v[104:107], v[136:139], v[214:217], v[104:107]
	v_mfma_f32_16x16x32_bf16 v[92:95], v[124:127], v[224:227], v[92:95]
	v_mfma_f32_16x16x32_bf16 v[88:91], v[136:139], v[224:227], v[88:91]
	v_mfma_f32_16x16x32_bf16 v[76:79], v[124:127], v[232:235], v[76:79]
	v_mfma_f32_16x16x32_bf16 v[72:75], v[136:139], v[232:235], v[72:75]
	v_mfma_f32_16x16x32_bf16 v[128:131], v[132:135], v[210:213], v[128:131]
	v_mfma_f32_16x16x32_bf16 v[120:123], v[140:143], v[210:213], v[120:123]
	v_mfma_f32_16x16x32_bf16 v[108:111], v[132:135], v[218:221], v[108:111]
	v_mfma_f32_16x16x32_bf16 v[104:107], v[140:143], v[218:221], v[104:107]
	v_mfma_f32_16x16x32_bf16 v[92:95], v[132:135], v[228:231], v[92:95]
	v_mfma_f32_16x16x32_bf16 v[88:91], v[140:143], v[228:231], v[88:91]
	v_mfma_f32_16x16x32_bf16 v[76:79], v[132:135], v[236:239], v[76:79]
	v_mfma_f32_16x16x32_bf16 v[72:75], v[140:143], v[236:239], v[72:75]
	s_setprio 0
	s_setprio 1
	v_mfma_f32_16x16x32_bf16 v[116:119], v[144:147], v[190:193], v[116:119]
	v_mfma_f32_16x16x32_bf16 v[112:115], v[182:185], v[190:193], v[112:115]
	v_mfma_f32_16x16x32_bf16 v[100:103], v[144:147], v[214:217], v[100:103]
	v_mfma_f32_16x16x32_bf16 v[96:99], v[182:185], v[214:217], v[96:99]
	v_mfma_f32_16x16x32_bf16 v[84:87], v[144:147], v[224:227], v[84:87]
	v_mfma_f32_16x16x32_bf16 v[80:83], v[182:185], v[224:227], v[80:83]
	v_mfma_f32_16x16x32_bf16 v[68:71], v[144:147], v[232:235], v[68:71]
	v_mfma_f32_16x16x32_bf16 v[64:67], v[182:185], v[232:235], v[64:67]
	v_mfma_f32_16x16x32_bf16 v[116:119], v[148:151], v[210:213], v[116:119]
	v_mfma_f32_16x16x32_bf16 v[112:115], v[186:189], v[210:213], v[112:115]
	v_mfma_f32_16x16x32_bf16 v[100:103], v[148:151], v[218:221], v[100:103]
	v_mfma_f32_16x16x32_bf16 v[96:99], v[186:189], v[218:221], v[96:99]
	v_mfma_f32_16x16x32_bf16 v[84:87], v[148:151], v[228:231], v[84:87]
	v_mfma_f32_16x16x32_bf16 v[80:83], v[186:189], v[228:231], v[80:83]
	v_mfma_f32_16x16x32_bf16 v[68:71], v[148:151], v[236:239], v[68:71]
	s_barrier
	v_mfma_f32_16x16x32_bf16 v[64:67], v[186:189], v[236:239], v[64:67]
	s_setprio 0
	s_add_i32 s62, s83, s8
	v_lshl_add_u64 v[198:199], v[198:199], 0, s[22:23]
	s_mov_b32 m0, s62
	ds_read_b128 v[190:193], v197 offset:49152
	ds_read_b128 v[210:213], v197 offset:50176
	ds_read_b128 v[214:217], v197 offset:51200
	ds_read_b128 v[218:221], v197 offset:52224
	ds_read_b128 v[224:227], v197 offset:53248
	ds_read_b128 v[228:231], v197 offset:54272
	ds_read_b128 v[232:235], v197 offset:55296
	ds_read_b128 v[236:239], v197 offset:56320
	global_load_lds_dwordx4 v[198:199], off
	s_add_i32 m0, s62, 0x2000
	s_add_u32 s44, s44, 0x20080
	v_lshl_add_u64 v[198:199], v[240:241], 0, s[22:23]
	s_addc_u32 s45, s45, 0
	s_add_i32 s62, s84, s8
	global_load_lds_dwordx4 v[198:199], off
	v_lshl_add_u64 v[198:199], s[44:45], 0, v[152:153]
	s_mov_b32 m0, s62
	s_nop 0
	global_load_lds_dwordx4 v[198:199], off
	v_lshl_add_u64 v[198:199], s[44:45], 0, v[172:173]
	s_add_i32 m0, s62, 0x2000
	s_nop 0
	global_load_lds_dwordx4 v[198:199], off
	v_lshl_add_u64 v[198:199], v[242:243], 0, s[22:23]
	s_mov_b32 m0, s69
	s_nop 0
	global_load_lds_dwordx4 v[198:199], off
	v_lshl_add_u64 v[198:199], v[244:245], 0, s[22:23]
	s_mov_b32 m0, s74
	s_nop 0
	global_load_lds_dwordx4 v[198:199], off
	s_waitcnt vmcnt(8)
	s_waitcnt lgkmcnt(0)
	s_barrier
	s_setprio 1
	s_waitcnt lgkmcnt(0)
	v_mfma_f32_16x16x32_bf16 v[60:63], v[124:127], v[190:193], v[60:63]
	v_mfma_f32_16x16x32_bf16 v[56:59], v[136:139], v[190:193], v[56:59]
	v_mfma_f32_16x16x32_bf16 v[48:51], v[124:127], v[214:217], v[48:51]
	v_mfma_f32_16x16x32_bf16 v[40:43], v[136:139], v[214:217], v[40:43]
	v_mfma_f32_16x16x32_bf16 v[32:35], v[124:127], v[224:227], v[32:35]
	v_mfma_f32_16x16x32_bf16 v[24:27], v[136:139], v[224:227], v[24:27]
	v_mfma_f32_16x16x32_bf16 v[16:19], v[124:127], v[232:235], v[16:19]
	v_mfma_f32_16x16x32_bf16 v[8:11], v[136:139], v[232:235], v[8:11]
	v_mfma_f32_16x16x32_bf16 v[60:63], v[132:135], v[210:213], v[60:63]
	v_mfma_f32_16x16x32_bf16 v[56:59], v[140:143], v[210:213], v[56:59]
	v_mfma_f32_16x16x32_bf16 v[48:51], v[132:135], v[218:221], v[48:51]
	v_mfma_f32_16x16x32_bf16 v[40:43], v[140:143], v[218:221], v[40:43]
	v_mfma_f32_16x16x32_bf16 v[32:35], v[132:135], v[228:231], v[32:35]
	v_mfma_f32_16x16x32_bf16 v[24:27], v[140:143], v[228:231], v[24:27]
	v_mfma_f32_16x16x32_bf16 v[16:19], v[132:135], v[236:239], v[16:19]
	v_mfma_f32_16x16x32_bf16 v[8:11], v[140:143], v[236:239], v[8:11]
	s_setprio 0
	s_setprio 1
	v_mfma_f32_16x16x32_bf16 v[52:55], v[144:147], v[190:193], v[52:55]
	v_mfma_f32_16x16x32_bf16 v[44:47], v[182:185], v[190:193], v[44:47]
	v_mfma_f32_16x16x32_bf16 v[36:39], v[144:147], v[214:217], v[36:39]
	v_mfma_f32_16x16x32_bf16 v[28:31], v[182:185], v[214:217], v[28:31]
	v_mfma_f32_16x16x32_bf16 v[20:23], v[144:147], v[224:227], v[20:23]
	v_mfma_f32_16x16x32_bf16 v[12:15], v[182:185], v[224:227], v[12:15]
	v_mfma_f32_16x16x32_bf16 v[4:7], v[144:147], v[232:235], v[4:7]
	v_mfma_f32_16x16x32_bf16 v[0:3], v[182:185], v[232:235], v[0:3]
	v_mfma_f32_16x16x32_bf16 v[52:55], v[148:151], v[210:213], v[52:55]
	v_mfma_f32_16x16x32_bf16 v[44:47], v[186:189], v[210:213], v[44:47]
	v_mfma_f32_16x16x32_bf16 v[36:39], v[148:151], v[218:221], v[36:39]
	v_mfma_f32_16x16x32_bf16 v[28:31], v[186:189], v[218:221], v[28:31]
	v_mfma_f32_16x16x32_bf16 v[20:23], v[148:151], v[228:231], v[20:23]
	v_mfma_f32_16x16x32_bf16 v[12:15], v[186:189], v[228:231], v[12:15]
	v_mfma_f32_16x16x32_bf16 v[4:7], v[148:151], v[236:239], v[4:7]
	s_barrier
	v_mfma_f32_16x16x32_bf16 v[0:3], v[186:189], v[236:239], v[0:3]
	s_setprio 0
	s_add_i32 s82, s82, 2
	s_add_u32 s80, s80, 0x100
	s_addc_u32 s81, s81, 0
	s_add_u32 s60, s60, 0x100
	s_addc_u32 s61, s61, 0
	s_cmp_gt_u32 s82, 5
.LBB0_705:
	s_add_u32 s44, s60, 0xfffe0080
	s_addc_u32 s45, s61, -1
	s_add_i32 s83, 0, 0x10000
	s_cmp_eq_u32 s82, 4
	s_cselect_b32 s63, s21, s45
	s_cselect_b32 s62, s78, s44
	s_cselect_b32 s45, s19, s81
	s_cselect_b32 s44, s79, s80
	s_add_i32 s86, 0, 0x14000
	v_add_u32_e32 v140, s83, v195
	v_add_u32_e32 v186, s86, v195
	ds_read_b128 v[124:127], v140
	ds_read_b128 v[132:135], v140 offset:1024
	ds_read_b128 v[136:139], v140 offset:2048
	ds_read_b128 v[140:143], v140 offset:3072
	ds_read_b128 v[144:147], v186
	ds_read_b128 v[148:151], v186 offset:1024
	ds_read_b128 v[182:185], v186 offset:2048
	ds_read_b128 v[186:189], v186 offset:3072
	v_lshl_add_u64 v[198:199], s[60:61], 0, v[180:181]
	s_add_i32 m0, s59, 0xc000
	ds_read_b128 v[190:193], v197
	ds_read_b128 v[210:213], v197 offset:1024
	ds_read_b128 v[214:217], v197 offset:2048
	ds_read_b128 v[218:221], v197 offset:3072
	ds_read_b128 v[224:227], v197 offset:4096
	ds_read_b128 v[228:231], v197 offset:5120
	ds_read_b128 v[232:235], v197 offset:6144
	ds_read_b128 v[236:239], v197 offset:7168
	global_load_lds_dwordx4 v[198:199], off
	v_lshl_add_u64 v[198:199], s[60:61], 0, v[178:179]
	s_add_i32 m0, s59, 0xe000
	s_nop 0
	global_load_lds_dwordx4 v[198:199], off
	s_waitcnt vmcnt(8)
	s_waitcnt lgkmcnt(0)
	s_barrier
	s_setprio 1
	s_waitcnt lgkmcnt(0)
	v_mfma_f32_16x16x32_bf16 v[128:131], v[124:127], v[190:193], v[128:131]
	v_mfma_f32_16x16x32_bf16 v[120:123], v[136:139], v[190:193], v[120:123]
	v_mfma_f32_16x16x32_bf16 v[108:111], v[124:127], v[214:217], v[108:111]
	v_mfma_f32_16x16x32_bf16 v[104:107], v[136:139], v[214:217], v[104:107]
	v_mfma_f32_16x16x32_bf16 v[92:95], v[124:127], v[224:227], v[92:95]
	v_mfma_f32_16x16x32_bf16 v[88:91], v[136:139], v[224:227], v[88:91]
	v_mfma_f32_16x16x32_bf16 v[76:79], v[124:127], v[232:235], v[76:79]
	v_mfma_f32_16x16x32_bf16 v[72:75], v[136:139], v[232:235], v[72:75]
	v_mfma_f32_16x16x32_bf16 v[128:131], v[132:135], v[210:213], v[128:131]
	v_mfma_f32_16x16x32_bf16 v[120:123], v[140:143], v[210:213], v[120:123]
	v_mfma_f32_16x16x32_bf16 v[108:111], v[132:135], v[218:221], v[108:111]
	v_mfma_f32_16x16x32_bf16 v[104:107], v[140:143], v[218:221], v[104:107]
	v_mfma_f32_16x16x32_bf16 v[92:95], v[132:135], v[228:231], v[92:95]
	v_mfma_f32_16x16x32_bf16 v[88:91], v[140:143], v[228:231], v[88:91]
	v_mfma_f32_16x16x32_bf16 v[76:79], v[132:135], v[236:239], v[76:79]
	v_mfma_f32_16x16x32_bf16 v[72:75], v[140:143], v[236:239], v[72:75]
	s_setprio 0
	s_setprio 1
	v_mfma_f32_16x16x32_bf16 v[116:119], v[144:147], v[190:193], v[116:119]
	v_mfma_f32_16x16x32_bf16 v[112:115], v[182:185], v[190:193], v[112:115]
	v_mfma_f32_16x16x32_bf16 v[100:103], v[144:147], v[214:217], v[100:103]
	v_mfma_f32_16x16x32_bf16 v[96:99], v[182:185], v[214:217], v[96:99]
	v_mfma_f32_16x16x32_bf16 v[84:87], v[144:147], v[224:227], v[84:87]
	v_mfma_f32_16x16x32_bf16 v[80:83], v[182:185], v[224:227], v[80:83]
	v_mfma_f32_16x16x32_bf16 v[68:71], v[144:147], v[232:235], v[68:71]
	v_mfma_f32_16x16x32_bf16 v[64:67], v[182:185], v[232:235], v[64:67]
	v_mfma_f32_16x16x32_bf16 v[116:119], v[148:151], v[210:213], v[116:119]
	v_mfma_f32_16x16x32_bf16 v[112:115], v[186:189], v[210:213], v[112:115]
	v_mfma_f32_16x16x32_bf16 v[100:103], v[148:151], v[218:221], v[100:103]
	v_mfma_f32_16x16x32_bf16 v[96:99], v[186:189], v[218:221], v[96:99]
	v_mfma_f32_16x16x32_bf16 v[84:87], v[148:151], v[228:231], v[84:87]
	v_mfma_f32_16x16x32_bf16 v[80:83], v[186:189], v[228:231], v[80:83]
	v_mfma_f32_16x16x32_bf16 v[68:71], v[148:151], v[236:239], v[68:71]
	s_barrier
	v_mfma_f32_16x16x32_bf16 v[64:67], v[186:189], v[236:239], v[64:67]
	s_setprio 0
	s_add_i32 s83, s83, s8
	v_lshl_add_u64 v[198:199], s[44:45], 0, v[152:153]
	s_mov_b32 m0, s83
	ds_read_b128 v[190:193], v197 offset:16384
	ds_read_b128 v[210:213], v197 offset:17408
	ds_read_b128 v[214:217], v197 offset:18432
	ds_read_b128 v[218:221], v197 offset:19456
	ds_read_b128 v[224:227], v197 offset:20480
	ds_read_b128 v[228:231], v197 offset:21504
	ds_read_b128 v[232:235], v197 offset:22528
	ds_read_b128 v[236:239], v197 offset:23552
	global_load_lds_dwordx4 v[198:199], off
	s_add_i32 m0, s83, 0x2000
	s_add_u32 s84, s44, 0x20000
	v_lshl_add_u64 v[240:241], s[44:45], 0, v[172:173]
	s_addc_u32 s85, s45, 0
	s_add_i32 s83, s86, s8
	global_load_lds_dwordx4 v[240:241], off
	v_lshl_add_u64 v[242:243], s[84:85], 0, v[152:153]
	s_mov_b32 m0, s83
	v_lshl_add_u64 v[244:245], s[62:63], 0, v[174:175]
	global_load_lds_dwordx4 v[242:243], off
	v_lshl_add_u64 v[242:243], s[84:85], 0, v[172:173]
	s_add_i32 m0, s83, 0x2000
	s_nop 0
	global_load_lds_dwordx4 v[242:243], off
	v_lshl_add_u64 v[242:243], s[62:63], 0, v[176:177]
	s_mov_b32 m0, s59
	s_nop 0
	global_load_lds_dwordx4 v[242:243], off
	s_mov_b32 m0, s66
	s_nop 0
	global_load_lds_dwordx4 v[244:245], off
	s_waitcnt vmcnt(8)
	s_waitcnt lgkmcnt(0)
	s_barrier
	s_setprio 1
	s_waitcnt lgkmcnt(0)
	v_mfma_f32_16x16x32_bf16 v[60:63], v[124:127], v[190:193], v[60:63]
	v_mfma_f32_16x16x32_bf16 v[56:59], v[136:139], v[190:193], v[56:59]
	v_mfma_f32_16x16x32_bf16 v[48:51], v[124:127], v[214:217], v[48:51]
	v_mfma_f32_16x16x32_bf16 v[40:43], v[136:139], v[214:217], v[40:43]
	v_mfma_f32_16x16x32_bf16 v[32:35], v[124:127], v[224:227], v[32:35]
	v_mfma_f32_16x16x32_bf16 v[24:27], v[136:139], v[224:227], v[24:27]
	v_mfma_f32_16x16x32_bf16 v[16:19], v[124:127], v[232:235], v[16:19]
	v_mfma_f32_16x16x32_bf16 v[8:11], v[136:139], v[232:235], v[8:11]
	v_mfma_f32_16x16x32_bf16 v[60:63], v[132:135], v[210:213], v[60:63]
	v_mfma_f32_16x16x32_bf16 v[56:59], v[140:143], v[210:213], v[56:59]
	v_mfma_f32_16x16x32_bf16 v[48:51], v[132:135], v[218:221], v[48:51]
	v_mfma_f32_16x16x32_bf16 v[40:43], v[140:143], v[218:221], v[40:43]
	v_mfma_f32_16x16x32_bf16 v[32:35], v[132:135], v[228:231], v[32:35]
	v_mfma_f32_16x16x32_bf16 v[24:27], v[140:143], v[228:231], v[24:27]
	v_mfma_f32_16x16x32_bf16 v[16:19], v[132:135], v[236:239], v[16:19]
	v_mfma_f32_16x16x32_bf16 v[8:11], v[140:143], v[236:239], v[8:11]
	s_setprio 0
	s_setprio 1
	v_mfma_f32_16x16x32_bf16 v[52:55], v[144:147], v[190:193], v[52:55]
	v_mfma_f32_16x16x32_bf16 v[44:47], v[182:185], v[190:193], v[44:47]
	v_mfma_f32_16x16x32_bf16 v[36:39], v[144:147], v[214:217], v[36:39]
	v_mfma_f32_16x16x32_bf16 v[28:31], v[182:185], v[214:217], v[28:31]
	v_mfma_f32_16x16x32_bf16 v[20:23], v[144:147], v[224:227], v[20:23]
	v_mfma_f32_16x16x32_bf16 v[12:15], v[182:185], v[224:227], v[12:15]
	v_mfma_f32_16x16x32_bf16 v[4:7], v[144:147], v[232:235], v[4:7]
	v_mfma_f32_16x16x32_bf16 v[0:3], v[182:185], v[232:235], v[0:3]
	v_mfma_f32_16x16x32_bf16 v[52:55], v[148:151], v[210:213], v[52:55]
	v_mfma_f32_16x16x32_bf16 v[44:47], v[186:189], v[210:213], v[44:47]
	v_mfma_f32_16x16x32_bf16 v[36:39], v[148:151], v[218:221], v[36:39]
	v_mfma_f32_16x16x32_bf16 v[28:31], v[186:189], v[218:221], v[28:31]
	v_mfma_f32_16x16x32_bf16 v[20:23], v[148:151], v[228:231], v[20:23]
	v_mfma_f32_16x16x32_bf16 v[12:15], v[186:189], v[228:231], v[12:15]
	v_mfma_f32_16x16x32_bf16 v[4:7], v[148:151], v[236:239], v[4:7]
	s_barrier
	v_mfma_f32_16x16x32_bf16 v[0:3], v[186:189], v[236:239], v[0:3]
	s_setprio 0
	s_add_i32 s83, 0, 0x18000
	s_add_i32 s84, 0, 0x1c000
	v_add_u32_e32 v140, s83, v195
	v_add_u32_e32 v186, s84, v195
	ds_read_b128 v[124:127], v140
	ds_read_b128 v[132:135], v140 offset:1024
	ds_read_b128 v[136:139], v140 offset:2048
	ds_read_b128 v[140:143], v140 offset:3072
	ds_read_b128 v[144:147], v186
	ds_read_b128 v[148:151], v186 offset:1024
	ds_read_b128 v[182:185], v186 offset:2048
	ds_read_b128 v[186:189], v186 offset:3072
	s_add_u32 s62, s62, 0x20000
	s_addc_u32 s63, s63, 0
	s_mov_b32 m0, s67
	v_lshl_add_u64 v[246:247], s[62:63], 0, v[176:177]
	ds_read_b128 v[190:193], v197 offset:32768
	ds_read_b128 v[210:213], v197 offset:33792
	ds_read_b128 v[214:217], v197 offset:34816
	ds_read_b128 v[218:221], v197 offset:35840
	ds_read_b128 v[224:227], v197 offset:36864
	ds_read_b128 v[228:231], v197 offset:37888
	ds_read_b128 v[232:235], v197 offset:38912
	ds_read_b128 v[236:239], v197 offset:39936
	global_load_lds_dwordx4 v[246:247], off
	v_lshl_add_u64 v[246:247], s[62:63], 0, v[174:175]
	s_mov_b32 m0, s68
	s_nop 0
	global_load_lds_dwordx4 v[246:247], off
	s_waitcnt vmcnt(8)
	s_waitcnt lgkmcnt(0)
	s_barrier
	s_setprio 1
	s_waitcnt lgkmcnt(0)
	v_mfma_f32_16x16x32_bf16 v[128:131], v[124:127], v[190:193], v[128:131]
	v_mfma_f32_16x16x32_bf16 v[120:123], v[136:139], v[190:193], v[120:123]
	v_mfma_f32_16x16x32_bf16 v[108:111], v[124:127], v[214:217], v[108:111]
	v_mfma_f32_16x16x32_bf16 v[104:107], v[136:139], v[214:217], v[104:107]
	v_mfma_f32_16x16x32_bf16 v[92:95], v[124:127], v[224:227], v[92:95]
	v_mfma_f32_16x16x32_bf16 v[88:91], v[136:139], v[224:227], v[88:91]
	v_mfma_f32_16x16x32_bf16 v[76:79], v[124:127], v[232:235], v[76:79]
	v_mfma_f32_16x16x32_bf16 v[72:75], v[136:139], v[232:235], v[72:75]
	v_mfma_f32_16x16x32_bf16 v[128:131], v[132:135], v[210:213], v[128:131]
	v_mfma_f32_16x16x32_bf16 v[120:123], v[140:143], v[210:213], v[120:123]
	v_mfma_f32_16x16x32_bf16 v[108:111], v[132:135], v[218:221], v[108:111]
	v_mfma_f32_16x16x32_bf16 v[104:107], v[140:143], v[218:221], v[104:107]
	v_mfma_f32_16x16x32_bf16 v[92:95], v[132:135], v[228:231], v[92:95]
	v_mfma_f32_16x16x32_bf16 v[88:91], v[140:143], v[228:231], v[88:91]
	v_mfma_f32_16x16x32_bf16 v[76:79], v[132:135], v[236:239], v[76:79]
	v_mfma_f32_16x16x32_bf16 v[72:75], v[140:143], v[236:239], v[72:75]
	s_setprio 0
	s_setprio 1
	v_mfma_f32_16x16x32_bf16 v[116:119], v[144:147], v[190:193], v[116:119]
	v_mfma_f32_16x16x32_bf16 v[112:115], v[182:185], v[190:193], v[112:115]
	v_mfma_f32_16x16x32_bf16 v[100:103], v[144:147], v[214:217], v[100:103]
	v_mfma_f32_16x16x32_bf16 v[96:99], v[182:185], v[214:217], v[96:99]
	v_mfma_f32_16x16x32_bf16 v[84:87], v[144:147], v[224:227], v[84:87]
	v_mfma_f32_16x16x32_bf16 v[80:83], v[182:185], v[224:227], v[80:83]
	v_mfma_f32_16x16x32_bf16 v[68:71], v[144:147], v[232:235], v[68:71]
	v_mfma_f32_16x16x32_bf16 v[64:67], v[182:185], v[232:235], v[64:67]
	v_mfma_f32_16x16x32_bf16 v[116:119], v[148:151], v[210:213], v[116:119]
	v_mfma_f32_16x16x32_bf16 v[112:115], v[186:189], v[210:213], v[112:115]
	v_mfma_f32_16x16x32_bf16 v[100:103], v[148:151], v[218:221], v[100:103]
	v_mfma_f32_16x16x32_bf16 v[96:99], v[186:189], v[218:221], v[96:99]
	v_mfma_f32_16x16x32_bf16 v[84:87], v[148:151], v[228:231], v[84:87]
	v_mfma_f32_16x16x32_bf16 v[80:83], v[186:189], v[228:231], v[80:83]
	v_mfma_f32_16x16x32_bf16 v[68:71], v[148:151], v[236:239], v[68:71]
	s_barrier
	v_mfma_f32_16x16x32_bf16 v[64:67], v[186:189], v[236:239], v[64:67]
	s_setprio 0
	s_add_i32 s62, s83, s8
	v_lshl_add_u64 v[198:199], v[198:199], 0, s[22:23]
	s_mov_b32 m0, s62
	ds_read_b128 v[190:193], v197 offset:49152
	ds_read_b128 v[210:213], v197 offset:50176
	ds_read_b128 v[214:217], v197 offset:51200
	ds_read_b128 v[218:221], v197 offset:52224
	ds_read_b128 v[224:227], v197 offset:53248
	ds_read_b128 v[228:231], v197 offset:54272
	ds_read_b128 v[232:235], v197 offset:55296
	ds_read_b128 v[236:239], v197 offset:56320
	global_load_lds_dwordx4 v[198:199], off
	s_add_i32 m0, s62, 0x2000
	s_add_u32 s44, s44, 0x20080
	v_lshl_add_u64 v[198:199], v[240:241], 0, s[22:23]
	s_addc_u32 s45, s45, 0
	s_add_i32 s62, s84, s8
	global_load_lds_dwordx4 v[198:199], off
	v_lshl_add_u64 v[198:199], s[44:45], 0, v[152:153]
	s_mov_b32 m0, s62
	s_nop 0
	global_load_lds_dwordx4 v[198:199], off
	v_lshl_add_u64 v[198:199], s[44:45], 0, v[172:173]
	s_add_i32 m0, s62, 0x2000
	s_nop 0
	global_load_lds_dwordx4 v[198:199], off
	v_lshl_add_u64 v[198:199], v[242:243], 0, s[22:23]
	s_mov_b32 m0, s69
	s_nop 0
	global_load_lds_dwordx4 v[198:199], off
	v_lshl_add_u64 v[198:199], v[244:245], 0, s[22:23]
	s_mov_b32 m0, s74
	s_nop 0
	global_load_lds_dwordx4 v[198:199], off
	s_waitcnt vmcnt(8)
	s_waitcnt lgkmcnt(0)
	s_barrier
	s_setprio 1
	s_waitcnt lgkmcnt(0)
	v_mfma_f32_16x16x32_bf16 v[60:63], v[124:127], v[190:193], v[60:63]
	v_mfma_f32_16x16x32_bf16 v[56:59], v[136:139], v[190:193], v[56:59]
	v_mfma_f32_16x16x32_bf16 v[48:51], v[124:127], v[214:217], v[48:51]
	v_mfma_f32_16x16x32_bf16 v[40:43], v[136:139], v[214:217], v[40:43]
	v_mfma_f32_16x16x32_bf16 v[32:35], v[124:127], v[224:227], v[32:35]
	v_mfma_f32_16x16x32_bf16 v[24:27], v[136:139], v[224:227], v[24:27]
	v_mfma_f32_16x16x32_bf16 v[16:19], v[124:127], v[232:235], v[16:19]
	v_mfma_f32_16x16x32_bf16 v[8:11], v[136:139], v[232:235], v[8:11]
	v_mfma_f32_16x16x32_bf16 v[60:63], v[132:135], v[210:213], v[60:63]
	v_mfma_f32_16x16x32_bf16 v[56:59], v[140:143], v[210:213], v[56:59]
	v_mfma_f32_16x16x32_bf16 v[48:51], v[132:135], v[218:221], v[48:51]
	v_mfma_f32_16x16x32_bf16 v[40:43], v[140:143], v[218:221], v[40:43]
	v_mfma_f32_16x16x32_bf16 v[32:35], v[132:135], v[228:231], v[32:35]
	v_mfma_f32_16x16x32_bf16 v[24:27], v[140:143], v[228:231], v[24:27]
	v_mfma_f32_16x16x32_bf16 v[16:19], v[132:135], v[236:239], v[16:19]
	v_mfma_f32_16x16x32_bf16 v[8:11], v[140:143], v[236:239], v[8:11]
	s_setprio 0
	s_setprio 1
	v_mfma_f32_16x16x32_bf16 v[52:55], v[144:147], v[190:193], v[52:55]
	v_mfma_f32_16x16x32_bf16 v[44:47], v[182:185], v[190:193], v[44:47]
	v_mfma_f32_16x16x32_bf16 v[36:39], v[144:147], v[214:217], v[36:39]
	v_mfma_f32_16x16x32_bf16 v[28:31], v[182:185], v[214:217], v[28:31]
	v_mfma_f32_16x16x32_bf16 v[20:23], v[144:147], v[224:227], v[20:23]
	v_mfma_f32_16x16x32_bf16 v[12:15], v[182:185], v[224:227], v[12:15]
	v_mfma_f32_16x16x32_bf16 v[4:7], v[144:147], v[232:235], v[4:7]
	v_mfma_f32_16x16x32_bf16 v[0:3], v[182:185], v[232:235], v[0:3]
	v_mfma_f32_16x16x32_bf16 v[52:55], v[148:151], v[210:213], v[52:55]
	v_mfma_f32_16x16x32_bf16 v[44:47], v[186:189], v[210:213], v[44:47]
	v_mfma_f32_16x16x32_bf16 v[36:39], v[148:151], v[218:221], v[36:39]
	v_mfma_f32_16x16x32_bf16 v[28:31], v[186:189], v[218:221], v[28:31]
	v_mfma_f32_16x16x32_bf16 v[20:23], v[148:151], v[228:231], v[20:23]
	v_mfma_f32_16x16x32_bf16 v[12:15], v[186:189], v[228:231], v[12:15]
	v_mfma_f32_16x16x32_bf16 v[4:7], v[148:151], v[236:239], v[4:7]
	s_barrier
	v_mfma_f32_16x16x32_bf16 v[0:3], v[186:189], v[236:239], v[0:3]
	s_setprio 0
	s_add_i32 s82, s82, 2
	s_add_u32 s80, s80, 0x100
	s_addc_u32 s81, s81, 0
	s_add_u32 s60, s60, 0x100
	s_addc_u32 s61, s61, 0
	s_cmp_gt_u32 s82, 5
	s_cbranch_scc0 .LBB0_705
	s_and_b64 vcc, exec, s[16:17]
	s_cbranch_vccz .LBB0_708
	s_barrier

.LBB0_724:
	s_ashr_i32 s21, s20, 31
	s_lshl_b64 s[48:49], s[20:21], 18
	v_readlane_b32 s19, v254, 28
	s_add_u32 s48, s19, s48
	v_readlane_b32 s19, v254, 29
	s_addc_u32 s49, s19, s49
	s_and_b64 s[50:51], s[46:47], exec
	s_cselect_b32 s21, s49, s45
	s_cselect_b32 s78, s48, s44
	s_ashr_i32 s19, s18, 31
	s_lshl_b64 s[50:51], s[18:19], 18
	v_readlane_b32 s19, v254, 24
	s_add_u32 s50, s19, s50
	v_readlane_b32 s19, v254, 25
	s_addc_u32 s51, s19, s51
	s_and_b64 s[62:63], s[46:47], exec
	s_cselect_b32 s19, s51, s61
	s_cselect_b32 s79, s50, s60
	s_add_u32 s80, s60, 0x100
	s_addc_u32 s81, s61, 0
	s_add_u32 s60, s44, 0x20080
	s_addc_u32 s61, s45, 0
	s_mov_b32 s82, -2
	s_add_u32 s44, s60, 0xfffe0080
	s_addc_u32 s45, s61, -1
	s_add_i32 s83, 0, 0x10000
	s_cmp_eq_u32 s82, 4
	s_cselect_b32 s63, s21, s45
	s_cselect_b32 s62, s78, s44
	s_cselect_b32 s45, s19, s81
	s_cselect_b32 s44, s79, s80
	s_add_i32 s86, 0, 0x14000
	v_add_u32_e32 v140, s83, v181
	v_add_u32_e32 v178, s86, v181
	ds_read_b128 v[128:131], v140
	ds_read_b128 v[132:135], v140 offset:1024
	ds_read_b128 v[136:139], v140 offset:2048
	ds_read_b128 v[140:143], v140 offset:3072
	ds_read_b128 v[174:177], v178
	ds_read_b128 v[184:187], v178 offset:1024
	ds_read_b128 v[188:191], v178 offset:2048
	ds_read_b128 v[192:195], v178 offset:3072
	v_lshl_add_u64 v[178:179], s[60:61], 0, v[172:173]
	s_add_i32 m0, s59, 0xc000
	ds_read_b128 v[196:199], v183
	ds_read_b128 v[210:213], v183 offset:1024
	ds_read_b128 v[214:217], v183 offset:2048
	ds_read_b128 v[218:221], v183 offset:3072
	ds_read_b128 v[224:227], v183 offset:4096
	ds_read_b128 v[228:231], v183 offset:5120
	ds_read_b128 v[232:235], v183 offset:6144
	ds_read_b128 v[236:239], v183 offset:7168
	global_load_lds_dwordx4 v[178:179], off
	v_lshl_add_u64 v[178:179], s[60:61], 0, v[150:151]
	s_add_i32 m0, s59, 0xe000
	s_nop 0
	global_load_lds_dwordx4 v[178:179], off
	s_waitcnt vmcnt(8)
	s_waitcnt lgkmcnt(0)
	s_barrier
	s_setprio 1
	s_waitcnt lgkmcnt(0)
	v_mfma_f32_16x16x32_bf16 v[124:127], v[128:131], v[196:199], 0
	v_mfma_f32_16x16x32_bf16 v[120:123], v[136:139], v[196:199], 0
	v_mfma_f32_16x16x32_bf16 v[108:111], v[128:131], v[214:217], 0
	v_mfma_f32_16x16x32_bf16 v[104:107], v[136:139], v[214:217], 0
	v_mfma_f32_16x16x32_bf16 v[92:95], v[128:131], v[224:227], 0
	v_mfma_f32_16x16x32_bf16 v[88:91], v[136:139], v[224:227], 0
	v_mfma_f32_16x16x32_bf16 v[76:79], v[128:131], v[232:235], 0
	v_mfma_f32_16x16x32_bf16 v[72:75], v[136:139], v[232:235], 0
	v_mfma_f32_16x16x32_bf16 v[124:127], v[132:135], v[210:213], v[124:127]
	v_mfma_f32_16x16x32_bf16 v[120:123], v[140:143], v[210:213], v[120:123]
	v_mfma_f32_16x16x32_bf16 v[108:111], v[132:135], v[218:221], v[108:111]
	v_mfma_f32_16x16x32_bf16 v[104:107], v[140:143], v[218:221], v[104:107]
	v_mfma_f32_16x16x32_bf16 v[92:95], v[132:135], v[228:231], v[92:95]
	v_mfma_f32_16x16x32_bf16 v[88:91], v[140:143], v[228:231], v[88:91]
	v_mfma_f32_16x16x32_bf16 v[76:79], v[132:135], v[236:239], v[76:79]
	v_mfma_f32_16x16x32_bf16 v[72:75], v[140:143], v[236:239], v[72:75]
	s_setprio 0
	s_setprio 1
	v_mfma_f32_16x16x32_bf16 v[116:119], v[174:177], v[196:199], 0
	v_mfma_f32_16x16x32_bf16 v[112:115], v[188:191], v[196:199], 0
	v_mfma_f32_16x16x32_bf16 v[100:103], v[174:177], v[214:217], 0
	v_mfma_f32_16x16x32_bf16 v[96:99], v[188:191], v[214:217], 0
	v_mfma_f32_16x16x32_bf16 v[84:87], v[174:177], v[224:227], 0
	v_mfma_f32_16x16x32_bf16 v[80:83], v[188:191], v[224:227], 0
	v_mfma_f32_16x16x32_bf16 v[68:71], v[174:177], v[232:235], 0
	v_mfma_f32_16x16x32_bf16 v[64:67], v[188:191], v[232:235], 0
	v_mfma_f32_16x16x32_bf16 v[116:119], v[184:187], v[210:213], v[116:119]
	v_mfma_f32_16x16x32_bf16 v[112:115], v[192:195], v[210:213], v[112:115]
	v_mfma_f32_16x16x32_bf16 v[100:103], v[184:187], v[218:221], v[100:103]
	v_mfma_f32_16x16x32_bf16 v[96:99], v[192:195], v[218:221], v[96:99]
	v_mfma_f32_16x16x32_bf16 v[84:87], v[184:187], v[228:231], v[84:87]
	v_mfma_f32_16x16x32_bf16 v[80:83], v[192:195], v[228:231], v[80:83]
	v_mfma_f32_16x16x32_bf16 v[68:71], v[184:187], v[236:239], v[68:71]
	s_barrier
	v_mfma_f32_16x16x32_bf16 v[64:67], v[192:195], v[236:239], v[64:67]
	s_setprio 0
	s_add_i32 s83, s83, s8
	v_lshl_add_u64 v[178:179], s[44:45], 0, v[152:153]
	s_mov_b32 m0, s83
	ds_read_b128 v[196:199], v183 offset:16384
	ds_read_b128 v[210:213], v183 offset:17408
	ds_read_b128 v[214:217], v183 offset:18432
	ds_read_b128 v[218:221], v183 offset:19456
	ds_read_b128 v[224:227], v183 offset:20480
	ds_read_b128 v[228:231], v183 offset:21504
	ds_read_b128 v[232:235], v183 offset:22528
	ds_read_b128 v[236:239], v183 offset:23552
	global_load_lds_dwordx4 v[178:179], off
	s_add_i32 m0, s83, 0x2000
	s_add_u32 s84, s44, 0x20000
	v_lshl_add_u64 v[240:241], s[44:45], 0, v[144:145]
	s_addc_u32 s85, s45, 0
	s_add_i32 s83, s86, s8
	global_load_lds_dwordx4 v[240:241], off
	v_lshl_add_u64 v[242:243], s[84:85], 0, v[152:153]
	s_mov_b32 m0, s83
	v_lshl_add_u64 v[244:245], s[62:63], 0, v[146:147]
	global_load_lds_dwordx4 v[242:243], off
	v_lshl_add_u64 v[242:243], s[84:85], 0, v[144:145]
	s_add_i32 m0, s83, 0x2000
	s_nop 0
	global_load_lds_dwordx4 v[242:243], off
	v_lshl_add_u64 v[242:243], s[62:63], 0, v[148:149]
	s_mov_b32 m0, s59
	s_nop 0
	global_load_lds_dwordx4 v[242:243], off
	s_mov_b32 m0, s66
	s_nop 0
	global_load_lds_dwordx4 v[244:245], off
	s_waitcnt vmcnt(8)
	s_waitcnt lgkmcnt(0)
	s_barrier
	s_setprio 1
	s_waitcnt lgkmcnt(0)
	v_mfma_f32_16x16x32_bf16 v[60:63], v[128:131], v[196:199], 0
	v_mfma_f32_16x16x32_bf16 v[56:59], v[136:139], v[196:199], 0
	v_mfma_f32_16x16x32_bf16 v[44:47], v[128:131], v[214:217], 0
	v_mfma_f32_16x16x32_bf16 v[40:43], v[136:139], v[214:217], 0
	v_mfma_f32_16x16x32_bf16 v[28:31], v[128:131], v[224:227], 0
	v_mfma_f32_16x16x32_bf16 v[24:27], v[136:139], v[224:227], 0
	v_mfma_f32_16x16x32_bf16 v[12:15], v[128:131], v[232:235], 0
	v_mfma_f32_16x16x32_bf16 v[8:11], v[136:139], v[232:235], 0
	v_mfma_f32_16x16x32_bf16 v[60:63], v[132:135], v[210:213], v[60:63]
	v_mfma_f32_16x16x32_bf16 v[56:59], v[140:143], v[210:213], v[56:59]
	v_mfma_f32_16x16x32_bf16 v[44:47], v[132:135], v[218:221], v[44:47]
	v_mfma_f32_16x16x32_bf16 v[40:43], v[140:143], v[218:221], v[40:43]
	v_mfma_f32_16x16x32_bf16 v[28:31], v[132:135], v[228:231], v[28:31]
	v_mfma_f32_16x16x32_bf16 v[24:27], v[140:143], v[228:231], v[24:27]
	v_mfma_f32_16x16x32_bf16 v[12:15], v[132:135], v[236:239], v[12:15]
	v_mfma_f32_16x16x32_bf16 v[8:11], v[140:143], v[236:239], v[8:11]
	s_setprio 0
	s_setprio 1
	v_mfma_f32_16x16x32_bf16 v[52:55], v[174:177], v[196:199], 0
	v_mfma_f32_16x16x32_bf16 v[48:51], v[188:191], v[196:199], 0
	v_mfma_f32_16x16x32_bf16 v[36:39], v[174:177], v[214:217], 0
	v_mfma_f32_16x16x32_bf16 v[32:35], v[188:191], v[214:217], 0
	v_mfma_f32_16x16x32_bf16 v[20:23], v[174:177], v[224:227], 0
	v_mfma_f32_16x16x32_bf16 v[16:19], v[188:191], v[224:227], 0
	v_mfma_f32_16x16x32_bf16 v[4:7], v[174:177], v[232:235], 0
	v_mfma_f32_16x16x32_bf16 v[0:3], v[188:191], v[232:235], 0
	v_mfma_f32_16x16x32_bf16 v[52:55], v[184:187], v[210:213], v[52:55]
	v_mfma_f32_16x16x32_bf16 v[48:51], v[192:195], v[210:213], v[48:51]
	v_mfma_f32_16x16x32_bf16 v[36:39], v[184:187], v[218:221], v[36:39]
	v_mfma_f32_16x16x32_bf16 v[32:35], v[192:195], v[218:221], v[32:35]
	v_mfma_f32_16x16x32_bf16 v[20:23], v[184:187], v[228:231], v[20:23]
	v_mfma_f32_16x16x32_bf16 v[16:19], v[192:195], v[228:231], v[16:19]
	v_mfma_f32_16x16x32_bf16 v[4:7], v[184:187], v[236:239], v[4:7]
	s_barrier
	v_mfma_f32_16x16x32_bf16 v[0:3], v[192:195], v[236:239], v[0:3]
	s_setprio 0
	s_add_i32 s83, 0, 0x18000
	s_add_i32 s84, 0, 0x1c000
	v_add_u32_e32 v140, s83, v181
	v_add_u32_e32 v192, s84, v181
	ds_read_b128 v[128:131], v140
	ds_read_b128 v[132:135], v140 offset:1024
	ds_read_b128 v[136:139], v140 offset:2048
	ds_read_b128 v[140:143], v140 offset:3072
	ds_read_b128 v[174:177], v192
	ds_read_b128 v[184:187], v192 offset:1024
	ds_read_b128 v[188:191], v192 offset:2048
	ds_read_b128 v[192:195], v192 offset:3072
	s_add_u32 s62, s62, 0x20000
	s_addc_u32 s63, s63, 0
	s_mov_b32 m0, s67
	v_lshl_add_u64 v[246:247], s[62:63], 0, v[148:149]
	ds_read_b128 v[196:199], v183 offset:32768
	ds_read_b128 v[210:213], v183 offset:33792
	ds_read_b128 v[214:217], v183 offset:34816
	ds_read_b128 v[218:221], v183 offset:35840
	ds_read_b128 v[224:227], v183 offset:36864
	ds_read_b128 v[228:231], v183 offset:37888
	ds_read_b128 v[232:235], v183 offset:38912
	ds_read_b128 v[236:239], v183 offset:39936
	global_load_lds_dwordx4 v[246:247], off
	v_lshl_add_u64 v[246:247], s[62:63], 0, v[146:147]
	s_mov_b32 m0, s68
	s_nop 0
	global_load_lds_dwordx4 v[246:247], off
	s_waitcnt vmcnt(8)
	s_waitcnt lgkmcnt(0)
	s_barrier
	s_setprio 1
	s_waitcnt lgkmcnt(0)
	v_mfma_f32_16x16x32_bf16 v[124:127], v[128:131], v[196:199], v[124:127]
	v_mfma_f32_16x16x32_bf16 v[120:123], v[136:139], v[196:199], v[120:123]
	v_mfma_f32_16x16x32_bf16 v[108:111], v[128:131], v[214:217], v[108:111]
	v_mfma_f32_16x16x32_bf16 v[104:107], v[136:139], v[214:217], v[104:107]
	v_mfma_f32_16x16x32_bf16 v[92:95], v[128:131], v[224:227], v[92:95]
	v_mfma_f32_16x16x32_bf16 v[88:91], v[136:139], v[224:227], v[88:91]
	v_mfma_f32_16x16x32_bf16 v[76:79], v[128:131], v[232:235], v[76:79]
	v_mfma_f32_16x16x32_bf16 v[72:75], v[136:139], v[232:235], v[72:75]
	v_mfma_f32_16x16x32_bf16 v[124:127], v[132:135], v[210:213], v[124:127]
	v_mfma_f32_16x16x32_bf16 v[120:123], v[140:143], v[210:213], v[120:123]
	v_mfma_f32_16x16x32_bf16 v[108:111], v[132:135], v[218:221], v[108:111]
	v_mfma_f32_16x16x32_bf16 v[104:107], v[140:143], v[218:221], v[104:107]
	v_mfma_f32_16x16x32_bf16 v[92:95], v[132:135], v[228:231], v[92:95]
	v_mfma_f32_16x16x32_bf16 v[88:91], v[140:143], v[228:231], v[88:91]
	v_mfma_f32_16x16x32_bf16 v[76:79], v[132:135], v[236:239], v[76:79]
	v_mfma_f32_16x16x32_bf16 v[72:75], v[140:143], v[236:239], v[72:75]
	s_setprio 0
	s_setprio 1
	v_mfma_f32_16x16x32_bf16 v[116:119], v[174:177], v[196:199], v[116:119]
	v_mfma_f32_16x16x32_bf16 v[112:115], v[188:191], v[196:199], v[112:115]
	v_mfma_f32_16x16x32_bf16 v[100:103], v[174:177], v[214:217], v[100:103]
	v_mfma_f32_16x16x32_bf16 v[96:99], v[188:191], v[214:217], v[96:99]
	v_mfma_f32_16x16x32_bf16 v[84:87], v[174:177], v[224:227], v[84:87]
	v_mfma_f32_16x16x32_bf16 v[80:83], v[188:191], v[224:227], v[80:83]
	v_mfma_f32_16x16x32_bf16 v[68:71], v[174:177], v[232:235], v[68:71]
	v_mfma_f32_16x16x32_bf16 v[64:67], v[188:191], v[232:235], v[64:67]
	v_mfma_f32_16x16x32_bf16 v[116:119], v[184:187], v[210:213], v[116:119]
	v_mfma_f32_16x16x32_bf16 v[112:115], v[192:195], v[210:213], v[112:115]
	v_mfma_f32_16x16x32_bf16 v[100:103], v[184:187], v[218:221], v[100:103]
	v_mfma_f32_16x16x32_bf16 v[96:99], v[192:195], v[218:221], v[96:99]
	v_mfma_f32_16x16x32_bf16 v[84:87], v[184:187], v[228:231], v[84:87]
	v_mfma_f32_16x16x32_bf16 v[80:83], v[192:195], v[228:231], v[80:83]
	v_mfma_f32_16x16x32_bf16 v[68:71], v[184:187], v[236:239], v[68:71]
	s_barrier
	v_mfma_f32_16x16x32_bf16 v[64:67], v[192:195], v[236:239], v[64:67]
	s_setprio 0
	s_add_i32 s62, s83, s8
	v_lshl_add_u64 v[178:179], v[178:179], 0, s[22:23]
	s_mov_b32 m0, s62
	ds_read_b128 v[196:199], v183 offset:49152
	ds_read_b128 v[210:213], v183 offset:50176
	ds_read_b128 v[214:217], v183 offset:51200
	ds_read_b128 v[218:221], v183 offset:52224
	ds_read_b128 v[224:227], v183 offset:53248
	ds_read_b128 v[228:231], v183 offset:54272
	ds_read_b128 v[232:235], v183 offset:55296
	ds_read_b128 v[236:239], v183 offset:56320
	global_load_lds_dwordx4 v[178:179], off
	s_add_i32 m0, s62, 0x2000
	s_add_u32 s44, s44, 0x20080
	v_lshl_add_u64 v[178:179], v[240:241], 0, s[22:23]
	s_addc_u32 s45, s45, 0
	s_add_i32 s62, s84, s8
	global_load_lds_dwordx4 v[178:179], off
	v_lshl_add_u64 v[178:179], s[44:45], 0, v[152:153]
	s_mov_b32 m0, s62
	s_nop 0
	global_load_lds_dwordx4 v[178:179], off
	v_lshl_add_u64 v[178:179], s[44:45], 0, v[144:145]
	s_add_i32 m0, s62, 0x2000
	s_nop 0
	global_load_lds_dwordx4 v[178:179], off
	v_lshl_add_u64 v[178:179], v[242:243], 0, s[22:23]
	s_mov_b32 m0, s69
	s_nop 0
	global_load_lds_dwordx4 v[178:179], off
	v_lshl_add_u64 v[178:179], v[244:245], 0, s[22:23]
	s_mov_b32 m0, s74
	s_nop 0
	global_load_lds_dwordx4 v[178:179], off
	s_waitcnt vmcnt(8)
	s_waitcnt lgkmcnt(0)
	s_barrier
	s_setprio 1
	s_waitcnt lgkmcnt(0)
	v_mfma_f32_16x16x32_bf16 v[60:63], v[128:131], v[196:199], v[60:63]
	v_mfma_f32_16x16x32_bf16 v[56:59], v[136:139], v[196:199], v[56:59]
	v_mfma_f32_16x16x32_bf16 v[44:47], v[128:131], v[214:217], v[44:47]
	v_mfma_f32_16x16x32_bf16 v[40:43], v[136:139], v[214:217], v[40:43]
	v_mfma_f32_16x16x32_bf16 v[28:31], v[128:131], v[224:227], v[28:31]
	v_mfma_f32_16x16x32_bf16 v[24:27], v[136:139], v[224:227], v[24:27]
	v_mfma_f32_16x16x32_bf16 v[12:15], v[128:131], v[232:235], v[12:15]
	v_mfma_f32_16x16x32_bf16 v[8:11], v[136:139], v[232:235], v[8:11]
	v_mfma_f32_16x16x32_bf16 v[60:63], v[132:135], v[210:213], v[60:63]
	v_mfma_f32_16x16x32_bf16 v[56:59], v[140:143], v[210:213], v[56:59]
	v_mfma_f32_16x16x32_bf16 v[44:47], v[132:135], v[218:221], v[44:47]
	v_mfma_f32_16x16x32_bf16 v[40:43], v[140:143], v[218:221], v[40:43]
	v_mfma_f32_16x16x32_bf16 v[28:31], v[132:135], v[228:231], v[28:31]
	v_mfma_f32_16x16x32_bf16 v[24:27], v[140:143], v[228:231], v[24:27]
	v_mfma_f32_16x16x32_bf16 v[12:15], v[132:135], v[236:239], v[12:15]
	v_mfma_f32_16x16x32_bf16 v[8:11], v[140:143], v[236:239], v[8:11]
	s_setprio 0
	s_setprio 1
	v_mfma_f32_16x16x32_bf16 v[52:55], v[174:177], v[196:199], v[52:55]
	v_mfma_f32_16x16x32_bf16 v[48:51], v[188:191], v[196:199], v[48:51]
	v_mfma_f32_16x16x32_bf16 v[36:39], v[174:177], v[214:217], v[36:39]
	v_mfma_f32_16x16x32_bf16 v[32:35], v[188:191], v[214:217], v[32:35]
	v_mfma_f32_16x16x32_bf16 v[20:23], v[174:177], v[224:227], v[20:23]
	v_mfma_f32_16x16x32_bf16 v[16:19], v[188:191], v[224:227], v[16:19]
	v_mfma_f32_16x16x32_bf16 v[4:7], v[174:177], v[232:235], v[4:7]
	v_mfma_f32_16x16x32_bf16 v[0:3], v[188:191], v[232:235], v[0:3]
	v_mfma_f32_16x16x32_bf16 v[52:55], v[184:187], v[210:213], v[52:55]
	v_mfma_f32_16x16x32_bf16 v[48:51], v[192:195], v[210:213], v[48:51]
	v_mfma_f32_16x16x32_bf16 v[36:39], v[184:187], v[218:221], v[36:39]
	v_mfma_f32_16x16x32_bf16 v[32:35], v[192:195], v[218:221], v[32:35]
	v_mfma_f32_16x16x32_bf16 v[20:23], v[184:187], v[228:231], v[20:23]
	v_mfma_f32_16x16x32_bf16 v[16:19], v[192:195], v[228:231], v[16:19]
	v_mfma_f32_16x16x32_bf16 v[4:7], v[184:187], v[236:239], v[4:7]
	s_barrier
	v_mfma_f32_16x16x32_bf16 v[0:3], v[192:195], v[236:239], v[0:3]
	s_setprio 0
	s_add_i32 s82, s82, 2
	s_add_u32 s80, s80, 0x100
	s_addc_u32 s81, s81, 0
	s_add_u32 s60, s60, 0x100
	s_addc_u32 s61, s61, 0
	s_cmp_gt_u32 s82, 5
.LBB0_725:
	s_add_u32 s44, s60, 0xfffe0080
	s_addc_u32 s45, s61, -1
	s_add_i32 s83, 0, 0x10000
	s_cmp_eq_u32 s82, 4
	s_cselect_b32 s63, s21, s45
	s_cselect_b32 s62, s78, s44
	s_cselect_b32 s45, s19, s81
	s_cselect_b32 s44, s79, s80
	s_add_i32 s86, 0, 0x14000
	v_add_u32_e32 v140, s83, v181
	v_add_u32_e32 v178, s86, v181
	ds_read_b128 v[128:131], v140
	ds_read_b128 v[132:135], v140 offset:1024
	ds_read_b128 v[136:139], v140 offset:2048
	ds_read_b128 v[140:143], v140 offset:3072
	ds_read_b128 v[174:177], v178
	ds_read_b128 v[184:187], v178 offset:1024
	ds_read_b128 v[188:191], v178 offset:2048
	ds_read_b128 v[192:195], v178 offset:3072
	v_lshl_add_u64 v[178:179], s[60:61], 0, v[172:173]
	s_add_i32 m0, s59, 0xc000
	ds_read_b128 v[196:199], v183
	ds_read_b128 v[210:213], v183 offset:1024
	ds_read_b128 v[214:217], v183 offset:2048
	ds_read_b128 v[218:221], v183 offset:3072
	ds_read_b128 v[224:227], v183 offset:4096
	ds_read_b128 v[228:231], v183 offset:5120
	ds_read_b128 v[232:235], v183 offset:6144
	ds_read_b128 v[236:239], v183 offset:7168
	global_load_lds_dwordx4 v[178:179], off
	v_lshl_add_u64 v[178:179], s[60:61], 0, v[150:151]
	s_add_i32 m0, s59, 0xe000
	s_nop 0
	global_load_lds_dwordx4 v[178:179], off
	s_waitcnt vmcnt(8)
	s_waitcnt lgkmcnt(0)
	s_barrier
	s_setprio 1
	s_waitcnt lgkmcnt(0)
	v_mfma_f32_16x16x32_bf16 v[124:127], v[128:131], v[196:199], v[124:127]
	v_mfma_f32_16x16x32_bf16 v[120:123], v[136:139], v[196:199], v[120:123]
	v_mfma_f32_16x16x32_bf16 v[108:111], v[128:131], v[214:217], v[108:111]
	v_mfma_f32_16x16x32_bf16 v[104:107], v[136:139], v[214:217], v[104:107]
	v_mfma_f32_16x16x32_bf16 v[92:95], v[128:131], v[224:227], v[92:95]
	v_mfma_f32_16x16x32_bf16 v[88:91], v[136:139], v[224:227], v[88:91]
	v_mfma_f32_16x16x32_bf16 v[76:79], v[128:131], v[232:235], v[76:79]
	v_mfma_f32_16x16x32_bf16 v[72:75], v[136:139], v[232:235], v[72:75]
	v_mfma_f32_16x16x32_bf16 v[124:127], v[132:135], v[210:213], v[124:127]
	v_mfma_f32_16x16x32_bf16 v[120:123], v[140:143], v[210:213], v[120:123]
	v_mfma_f32_16x16x32_bf16 v[108:111], v[132:135], v[218:221], v[108:111]
	v_mfma_f32_16x16x32_bf16 v[104:107], v[140:143], v[218:221], v[104:107]
	v_mfma_f32_16x16x32_bf16 v[92:95], v[132:135], v[228:231], v[92:95]
	v_mfma_f32_16x16x32_bf16 v[88:91], v[140:143], v[228:231], v[88:91]
	v_mfma_f32_16x16x32_bf16 v[76:79], v[132:135], v[236:239], v[76:79]
	v_mfma_f32_16x16x32_bf16 v[72:75], v[140:143], v[236:239], v[72:75]
	s_setprio 0
	s_setprio 1
	v_mfma_f32_16x16x32_bf16 v[116:119], v[174:177], v[196:199], v[116:119]
	v_mfma_f32_16x16x32_bf16 v[112:115], v[188:191], v[196:199], v[112:115]
	v_mfma_f32_16x16x32_bf16 v[100:103], v[174:177], v[214:217], v[100:103]
	v_mfma_f32_16x16x32_bf16 v[96:99], v[188:191], v[214:217], v[96:99]
	v_mfma_f32_16x16x32_bf16 v[84:87], v[174:177], v[224:227], v[84:87]
	v_mfma_f32_16x16x32_bf16 v[80:83], v[188:191], v[224:227], v[80:83]
	v_mfma_f32_16x16x32_bf16 v[68:71], v[174:177], v[232:235], v[68:71]
	v_mfma_f32_16x16x32_bf16 v[64:67], v[188:191], v[232:235], v[64:67]
	v_mfma_f32_16x16x32_bf16 v[116:119], v[184:187], v[210:213], v[116:119]
	v_mfma_f32_16x16x32_bf16 v[112:115], v[192:195], v[210:213], v[112:115]
	v_mfma_f32_16x16x32_bf16 v[100:103], v[184:187], v[218:221], v[100:103]
	v_mfma_f32_16x16x32_bf16 v[96:99], v[192:195], v[218:221], v[96:99]
	v_mfma_f32_16x16x32_bf16 v[84:87], v[184:187], v[228:231], v[84:87]
	v_mfma_f32_16x16x32_bf16 v[80:83], v[192:195], v[228:231], v[80:83]
	v_mfma_f32_16x16x32_bf16 v[68:71], v[184:187], v[236:239], v[68:71]
	s_barrier
	v_mfma_f32_16x16x32_bf16 v[64:67], v[192:195], v[236:239], v[64:67]
	s_setprio 0
	s_add_i32 s83, s83, s8
	v_lshl_add_u64 v[178:179], s[44:45], 0, v[152:153]
	s_mov_b32 m0, s83
	ds_read_b128 v[196:199], v183 offset:16384
	ds_read_b128 v[210:213], v183 offset:17408
	ds_read_b128 v[214:217], v183 offset:18432
	ds_read_b128 v[218:221], v183 offset:19456
	ds_read_b128 v[224:227], v183 offset:20480
	ds_read_b128 v[228:231], v183 offset:21504
	ds_read_b128 v[232:235], v183 offset:22528
	ds_read_b128 v[236:239], v183 offset:23552
	global_load_lds_dwordx4 v[178:179], off
	s_add_i32 m0, s83, 0x2000
	s_add_u32 s84, s44, 0x20000
	v_lshl_add_u64 v[240:241], s[44:45], 0, v[144:145]
	s_addc_u32 s85, s45, 0
	s_add_i32 s83, s86, s8
	global_load_lds_dwordx4 v[240:241], off
	v_lshl_add_u64 v[242:243], s[84:85], 0, v[152:153]
	s_mov_b32 m0, s83
	v_lshl_add_u64 v[244:245], s[62:63], 0, v[146:147]
	global_load_lds_dwordx4 v[242:243], off
	v_lshl_add_u64 v[242:243], s[84:85], 0, v[144:145]
	s_add_i32 m0, s83, 0x2000
	s_nop 0
	global_load_lds_dwordx4 v[242:243], off
	v_lshl_add_u64 v[242:243], s[62:63], 0, v[148:149]
	s_mov_b32 m0, s59
	s_nop 0
	global_load_lds_dwordx4 v[242:243], off
	s_mov_b32 m0, s66
	s_nop 0
	global_load_lds_dwordx4 v[244:245], off
	s_waitcnt vmcnt(8)
	s_waitcnt lgkmcnt(0)
	s_barrier
	s_setprio 1
	s_waitcnt lgkmcnt(0)
	v_mfma_f32_16x16x32_bf16 v[60:63], v[128:131], v[196:199], v[60:63]
	v_mfma_f32_16x16x32_bf16 v[56:59], v[136:139], v[196:199], v[56:59]
	v_mfma_f32_16x16x32_bf16 v[44:47], v[128:131], v[214:217], v[44:47]
	v_mfma_f32_16x16x32_bf16 v[40:43], v[136:139], v[214:217], v[40:43]
	v_mfma_f32_16x16x32_bf16 v[28:31], v[128:131], v[224:227], v[28:31]
	v_mfma_f32_16x16x32_bf16 v[24:27], v[136:139], v[224:227], v[24:27]
	v_mfma_f32_16x16x32_bf16 v[12:15], v[128:131], v[232:235], v[12:15]
	v_mfma_f32_16x16x32_bf16 v[8:11], v[136:139], v[232:235], v[8:11]
	v_mfma_f32_16x16x32_bf16 v[60:63], v[132:135], v[210:213], v[60:63]
	v_mfma_f32_16x16x32_bf16 v[56:59], v[140:143], v[210:213], v[56:59]
	v_mfma_f32_16x16x32_bf16 v[44:47], v[132:135], v[218:221], v[44:47]
	v_mfma_f32_16x16x32_bf16 v[40:43], v[140:143], v[218:221], v[40:43]
	v_mfma_f32_16x16x32_bf16 v[28:31], v[132:135], v[228:231], v[28:31]
	v_mfma_f32_16x16x32_bf16 v[24:27], v[140:143], v[228:231], v[24:27]
	v_mfma_f32_16x16x32_bf16 v[12:15], v[132:135], v[236:239], v[12:15]
	v_mfma_f32_16x16x32_bf16 v[8:11], v[140:143], v[236:239], v[8:11]
	s_setprio 0
	s_setprio 1
	v_mfma_f32_16x16x32_bf16 v[52:55], v[174:177], v[196:199], v[52:55]
	v_mfma_f32_16x16x32_bf16 v[48:51], v[188:191], v[196:199], v[48:51]
	v_mfma_f32_16x16x32_bf16 v[36:39], v[174:177], v[214:217], v[36:39]
	v_mfma_f32_16x16x32_bf16 v[32:35], v[188:191], v[214:217], v[32:35]
	v_mfma_f32_16x16x32_bf16 v[20:23], v[174:177], v[224:227], v[20:23]
	v_mfma_f32_16x16x32_bf16 v[16:19], v[188:191], v[224:227], v[16:19]
	v_mfma_f32_16x16x32_bf16 v[4:7], v[174:177], v[232:235], v[4:7]
	v_mfma_f32_16x16x32_bf16 v[0:3], v[188:191], v[232:235], v[0:3]
	v_mfma_f32_16x16x32_bf16 v[52:55], v[184:187], v[210:213], v[52:55]
	v_mfma_f32_16x16x32_bf16 v[48:51], v[192:195], v[210:213], v[48:51]
	v_mfma_f32_16x16x32_bf16 v[36:39], v[184:187], v[218:221], v[36:39]
	v_mfma_f32_16x16x32_bf16 v[32:35], v[192:195], v[218:221], v[32:35]
	v_mfma_f32_16x16x32_bf16 v[20:23], v[184:187], v[228:231], v[20:23]
	v_mfma_f32_16x16x32_bf16 v[16:19], v[192:195], v[228:231], v[16:19]
	v_mfma_f32_16x16x32_bf16 v[4:7], v[184:187], v[236:239], v[4:7]
	s_barrier
	v_mfma_f32_16x16x32_bf16 v[0:3], v[192:195], v[236:239], v[0:3]
	s_setprio 0
	s_add_i32 s83, 0, 0x18000
	s_add_i32 s84, 0, 0x1c000
	v_add_u32_e32 v140, s83, v181
	v_add_u32_e32 v192, s84, v181
	ds_read_b128 v[128:131], v140
	ds_read_b128 v[132:135], v140 offset:1024
	ds_read_b128 v[136:139], v140 offset:2048
	ds_read_b128 v[140:143], v140 offset:3072
	ds_read_b128 v[174:177], v192
	ds_read_b128 v[184:187], v192 offset:1024
	ds_read_b128 v[188:191], v192 offset:2048
	ds_read_b128 v[192:195], v192 offset:3072
	s_add_u32 s62, s62, 0x20000
	s_addc_u32 s63, s63, 0
	s_mov_b32 m0, s67
	v_lshl_add_u64 v[246:247], s[62:63], 0, v[148:149]
	ds_read_b128 v[196:199], v183 offset:32768
	ds_read_b128 v[210:213], v183 offset:33792
	ds_read_b128 v[214:217], v183 offset:34816
	ds_read_b128 v[218:221], v183 offset:35840
	ds_read_b128 v[224:227], v183 offset:36864
	ds_read_b128 v[228:231], v183 offset:37888
	ds_read_b128 v[232:235], v183 offset:38912
	ds_read_b128 v[236:239], v183 offset:39936
	global_load_lds_dwordx4 v[246:247], off
	v_lshl_add_u64 v[246:247], s[62:63], 0, v[146:147]
	s_mov_b32 m0, s68
	s_nop 0
	global_load_lds_dwordx4 v[246:247], off
	s_waitcnt vmcnt(8)
	s_waitcnt lgkmcnt(0)
	s_barrier
	s_setprio 1
	s_waitcnt lgkmcnt(0)
	v_mfma_f32_16x16x32_bf16 v[124:127], v[128:131], v[196:199], v[124:127]
	v_mfma_f32_16x16x32_bf16 v[120:123], v[136:139], v[196:199], v[120:123]
	v_mfma_f32_16x16x32_bf16 v[108:111], v[128:131], v[214:217], v[108:111]
	v_mfma_f32_16x16x32_bf16 v[104:107], v[136:139], v[214:217], v[104:107]
	v_mfma_f32_16x16x32_bf16 v[92:95], v[128:131], v[224:227], v[92:95]
	v_mfma_f32_16x16x32_bf16 v[88:91], v[136:139], v[224:227], v[88:91]
	v_mfma_f32_16x16x32_bf16 v[76:79], v[128:131], v[232:235], v[76:79]
	v_mfma_f32_16x16x32_bf16 v[72:75], v[136:139], v[232:235], v[72:75]
	v_mfma_f32_16x16x32_bf16 v[124:127], v[132:135], v[210:213], v[124:127]
	v_mfma_f32_16x16x32_bf16 v[120:123], v[140:143], v[210:213], v[120:123]
	v_mfma_f32_16x16x32_bf16 v[108:111], v[132:135], v[218:221], v[108:111]
	v_mfma_f32_16x16x32_bf16 v[104:107], v[140:143], v[218:221], v[104:107]
	v_mfma_f32_16x16x32_bf16 v[92:95], v[132:135], v[228:231], v[92:95]
	v_mfma_f32_16x16x32_bf16 v[88:91], v[140:143], v[228:231], v[88:91]
	v_mfma_f32_16x16x32_bf16 v[76:79], v[132:135], v[236:239], v[76:79]
	v_mfma_f32_16x16x32_bf16 v[72:75], v[140:143], v[236:239], v[72:75]
	s_setprio 0
	s_setprio 1
	v_mfma_f32_16x16x32_bf16 v[116:119], v[174:177], v[196:199], v[116:119]
	v_mfma_f32_16x16x32_bf16 v[112:115], v[188:191], v[196:199], v[112:115]
	v_mfma_f32_16x16x32_bf16 v[100:103], v[174:177], v[214:217], v[100:103]
	v_mfma_f32_16x16x32_bf16 v[96:99], v[188:191], v[214:217], v[96:99]
	v_mfma_f32_16x16x32_bf16 v[84:87], v[174:177], v[224:227], v[84:87]
	v_mfma_f32_16x16x32_bf16 v[80:83], v[188:191], v[224:227], v[80:83]
	v_mfma_f32_16x16x32_bf16 v[68:71], v[174:177], v[232:235], v[68:71]
	v_mfma_f32_16x16x32_bf16 v[64:67], v[188:191], v[232:235], v[64:67]
	v_mfma_f32_16x16x32_bf16 v[116:119], v[184:187], v[210:213], v[116:119]
	v_mfma_f32_16x16x32_bf16 v[112:115], v[192:195], v[210:213], v[112:115]
	v_mfma_f32_16x16x32_bf16 v[100:103], v[184:187], v[218:221], v[100:103]
	v_mfma_f32_16x16x32_bf16 v[96:99], v[192:195], v[218:221], v[96:99]
	v_mfma_f32_16x16x32_bf16 v[84:87], v[184:187], v[228:231], v[84:87]
	v_mfma_f32_16x16x32_bf16 v[80:83], v[192:195], v[228:231], v[80:83]
	v_mfma_f32_16x16x32_bf16 v[68:71], v[184:187], v[236:239], v[68:71]
	s_barrier
	v_mfma_f32_16x16x32_bf16 v[64:67], v[192:195], v[236:239], v[64:67]
	s_setprio 0
	s_add_i32 s62, s83, s8
	v_lshl_add_u64 v[178:179], v[178:179], 0, s[22:23]
	s_mov_b32 m0, s62
	ds_read_b128 v[196:199], v183 offset:49152
	ds_read_b128 v[210:213], v183 offset:50176
	ds_read_b128 v[214:217], v183 offset:51200
	ds_read_b128 v[218:221], v183 offset:52224
	ds_read_b128 v[224:227], v183 offset:53248
	ds_read_b128 v[228:231], v183 offset:54272
	ds_read_b128 v[232:235], v183 offset:55296
	ds_read_b128 v[236:239], v183 offset:56320
	global_load_lds_dwordx4 v[178:179], off
	s_add_i32 m0, s62, 0x2000
	s_add_u32 s44, s44, 0x20080
	v_lshl_add_u64 v[178:179], v[240:241], 0, s[22:23]
	s_addc_u32 s45, s45, 0
	s_add_i32 s62, s84, s8
	global_load_lds_dwordx4 v[178:179], off
	v_lshl_add_u64 v[178:179], s[44:45], 0, v[152:153]
	s_mov_b32 m0, s62
	s_nop 0
	global_load_lds_dwordx4 v[178:179], off
	v_lshl_add_u64 v[178:179], s[44:45], 0, v[144:145]
	s_add_i32 m0, s62, 0x2000
	s_nop 0
	global_load_lds_dwordx4 v[178:179], off
	v_lshl_add_u64 v[178:179], v[242:243], 0, s[22:23]
	s_mov_b32 m0, s69
	s_nop 0
	global_load_lds_dwordx4 v[178:179], off
	v_lshl_add_u64 v[178:179], v[244:245], 0, s[22:23]
	s_mov_b32 m0, s74
	s_nop 0
	global_load_lds_dwordx4 v[178:179], off
	s_waitcnt vmcnt(8)
	s_waitcnt lgkmcnt(0)
	s_barrier
	s_setprio 1
	s_waitcnt lgkmcnt(0)
	v_mfma_f32_16x16x32_bf16 v[60:63], v[128:131], v[196:199], v[60:63]
	v_mfma_f32_16x16x32_bf16 v[56:59], v[136:139], v[196:199], v[56:59]
	v_mfma_f32_16x16x32_bf16 v[44:47], v[128:131], v[214:217], v[44:47]
	v_mfma_f32_16x16x32_bf16 v[40:43], v[136:139], v[214:217], v[40:43]
	v_mfma_f32_16x16x32_bf16 v[28:31], v[128:131], v[224:227], v[28:31]
	v_mfma_f32_16x16x32_bf16 v[24:27], v[136:139], v[224:227], v[24:27]
	v_mfma_f32_16x16x32_bf16 v[12:15], v[128:131], v[232:235], v[12:15]
	v_mfma_f32_16x16x32_bf16 v[8:11], v[136:139], v[232:235], v[8:11]
	v_mfma_f32_16x16x32_bf16 v[60:63], v[132:135], v[210:213], v[60:63]
	v_mfma_f32_16x16x32_bf16 v[56:59], v[140:143], v[210:213], v[56:59]
	v_mfma_f32_16x16x32_bf16 v[44:47], v[132:135], v[218:221], v[44:47]
	v_mfma_f32_16x16x32_bf16 v[40:43], v[140:143], v[218:221], v[40:43]
	v_mfma_f32_16x16x32_bf16 v[28:31], v[132:135], v[228:231], v[28:31]
	v_mfma_f32_16x16x32_bf16 v[24:27], v[140:143], v[228:231], v[24:27]
	v_mfma_f32_16x16x32_bf16 v[12:15], v[132:135], v[236:239], v[12:15]
	v_mfma_f32_16x16x32_bf16 v[8:11], v[140:143], v[236:239], v[8:11]
	s_setprio 0
	s_setprio 1
	v_mfma_f32_16x16x32_bf16 v[52:55], v[174:177], v[196:199], v[52:55]
	v_mfma_f32_16x16x32_bf16 v[48:51], v[188:191], v[196:199], v[48:51]
	v_mfma_f32_16x16x32_bf16 v[36:39], v[174:177], v[214:217], v[36:39]
	v_mfma_f32_16x16x32_bf16 v[32:35], v[188:191], v[214:217], v[32:35]
	v_mfma_f32_16x16x32_bf16 v[20:23], v[174:177], v[224:227], v[20:23]
	v_mfma_f32_16x16x32_bf16 v[16:19], v[188:191], v[224:227], v[16:19]
	v_mfma_f32_16x16x32_bf16 v[4:7], v[174:177], v[232:235], v[4:7]
	v_mfma_f32_16x16x32_bf16 v[0:3], v[188:191], v[232:235], v[0:3]
	v_mfma_f32_16x16x32_bf16 v[52:55], v[184:187], v[210:213], v[52:55]
	v_mfma_f32_16x16x32_bf16 v[48:51], v[192:195], v[210:213], v[48:51]
	v_mfma_f32_16x16x32_bf16 v[36:39], v[184:187], v[218:221], v[36:39]
	v_mfma_f32_16x16x32_bf16 v[32:35], v[192:195], v[218:221], v[32:35]
	v_mfma_f32_16x16x32_bf16 v[20:23], v[184:187], v[228:231], v[20:23]
	v_mfma_f32_16x16x32_bf16 v[16:19], v[192:195], v[228:231], v[16:19]
	v_mfma_f32_16x16x32_bf16 v[4:7], v[184:187], v[236:239], v[4:7]
	s_barrier
	v_mfma_f32_16x16x32_bf16 v[0:3], v[192:195], v[236:239], v[0:3]
	s_setprio 0
	s_add_i32 s82, s82, 2
	s_add_u32 s80, s80, 0x100
	s_addc_u32 s81, s81, 0
	s_add_u32 s60, s60, 0x100
	s_addc_u32 s61, s61, 0
	s_cmp_gt_u32 s82, 5
	s_cbranch_scc0 .LBB0_725
	s_and_b64 vcc, exec, s[16:17]
	s_cbranch_vccz .LBB0_728
	s_barrier

.LBB0_821:
	s_ashr_i32 s21, s20, 31
	s_lshl_b64 s[48:49], s[20:21], 19
	s_add_u32 s48, s70, s48
	s_addc_u32 s49, s71, s49
	s_and_b64 s[50:51], s[46:47], exec
	s_cselect_b32 s21, s49, s61
	s_cselect_b32 s81, s48, s60
	s_ashr_i32 s19, s18, 31
	s_lshl_b64 s[50:51], s[18:19], 19
	v_readlane_b32 s19, v254, 54
	s_add_u32 s50, s19, s50
	v_readlane_b32 s19, v254, 55
	s_addc_u32 s51, s19, s51
	s_and_b64 s[66:67], s[46:47], exec
	s_cselect_b32 s19, s51, s63
	s_cselect_b32 s82, s50, s62
	s_add_u32 s83, s62, 0x100
	s_addc_u32 s84, s63, 0
	s_add_u32 s60, s60, 0x40080
	s_addc_u32 s61, s61, 0
	s_mov_b32 s85, -2
	s_waitcnt lgkmcnt(0)
	s_add_u32 s62, s60, 0xfffc0080
	s_addc_u32 s63, s61, -1
	s_add_i32 s86, 0, 0x10000
	s_cmp_eq_u32 s85, 12
	s_cselect_b32 s67, s21, s63
	s_cselect_b32 s66, s81, s62
	s_cselect_b32 s63, s19, s84
	s_cselect_b32 s62, s82, s83
	s_add_i32 s89, 0, 0x14000
	v_add_u32_e32 v124, s86, v210
	v_add_u32_e32 v186, s89, v210
	ds_read_b128 v[112:115], v124
	ds_read_b128 v[116:119], v124 offset:1024
	ds_read_b128 v[120:123], v124 offset:2048
	ds_read_b128 v[124:127], v124 offset:3072
	ds_read_b128 v[132:135], v186
	ds_read_b128 v[140:143], v186 offset:1024
	ds_read_b128 v[182:185], v186 offset:2048
	ds_read_b128 v[186:189], v186 offset:3072
	v_lshl_add_u64 v[198:199], s[60:61], 0, v[180:181]
	s_add_i32 m0, s68, 0xc000
	ds_read_b128 v[190:193], v212
	ds_read_b128 v[194:197], v212 offset:1024
	ds_read_b128 v[214:217], v212 offset:2048
	ds_read_b128 v[218:221], v212 offset:3072
	ds_read_b128 v[224:227], v212 offset:4096
	ds_read_b128 v[228:231], v212 offset:5120
	ds_read_b128 v[232:235], v212 offset:6144
	ds_read_b128 v[236:239], v212 offset:7168
	global_load_lds_dwordx4 v[198:199], off
	v_lshl_add_u64 v[198:199], s[60:61], 0, v[178:179]
	s_add_i32 m0, s68, 0xe000
	s_nop 0
	global_load_lds_dwordx4 v[198:199], off
	s_waitcnt vmcnt(8)
	s_waitcnt lgkmcnt(0)
	s_barrier
	s_setprio 1
	s_waitcnt lgkmcnt(0)
	v_mfma_f32_16x16x32_bf16 v[148:151], v[112:115], v[190:193], 0
	v_mfma_f32_16x16x32_bf16 v[144:147], v[120:123], v[190:193], 0
	v_mfma_f32_16x16x32_bf16 v[108:111], v[112:115], v[214:217], 0
	v_mfma_f32_16x16x32_bf16 v[104:107], v[120:123], v[214:217], 0
	v_mfma_f32_16x16x32_bf16 v[92:95], v[112:115], v[224:227], 0
	v_mfma_f32_16x16x32_bf16 v[88:91], v[120:123], v[224:227], 0
	v_mfma_f32_16x16x32_bf16 v[76:79], v[112:115], v[232:235], 0
	v_mfma_f32_16x16x32_bf16 v[72:75], v[120:123], v[232:235], 0
	v_mfma_f32_16x16x32_bf16 v[148:151], v[116:119], v[194:197], v[148:151]
	v_mfma_f32_16x16x32_bf16 v[144:147], v[124:127], v[194:197], v[144:147]
	v_mfma_f32_16x16x32_bf16 v[108:111], v[116:119], v[218:221], v[108:111]
	v_mfma_f32_16x16x32_bf16 v[104:107], v[124:127], v[218:221], v[104:107]
	v_mfma_f32_16x16x32_bf16 v[92:95], v[116:119], v[228:231], v[92:95]
	v_mfma_f32_16x16x32_bf16 v[88:91], v[124:127], v[228:231], v[88:91]
	v_mfma_f32_16x16x32_bf16 v[76:79], v[116:119], v[236:239], v[76:79]
	v_mfma_f32_16x16x32_bf16 v[72:75], v[124:127], v[236:239], v[72:75]
	s_setprio 0
	s_setprio 1
	v_mfma_f32_16x16x32_bf16 v[136:139], v[132:135], v[190:193], 0
	v_mfma_f32_16x16x32_bf16 v[128:131], v[182:185], v[190:193], 0
	v_mfma_f32_16x16x32_bf16 v[100:103], v[132:135], v[214:217], 0
	v_mfma_f32_16x16x32_bf16 v[96:99], v[182:185], v[214:217], 0
	v_mfma_f32_16x16x32_bf16 v[84:87], v[132:135], v[224:227], 0
	v_mfma_f32_16x16x32_bf16 v[80:83], v[182:185], v[224:227], 0
	v_mfma_f32_16x16x32_bf16 v[68:71], v[132:135], v[232:235], 0
	v_mfma_f32_16x16x32_bf16 v[64:67], v[182:185], v[232:235], 0
	v_mfma_f32_16x16x32_bf16 v[136:139], v[140:143], v[194:197], v[136:139]
	v_mfma_f32_16x16x32_bf16 v[128:131], v[186:189], v[194:197], v[128:131]
	v_mfma_f32_16x16x32_bf16 v[100:103], v[140:143], v[218:221], v[100:103]
	v_mfma_f32_16x16x32_bf16 v[96:99], v[186:189], v[218:221], v[96:99]
	v_mfma_f32_16x16x32_bf16 v[84:87], v[140:143], v[228:231], v[84:87]
	v_mfma_f32_16x16x32_bf16 v[80:83], v[186:189], v[228:231], v[80:83]
	v_mfma_f32_16x16x32_bf16 v[68:71], v[140:143], v[236:239], v[68:71]
	s_barrier
	v_mfma_f32_16x16x32_bf16 v[64:67], v[186:189], v[236:239], v[64:67]
	s_setprio 0
	s_add_i32 s86, s86, s59
	v_lshl_add_u64 v[198:199], s[62:63], 0, v[152:153]
	s_mov_b32 m0, s86
	ds_read_b128 v[190:193], v212 offset:16384
	ds_read_b128 v[194:197], v212 offset:17408
	ds_read_b128 v[214:217], v212 offset:18432
	ds_read_b128 v[218:221], v212 offset:19456
	ds_read_b128 v[224:227], v212 offset:20480
	ds_read_b128 v[228:231], v212 offset:21504
	ds_read_b128 v[232:235], v212 offset:22528
	ds_read_b128 v[236:239], v212 offset:23552
	global_load_lds_dwordx4 v[198:199], off
	s_add_i32 m0, s86, 0x2000
	s_add_u32 s86, s62, 0x40000
	v_lshl_add_u64 v[240:241], s[62:63], 0, v[172:173]
	s_addc_u32 s87, s63, 0
	s_add_i32 s89, s89, s59
	global_load_lds_dwordx4 v[240:241], off
	v_lshl_add_u64 v[242:243], s[86:87], 0, v[152:153]
	s_mov_b32 m0, s89
	v_lshl_add_u64 v[244:245], s[66:67], 0, v[174:175]
	global_load_lds_dwordx4 v[242:243], off
	v_lshl_add_u64 v[242:243], s[86:87], 0, v[172:173]
	s_add_i32 m0, s89, 0x2000
	s_nop 0
	global_load_lds_dwordx4 v[242:243], off
	v_lshl_add_u64 v[242:243], s[66:67], 0, v[176:177]
	s_mov_b32 m0, s68
	s_nop 0
	global_load_lds_dwordx4 v[242:243], off
	s_mov_b32 m0, s69
	s_nop 0
	global_load_lds_dwordx4 v[244:245], off
	s_waitcnt vmcnt(8)
	s_waitcnt lgkmcnt(0)
	s_barrier
	s_setprio 1
	s_waitcnt lgkmcnt(0)
	v_mfma_f32_16x16x32_bf16 v[60:63], v[112:115], v[190:193], 0
	v_mfma_f32_16x16x32_bf16 v[56:59], v[120:123], v[190:193], 0
	v_mfma_f32_16x16x32_bf16 v[44:47], v[112:115], v[214:217], 0
	v_mfma_f32_16x16x32_bf16 v[40:43], v[120:123], v[214:217], 0
	v_mfma_f32_16x16x32_bf16 v[28:31], v[112:115], v[224:227], 0
	v_mfma_f32_16x16x32_bf16 v[24:27], v[120:123], v[224:227], 0
	v_mfma_f32_16x16x32_bf16 v[12:15], v[112:115], v[232:235], 0
	v_mfma_f32_16x16x32_bf16 v[8:11], v[120:123], v[232:235], 0
	v_mfma_f32_16x16x32_bf16 v[60:63], v[116:119], v[194:197], v[60:63]
	v_mfma_f32_16x16x32_bf16 v[56:59], v[124:127], v[194:197], v[56:59]
	v_mfma_f32_16x16x32_bf16 v[44:47], v[116:119], v[218:221], v[44:47]
	v_mfma_f32_16x16x32_bf16 v[40:43], v[124:127], v[218:221], v[40:43]
	v_mfma_f32_16x16x32_bf16 v[28:31], v[116:119], v[228:231], v[28:31]
	v_mfma_f32_16x16x32_bf16 v[24:27], v[124:127], v[228:231], v[24:27]
	v_mfma_f32_16x16x32_bf16 v[12:15], v[116:119], v[236:239], v[12:15]
	v_mfma_f32_16x16x32_bf16 v[8:11], v[124:127], v[236:239], v[8:11]
	s_setprio 0
	s_setprio 1
	v_mfma_f32_16x16x32_bf16 v[52:55], v[132:135], v[190:193], 0
	v_mfma_f32_16x16x32_bf16 v[48:51], v[182:185], v[190:193], 0
	v_mfma_f32_16x16x32_bf16 v[36:39], v[132:135], v[214:217], 0
	v_mfma_f32_16x16x32_bf16 v[32:35], v[182:185], v[214:217], 0
	v_mfma_f32_16x16x32_bf16 v[20:23], v[132:135], v[224:227], 0
	v_mfma_f32_16x16x32_bf16 v[16:19], v[182:185], v[224:227], 0
	v_mfma_f32_16x16x32_bf16 v[4:7], v[132:135], v[232:235], 0
	v_mfma_f32_16x16x32_bf16 v[0:3], v[182:185], v[232:235], 0
	v_mfma_f32_16x16x32_bf16 v[52:55], v[140:143], v[194:197], v[52:55]
	v_mfma_f32_16x16x32_bf16 v[48:51], v[186:189], v[194:197], v[48:51]
	v_mfma_f32_16x16x32_bf16 v[36:39], v[140:143], v[218:221], v[36:39]
	v_mfma_f32_16x16x32_bf16 v[32:35], v[186:189], v[218:221], v[32:35]
	v_mfma_f32_16x16x32_bf16 v[20:23], v[140:143], v[228:231], v[20:23]
	v_mfma_f32_16x16x32_bf16 v[16:19], v[186:189], v[228:231], v[16:19]
	v_mfma_f32_16x16x32_bf16 v[4:7], v[140:143], v[236:239], v[4:7]
	s_barrier
	v_mfma_f32_16x16x32_bf16 v[0:3], v[186:189], v[236:239], v[0:3]
	s_setprio 0
	s_add_i32 s86, 0, 0x18000
	s_add_i32 s87, 0, 0x1c000
	v_add_u32_e32 v124, s86, v210
	v_add_u32_e32 v186, s87, v210
	ds_read_b128 v[112:115], v124
	ds_read_b128 v[116:119], v124 offset:1024
	ds_read_b128 v[120:123], v124 offset:2048
	ds_read_b128 v[124:127], v124 offset:3072
	ds_read_b128 v[132:135], v186
	ds_read_b128 v[140:143], v186 offset:1024
	ds_read_b128 v[182:185], v186 offset:2048
	ds_read_b128 v[186:189], v186 offset:3072
	s_add_u32 s66, s66, 0x40000
	s_addc_u32 s67, s67, 0
	s_mov_b32 m0, s74
	v_lshl_add_u64 v[246:247], s[66:67], 0, v[176:177]
	ds_read_b128 v[190:193], v212 offset:32768
	ds_read_b128 v[194:197], v212 offset:33792
	ds_read_b128 v[214:217], v212 offset:34816
	ds_read_b128 v[218:221], v212 offset:35840
	ds_read_b128 v[224:227], v212 offset:36864
	ds_read_b128 v[228:231], v212 offset:37888
	ds_read_b128 v[232:235], v212 offset:38912
	ds_read_b128 v[236:239], v212 offset:39936
	global_load_lds_dwordx4 v[246:247], off
	v_lshl_add_u64 v[246:247], s[66:67], 0, v[174:175]
	s_mov_b32 m0, s75
	s_nop 0
	global_load_lds_dwordx4 v[246:247], off
	s_waitcnt vmcnt(8)
	s_waitcnt lgkmcnt(0)
	s_barrier
	s_setprio 1
	s_waitcnt lgkmcnt(0)
	v_mfma_f32_16x16x32_bf16 v[148:151], v[112:115], v[190:193], v[148:151]
	v_mfma_f32_16x16x32_bf16 v[144:147], v[120:123], v[190:193], v[144:147]
	v_mfma_f32_16x16x32_bf16 v[108:111], v[112:115], v[214:217], v[108:111]
	v_mfma_f32_16x16x32_bf16 v[104:107], v[120:123], v[214:217], v[104:107]
	v_mfma_f32_16x16x32_bf16 v[92:95], v[112:115], v[224:227], v[92:95]
	v_mfma_f32_16x16x32_bf16 v[88:91], v[120:123], v[224:227], v[88:91]
	v_mfma_f32_16x16x32_bf16 v[76:79], v[112:115], v[232:235], v[76:79]
	v_mfma_f32_16x16x32_bf16 v[72:75], v[120:123], v[232:235], v[72:75]
	v_mfma_f32_16x16x32_bf16 v[148:151], v[116:119], v[194:197], v[148:151]
	v_mfma_f32_16x16x32_bf16 v[144:147], v[124:127], v[194:197], v[144:147]
	v_mfma_f32_16x16x32_bf16 v[108:111], v[116:119], v[218:221], v[108:111]
	v_mfma_f32_16x16x32_bf16 v[104:107], v[124:127], v[218:221], v[104:107]
	v_mfma_f32_16x16x32_bf16 v[92:95], v[116:119], v[228:231], v[92:95]
	v_mfma_f32_16x16x32_bf16 v[88:91], v[124:127], v[228:231], v[88:91]
	v_mfma_f32_16x16x32_bf16 v[76:79], v[116:119], v[236:239], v[76:79]
	v_mfma_f32_16x16x32_bf16 v[72:75], v[124:127], v[236:239], v[72:75]
	s_setprio 0
	s_setprio 1
	v_mfma_f32_16x16x32_bf16 v[136:139], v[132:135], v[190:193], v[136:139]
	v_mfma_f32_16x16x32_bf16 v[128:131], v[182:185], v[190:193], v[128:131]
	v_mfma_f32_16x16x32_bf16 v[100:103], v[132:135], v[214:217], v[100:103]
	v_mfma_f32_16x16x32_bf16 v[96:99], v[182:185], v[214:217], v[96:99]
	v_mfma_f32_16x16x32_bf16 v[84:87], v[132:135], v[224:227], v[84:87]
	v_mfma_f32_16x16x32_bf16 v[80:83], v[182:185], v[224:227], v[80:83]
	v_mfma_f32_16x16x32_bf16 v[68:71], v[132:135], v[232:235], v[68:71]
	v_mfma_f32_16x16x32_bf16 v[64:67], v[182:185], v[232:235], v[64:67]
	v_mfma_f32_16x16x32_bf16 v[136:139], v[140:143], v[194:197], v[136:139]
	v_mfma_f32_16x16x32_bf16 v[128:131], v[186:189], v[194:197], v[128:131]
	v_mfma_f32_16x16x32_bf16 v[100:103], v[140:143], v[218:221], v[100:103]
	v_mfma_f32_16x16x32_bf16 v[96:99], v[186:189], v[218:221], v[96:99]
	v_mfma_f32_16x16x32_bf16 v[84:87], v[140:143], v[228:231], v[84:87]
	v_mfma_f32_16x16x32_bf16 v[80:83], v[186:189], v[228:231], v[80:83]
	v_mfma_f32_16x16x32_bf16 v[68:71], v[140:143], v[236:239], v[68:71]
	s_barrier
	v_mfma_f32_16x16x32_bf16 v[64:67], v[186:189], v[236:239], v[64:67]
	s_setprio 0
	s_add_i32 s66, s86, s59
	v_lshl_add_u64 v[198:199], v[198:199], 0, s[22:23]
	s_mov_b32 m0, s66
	ds_read_b128 v[190:193], v212 offset:49152
	ds_read_b128 v[194:197], v212 offset:50176
	ds_read_b128 v[214:217], v212 offset:51200
	ds_read_b128 v[218:221], v212 offset:52224
	ds_read_b128 v[224:227], v212 offset:53248
	ds_read_b128 v[228:231], v212 offset:54272
	ds_read_b128 v[232:235], v212 offset:55296
	ds_read_b128 v[236:239], v212 offset:56320
	global_load_lds_dwordx4 v[198:199], off
	s_add_i32 m0, s66, 0x2000
	s_add_u32 s62, s62, 0x40080
	v_lshl_add_u64 v[198:199], v[240:241], 0, s[22:23]
	s_addc_u32 s63, s63, 0
	s_add_i32 s66, s87, s59
	global_load_lds_dwordx4 v[198:199], off
	v_lshl_add_u64 v[198:199], s[62:63], 0, v[152:153]
	s_mov_b32 m0, s66
	s_nop 0
	global_load_lds_dwordx4 v[198:199], off
	v_lshl_add_u64 v[198:199], s[62:63], 0, v[172:173]
	s_add_i32 m0, s66, 0x2000
	s_nop 0
	global_load_lds_dwordx4 v[198:199], off
	v_lshl_add_u64 v[198:199], v[242:243], 0, s[22:23]
	s_mov_b32 m0, s77
	s_nop 0
	global_load_lds_dwordx4 v[198:199], off
	v_lshl_add_u64 v[198:199], v[244:245], 0, s[22:23]
	s_mov_b32 m0, s78
	s_nop 0
	global_load_lds_dwordx4 v[198:199], off
	s_waitcnt vmcnt(8)
	s_waitcnt lgkmcnt(0)
	s_barrier
	s_setprio 1
	s_waitcnt lgkmcnt(0)
	v_mfma_f32_16x16x32_bf16 v[60:63], v[112:115], v[190:193], v[60:63]
	v_mfma_f32_16x16x32_bf16 v[56:59], v[120:123], v[190:193], v[56:59]
	v_mfma_f32_16x16x32_bf16 v[44:47], v[112:115], v[214:217], v[44:47]
	v_mfma_f32_16x16x32_bf16 v[40:43], v[120:123], v[214:217], v[40:43]
	v_mfma_f32_16x16x32_bf16 v[28:31], v[112:115], v[224:227], v[28:31]
	v_mfma_f32_16x16x32_bf16 v[24:27], v[120:123], v[224:227], v[24:27]
	v_mfma_f32_16x16x32_bf16 v[12:15], v[112:115], v[232:235], v[12:15]
	v_mfma_f32_16x16x32_bf16 v[8:11], v[120:123], v[232:235], v[8:11]
	v_mfma_f32_16x16x32_bf16 v[60:63], v[116:119], v[194:197], v[60:63]
	v_mfma_f32_16x16x32_bf16 v[56:59], v[124:127], v[194:197], v[56:59]
	v_mfma_f32_16x16x32_bf16 v[44:47], v[116:119], v[218:221], v[44:47]
	v_mfma_f32_16x16x32_bf16 v[40:43], v[124:127], v[218:221], v[40:43]
	v_mfma_f32_16x16x32_bf16 v[28:31], v[116:119], v[228:231], v[28:31]
	v_mfma_f32_16x16x32_bf16 v[24:27], v[124:127], v[228:231], v[24:27]
	v_mfma_f32_16x16x32_bf16 v[12:15], v[116:119], v[236:239], v[12:15]
	v_mfma_f32_16x16x32_bf16 v[8:11], v[124:127], v[236:239], v[8:11]
	s_setprio 0
	s_setprio 1
	v_mfma_f32_16x16x32_bf16 v[52:55], v[132:135], v[190:193], v[52:55]
	v_mfma_f32_16x16x32_bf16 v[48:51], v[182:185], v[190:193], v[48:51]
	v_mfma_f32_16x16x32_bf16 v[36:39], v[132:135], v[214:217], v[36:39]
	v_mfma_f32_16x16x32_bf16 v[32:35], v[182:185], v[214:217], v[32:35]
	v_mfma_f32_16x16x32_bf16 v[20:23], v[132:135], v[224:227], v[20:23]
	v_mfma_f32_16x16x32_bf16 v[16:19], v[182:185], v[224:227], v[16:19]
	v_mfma_f32_16x16x32_bf16 v[4:7], v[132:135], v[232:235], v[4:7]
	v_mfma_f32_16x16x32_bf16 v[0:3], v[182:185], v[232:235], v[0:3]
	v_mfma_f32_16x16x32_bf16 v[52:55], v[140:143], v[194:197], v[52:55]
	v_mfma_f32_16x16x32_bf16 v[48:51], v[186:189], v[194:197], v[48:51]
	v_mfma_f32_16x16x32_bf16 v[36:39], v[140:143], v[218:221], v[36:39]
	v_mfma_f32_16x16x32_bf16 v[32:35], v[186:189], v[218:221], v[32:35]
	v_mfma_f32_16x16x32_bf16 v[20:23], v[140:143], v[228:231], v[20:23]
	v_mfma_f32_16x16x32_bf16 v[16:19], v[186:189], v[228:231], v[16:19]
	v_mfma_f32_16x16x32_bf16 v[4:7], v[140:143], v[236:239], v[4:7]
	s_barrier
	v_mfma_f32_16x16x32_bf16 v[0:3], v[186:189], v[236:239], v[0:3]
	s_setprio 0
	s_add_i32 s85, s85, 2
	s_add_u32 s83, s83, 0x100
	s_addc_u32 s84, s84, 0
	s_add_u32 s60, s60, 0x100
	s_addc_u32 s61, s61, 0
	s_cmp_gt_u32 s85, 13
.LBB0_822:
	s_add_u32 s62, s60, 0xfffc0080
	s_addc_u32 s63, s61, -1
	s_add_i32 s86, 0, 0x10000
	s_cmp_eq_u32 s85, 12
	s_cselect_b32 s67, s21, s63
	s_cselect_b32 s66, s81, s62
	s_cselect_b32 s63, s19, s84
	s_cselect_b32 s62, s82, s83
	s_add_i32 s89, 0, 0x14000
	v_add_u32_e32 v124, s86, v210
	v_add_u32_e32 v186, s89, v210
	ds_read_b128 v[112:115], v124
	ds_read_b128 v[116:119], v124 offset:1024
	ds_read_b128 v[120:123], v124 offset:2048
	ds_read_b128 v[124:127], v124 offset:3072
	ds_read_b128 v[132:135], v186
	ds_read_b128 v[140:143], v186 offset:1024
	ds_read_b128 v[182:185], v186 offset:2048
	ds_read_b128 v[186:189], v186 offset:3072
	v_lshl_add_u64 v[198:199], s[60:61], 0, v[180:181]
	s_add_i32 m0, s68, 0xc000
	ds_read_b128 v[190:193], v212
	ds_read_b128 v[194:197], v212 offset:1024
	ds_read_b128 v[214:217], v212 offset:2048
	ds_read_b128 v[218:221], v212 offset:3072
	ds_read_b128 v[224:227], v212 offset:4096
	ds_read_b128 v[228:231], v212 offset:5120
	ds_read_b128 v[232:235], v212 offset:6144
	ds_read_b128 v[236:239], v212 offset:7168
	global_load_lds_dwordx4 v[198:199], off
	v_lshl_add_u64 v[198:199], s[60:61], 0, v[178:179]
	s_add_i32 m0, s68, 0xe000
	s_nop 0
	global_load_lds_dwordx4 v[198:199], off
	s_waitcnt vmcnt(8)
	s_waitcnt lgkmcnt(0)
	s_barrier
	s_setprio 1
	s_waitcnt lgkmcnt(0)
	v_mfma_f32_16x16x32_bf16 v[148:151], v[112:115], v[190:193], v[148:151]
	v_mfma_f32_16x16x32_bf16 v[144:147], v[120:123], v[190:193], v[144:147]
	v_mfma_f32_16x16x32_bf16 v[108:111], v[112:115], v[214:217], v[108:111]
	v_mfma_f32_16x16x32_bf16 v[104:107], v[120:123], v[214:217], v[104:107]
	v_mfma_f32_16x16x32_bf16 v[92:95], v[112:115], v[224:227], v[92:95]
	v_mfma_f32_16x16x32_bf16 v[88:91], v[120:123], v[224:227], v[88:91]
	v_mfma_f32_16x16x32_bf16 v[76:79], v[112:115], v[232:235], v[76:79]
	v_mfma_f32_16x16x32_bf16 v[72:75], v[120:123], v[232:235], v[72:75]
	v_mfma_f32_16x16x32_bf16 v[148:151], v[116:119], v[194:197], v[148:151]
	v_mfma_f32_16x16x32_bf16 v[144:147], v[124:127], v[194:197], v[144:147]
	v_mfma_f32_16x16x32_bf16 v[108:111], v[116:119], v[218:221], v[108:111]
	v_mfma_f32_16x16x32_bf16 v[104:107], v[124:127], v[218:221], v[104:107]
	v_mfma_f32_16x16x32_bf16 v[92:95], v[116:119], v[228:231], v[92:95]
	v_mfma_f32_16x16x32_bf16 v[88:91], v[124:127], v[228:231], v[88:91]
	v_mfma_f32_16x16x32_bf16 v[76:79], v[116:119], v[236:239], v[76:79]
	v_mfma_f32_16x16x32_bf16 v[72:75], v[124:127], v[236:239], v[72:75]
	s_setprio 0
	s_setprio 1
	v_mfma_f32_16x16x32_bf16 v[136:139], v[132:135], v[190:193], v[136:139]
	v_mfma_f32_16x16x32_bf16 v[128:131], v[182:185], v[190:193], v[128:131]
	v_mfma_f32_16x16x32_bf16 v[100:103], v[132:135], v[214:217], v[100:103]
	v_mfma_f32_16x16x32_bf16 v[96:99], v[182:185], v[214:217], v[96:99]
	v_mfma_f32_16x16x32_bf16 v[84:87], v[132:135], v[224:227], v[84:87]
	v_mfma_f32_16x16x32_bf16 v[80:83], v[182:185], v[224:227], v[80:83]
	v_mfma_f32_16x16x32_bf16 v[68:71], v[132:135], v[232:235], v[68:71]
	v_mfma_f32_16x16x32_bf16 v[64:67], v[182:185], v[232:235], v[64:67]
	v_mfma_f32_16x16x32_bf16 v[136:139], v[140:143], v[194:197], v[136:139]
	v_mfma_f32_16x16x32_bf16 v[128:131], v[186:189], v[194:197], v[128:131]
	v_mfma_f32_16x16x32_bf16 v[100:103], v[140:143], v[218:221], v[100:103]
	v_mfma_f32_16x16x32_bf16 v[96:99], v[186:189], v[218:221], v[96:99]
	v_mfma_f32_16x16x32_bf16 v[84:87], v[140:143], v[228:231], v[84:87]
	v_mfma_f32_16x16x32_bf16 v[80:83], v[186:189], v[228:231], v[80:83]
	v_mfma_f32_16x16x32_bf16 v[68:71], v[140:143], v[236:239], v[68:71]
	s_barrier
	v_mfma_f32_16x16x32_bf16 v[64:67], v[186:189], v[236:239], v[64:67]
	s_setprio 0
	s_add_i32 s86, s86, s59
	v_lshl_add_u64 v[198:199], s[62:63], 0, v[152:153]
	s_mov_b32 m0, s86
	ds_read_b128 v[190:193], v212 offset:16384
	ds_read_b128 v[194:197], v212 offset:17408
	ds_read_b128 v[214:217], v212 offset:18432
	ds_read_b128 v[218:221], v212 offset:19456
	ds_read_b128 v[224:227], v212 offset:20480
	ds_read_b128 v[228:231], v212 offset:21504
	ds_read_b128 v[232:235], v212 offset:22528
	ds_read_b128 v[236:239], v212 offset:23552
	global_load_lds_dwordx4 v[198:199], off
	s_add_i32 m0, s86, 0x2000
	s_add_u32 s86, s62, 0x40000
	v_lshl_add_u64 v[240:241], s[62:63], 0, v[172:173]
	s_addc_u32 s87, s63, 0
	s_add_i32 s89, s89, s59
	global_load_lds_dwordx4 v[240:241], off
	v_lshl_add_u64 v[242:243], s[86:87], 0, v[152:153]
	s_mov_b32 m0, s89
	v_lshl_add_u64 v[244:245], s[66:67], 0, v[174:175]
	global_load_lds_dwordx4 v[242:243], off
	v_lshl_add_u64 v[242:243], s[86:87], 0, v[172:173]
	s_add_i32 m0, s89, 0x2000
	s_nop 0
	global_load_lds_dwordx4 v[242:243], off
	v_lshl_add_u64 v[242:243], s[66:67], 0, v[176:177]
	s_mov_b32 m0, s68
	s_nop 0
	global_load_lds_dwordx4 v[242:243], off
	s_mov_b32 m0, s69
	s_nop 0
	global_load_lds_dwordx4 v[244:245], off
	s_waitcnt vmcnt(8)
	s_waitcnt lgkmcnt(0)
	s_barrier
	s_setprio 1
	s_waitcnt lgkmcnt(0)
	v_mfma_f32_16x16x32_bf16 v[60:63], v[112:115], v[190:193], v[60:63]
	v_mfma_f32_16x16x32_bf16 v[56:59], v[120:123], v[190:193], v[56:59]
	v_mfma_f32_16x16x32_bf16 v[44:47], v[112:115], v[214:217], v[44:47]
	v_mfma_f32_16x16x32_bf16 v[40:43], v[120:123], v[214:217], v[40:43]
	v_mfma_f32_16x16x32_bf16 v[28:31], v[112:115], v[224:227], v[28:31]
	v_mfma_f32_16x16x32_bf16 v[24:27], v[120:123], v[224:227], v[24:27]
	v_mfma_f32_16x16x32_bf16 v[12:15], v[112:115], v[232:235], v[12:15]
	v_mfma_f32_16x16x32_bf16 v[8:11], v[120:123], v[232:235], v[8:11]
	v_mfma_f32_16x16x32_bf16 v[60:63], v[116:119], v[194:197], v[60:63]
	v_mfma_f32_16x16x32_bf16 v[56:59], v[124:127], v[194:197], v[56:59]
	v_mfma_f32_16x16x32_bf16 v[44:47], v[116:119], v[218:221], v[44:47]
	v_mfma_f32_16x16x32_bf16 v[40:43], v[124:127], v[218:221], v[40:43]
	v_mfma_f32_16x16x32_bf16 v[28:31], v[116:119], v[228:231], v[28:31]
	v_mfma_f32_16x16x32_bf16 v[24:27], v[124:127], v[228:231], v[24:27]
	v_mfma_f32_16x16x32_bf16 v[12:15], v[116:119], v[236:239], v[12:15]
	v_mfma_f32_16x16x32_bf16 v[8:11], v[124:127], v[236:239], v[8:11]
	s_setprio 0
	s_setprio 1
	v_mfma_f32_16x16x32_bf16 v[52:55], v[132:135], v[190:193], v[52:55]
	v_mfma_f32_16x16x32_bf16 v[48:51], v[182:185], v[190:193], v[48:51]
	v_mfma_f32_16x16x32_bf16 v[36:39], v[132:135], v[214:217], v[36:39]
	v_mfma_f32_16x16x32_bf16 v[32:35], v[182:185], v[214:217], v[32:35]
	v_mfma_f32_16x16x32_bf16 v[20:23], v[132:135], v[224:227], v[20:23]
	v_mfma_f32_16x16x32_bf16 v[16:19], v[182:185], v[224:227], v[16:19]
	v_mfma_f32_16x16x32_bf16 v[4:7], v[132:135], v[232:235], v[4:7]
	v_mfma_f32_16x16x32_bf16 v[0:3], v[182:185], v[232:235], v[0:3]
	v_mfma_f32_16x16x32_bf16 v[52:55], v[140:143], v[194:197], v[52:55]
	v_mfma_f32_16x16x32_bf16 v[48:51], v[186:189], v[194:197], v[48:51]
	v_mfma_f32_16x16x32_bf16 v[36:39], v[140:143], v[218:221], v[36:39]
	v_mfma_f32_16x16x32_bf16 v[32:35], v[186:189], v[218:221], v[32:35]
	v_mfma_f32_16x16x32_bf16 v[20:23], v[140:143], v[228:231], v[20:23]
	v_mfma_f32_16x16x32_bf16 v[16:19], v[186:189], v[228:231], v[16:19]
	v_mfma_f32_16x16x32_bf16 v[4:7], v[140:143], v[236:239], v[4:7]
	s_barrier
	v_mfma_f32_16x16x32_bf16 v[0:3], v[186:189], v[236:239], v[0:3]
	s_setprio 0
	s_add_i32 s86, 0, 0x18000
	s_add_i32 s87, 0, 0x1c000
	v_add_u32_e32 v124, s86, v210
	v_add_u32_e32 v186, s87, v210
	ds_read_b128 v[112:115], v124
	ds_read_b128 v[116:119], v124 offset:1024
	ds_read_b128 v[120:123], v124 offset:2048
	ds_read_b128 v[124:127], v124 offset:3072
	ds_read_b128 v[132:135], v186
	ds_read_b128 v[140:143], v186 offset:1024
	ds_read_b128 v[182:185], v186 offset:2048
	ds_read_b128 v[186:189], v186 offset:3072
	s_add_u32 s66, s66, 0x40000
	s_addc_u32 s67, s67, 0
	s_mov_b32 m0, s74
	v_lshl_add_u64 v[246:247], s[66:67], 0, v[176:177]
	ds_read_b128 v[190:193], v212 offset:32768
	ds_read_b128 v[194:197], v212 offset:33792
	ds_read_b128 v[214:217], v212 offset:34816
	ds_read_b128 v[218:221], v212 offset:35840
	ds_read_b128 v[224:227], v212 offset:36864
	ds_read_b128 v[228:231], v212 offset:37888
	ds_read_b128 v[232:235], v212 offset:38912
	ds_read_b128 v[236:239], v212 offset:39936
	global_load_lds_dwordx4 v[246:247], off
	v_lshl_add_u64 v[246:247], s[66:67], 0, v[174:175]
	s_mov_b32 m0, s75
	s_nop 0
	global_load_lds_dwordx4 v[246:247], off
	s_waitcnt vmcnt(8)
	s_waitcnt lgkmcnt(0)
	s_barrier
	s_setprio 1
	s_waitcnt lgkmcnt(0)
	v_mfma_f32_16x16x32_bf16 v[148:151], v[112:115], v[190:193], v[148:151]
	v_mfma_f32_16x16x32_bf16 v[144:147], v[120:123], v[190:193], v[144:147]
	v_mfma_f32_16x16x32_bf16 v[108:111], v[112:115], v[214:217], v[108:111]
	v_mfma_f32_16x16x32_bf16 v[104:107], v[120:123], v[214:217], v[104:107]
	v_mfma_f32_16x16x32_bf16 v[92:95], v[112:115], v[224:227], v[92:95]
	v_mfma_f32_16x16x32_bf16 v[88:91], v[120:123], v[224:227], v[88:91]
	v_mfma_f32_16x16x32_bf16 v[76:79], v[112:115], v[232:235], v[76:79]
	v_mfma_f32_16x16x32_bf16 v[72:75], v[120:123], v[232:235], v[72:75]
	v_mfma_f32_16x16x32_bf16 v[148:151], v[116:119], v[194:197], v[148:151]
	v_mfma_f32_16x16x32_bf16 v[144:147], v[124:127], v[194:197], v[144:147]
	v_mfma_f32_16x16x32_bf16 v[108:111], v[116:119], v[218:221], v[108:111]
	v_mfma_f32_16x16x32_bf16 v[104:107], v[124:127], v[218:221], v[104:107]
	v_mfma_f32_16x16x32_bf16 v[92:95], v[116:119], v[228:231], v[92:95]
	v_mfma_f32_16x16x32_bf16 v[88:91], v[124:127], v[228:231], v[88:91]
	v_mfma_f32_16x16x32_bf16 v[76:79], v[116:119], v[236:239], v[76:79]
	v_mfma_f32_16x16x32_bf16 v[72:75], v[124:127], v[236:239], v[72:75]
	s_setprio 0
	s_setprio 1
	v_mfma_f32_16x16x32_bf16 v[136:139], v[132:135], v[190:193], v[136:139]
	v_mfma_f32_16x16x32_bf16 v[128:131], v[182:185], v[190:193], v[128:131]
	v_mfma_f32_16x16x32_bf16 v[100:103], v[132:135], v[214:217], v[100:103]
	v_mfma_f32_16x16x32_bf16 v[96:99], v[182:185], v[214:217], v[96:99]
	v_mfma_f32_16x16x32_bf16 v[84:87], v[132:135], v[224:227], v[84:87]
	v_mfma_f32_16x16x32_bf16 v[80:83], v[182:185], v[224:227], v[80:83]
	v_mfma_f32_16x16x32_bf16 v[68:71], v[132:135], v[232:235], v[68:71]
	v_mfma_f32_16x16x32_bf16 v[64:67], v[182:185], v[232:235], v[64:67]
	v_mfma_f32_16x16x32_bf16 v[136:139], v[140:143], v[194:197], v[136:139]
	v_mfma_f32_16x16x32_bf16 v[128:131], v[186:189], v[194:197], v[128:131]
	v_mfma_f32_16x16x32_bf16 v[100:103], v[140:143], v[218:221], v[100:103]
	v_mfma_f32_16x16x32_bf16 v[96:99], v[186:189], v[218:221], v[96:99]
	v_mfma_f32_16x16x32_bf16 v[84:87], v[140:143], v[228:231], v[84:87]
	v_mfma_f32_16x16x32_bf16 v[80:83], v[186:189], v[228:231], v[80:83]
	v_mfma_f32_16x16x32_bf16 v[68:71], v[140:143], v[236:239], v[68:71]
	s_barrier
	v_mfma_f32_16x16x32_bf16 v[64:67], v[186:189], v[236:239], v[64:67]
	s_setprio 0
	s_add_i32 s66, s86, s59
	v_lshl_add_u64 v[198:199], v[198:199], 0, s[22:23]
	s_mov_b32 m0, s66
	ds_read_b128 v[190:193], v212 offset:49152
	ds_read_b128 v[194:197], v212 offset:50176
	ds_read_b128 v[214:217], v212 offset:51200
	ds_read_b128 v[218:221], v212 offset:52224
	ds_read_b128 v[224:227], v212 offset:53248
	ds_read_b128 v[228:231], v212 offset:54272
	ds_read_b128 v[232:235], v212 offset:55296
	ds_read_b128 v[236:239], v212 offset:56320
	global_load_lds_dwordx4 v[198:199], off
	s_add_i32 m0, s66, 0x2000
	s_add_u32 s62, s62, 0x40080
	v_lshl_add_u64 v[198:199], v[240:241], 0, s[22:23]
	s_addc_u32 s63, s63, 0
	s_add_i32 s66, s87, s59
	global_load_lds_dwordx4 v[198:199], off
	v_lshl_add_u64 v[198:199], s[62:63], 0, v[152:153]
	s_mov_b32 m0, s66
	s_nop 0
	global_load_lds_dwordx4 v[198:199], off
	v_lshl_add_u64 v[198:199], s[62:63], 0, v[172:173]
	s_add_i32 m0, s66, 0x2000
	s_nop 0
	global_load_lds_dwordx4 v[198:199], off
	v_lshl_add_u64 v[198:199], v[242:243], 0, s[22:23]
	s_mov_b32 m0, s77
	s_nop 0
	global_load_lds_dwordx4 v[198:199], off
	v_lshl_add_u64 v[198:199], v[244:245], 0, s[22:23]
	s_mov_b32 m0, s78
	s_nop 0
	global_load_lds_dwordx4 v[198:199], off
	s_waitcnt vmcnt(8)
	s_waitcnt lgkmcnt(0)
	s_barrier
	s_setprio 1
	s_waitcnt lgkmcnt(0)
	v_mfma_f32_16x16x32_bf16 v[60:63], v[112:115], v[190:193], v[60:63]
	v_mfma_f32_16x16x32_bf16 v[56:59], v[120:123], v[190:193], v[56:59]
	v_mfma_f32_16x16x32_bf16 v[44:47], v[112:115], v[214:217], v[44:47]
	v_mfma_f32_16x16x32_bf16 v[40:43], v[120:123], v[214:217], v[40:43]
	v_mfma_f32_16x16x32_bf16 v[28:31], v[112:115], v[224:227], v[28:31]
	v_mfma_f32_16x16x32_bf16 v[24:27], v[120:123], v[224:227], v[24:27]
	v_mfma_f32_16x16x32_bf16 v[12:15], v[112:115], v[232:235], v[12:15]
	v_mfma_f32_16x16x32_bf16 v[8:11], v[120:123], v[232:235], v[8:11]
	v_mfma_f32_16x16x32_bf16 v[60:63], v[116:119], v[194:197], v[60:63]
	v_mfma_f32_16x16x32_bf16 v[56:59], v[124:127], v[194:197], v[56:59]
	v_mfma_f32_16x16x32_bf16 v[44:47], v[116:119], v[218:221], v[44:47]
	v_mfma_f32_16x16x32_bf16 v[40:43], v[124:127], v[218:221], v[40:43]
	v_mfma_f32_16x16x32_bf16 v[28:31], v[116:119], v[228:231], v[28:31]
	v_mfma_f32_16x16x32_bf16 v[24:27], v[124:127], v[228:231], v[24:27]
	v_mfma_f32_16x16x32_bf16 v[12:15], v[116:119], v[236:239], v[12:15]
	v_mfma_f32_16x16x32_bf16 v[8:11], v[124:127], v[236:239], v[8:11]
	s_setprio 0
	s_setprio 1
	v_mfma_f32_16x16x32_bf16 v[52:55], v[132:135], v[190:193], v[52:55]
	v_mfma_f32_16x16x32_bf16 v[48:51], v[182:185], v[190:193], v[48:51]
	v_mfma_f32_16x16x32_bf16 v[36:39], v[132:135], v[214:217], v[36:39]
	v_mfma_f32_16x16x32_bf16 v[32:35], v[182:185], v[214:217], v[32:35]
	v_mfma_f32_16x16x32_bf16 v[20:23], v[132:135], v[224:227], v[20:23]
	v_mfma_f32_16x16x32_bf16 v[16:19], v[182:185], v[224:227], v[16:19]
	v_mfma_f32_16x16x32_bf16 v[4:7], v[132:135], v[232:235], v[4:7]
	v_mfma_f32_16x16x32_bf16 v[0:3], v[182:185], v[232:235], v[0:3]
	v_mfma_f32_16x16x32_bf16 v[52:55], v[140:143], v[194:197], v[52:55]
	v_mfma_f32_16x16x32_bf16 v[48:51], v[186:189], v[194:197], v[48:51]
	v_mfma_f32_16x16x32_bf16 v[36:39], v[140:143], v[218:221], v[36:39]
	v_mfma_f32_16x16x32_bf16 v[32:35], v[186:189], v[218:221], v[32:35]
	v_mfma_f32_16x16x32_bf16 v[20:23], v[140:143], v[228:231], v[20:23]
	v_mfma_f32_16x16x32_bf16 v[16:19], v[186:189], v[228:231], v[16:19]
	v_mfma_f32_16x16x32_bf16 v[4:7], v[140:143], v[236:239], v[4:7]
	s_barrier
	v_mfma_f32_16x16x32_bf16 v[0:3], v[186:189], v[236:239], v[0:3]
	s_setprio 0
	s_add_i32 s85, s85, 2
	s_add_u32 s83, s83, 0x100
	s_addc_u32 s84, s84, 0
	s_add_u32 s60, s60, 0x100
	s_addc_u32 s61, s61, 0
	s_cmp_gt_u32 s85, 13
	s_cbranch_scc0 .LBB0_822
	s_and_b64 vcc, exec, s[16:17]
	s_cbranch_vccz .LBB0_825
	s_barrier
